# row1 (adaLN norm1 / MoE combine) rewritten as a streaming 4-row software pipeline, modulation vectors kept in registers
# speedup vs baseline: 1.1295x; 1.0177x over previous
; #define TIDX tid_opaque()
; DI void row1_phase(const Params& P, int combine_l, int norm_l, int r_begin) {
;   const int lane = TIDX & 63, gw = blockIdx.x * 4 + (TIDX >> 6), nw = gridDim.x * 4;
;   auto load_row = [&](int r, float4 (&xv)[4], h4 (&ya)[4], h4 (&yb)[4]) {
;     if (combine_l < 0) {
;       const float* src = r < TC ? P.ctx + (size_t)r * D : P.x + (size_t)(r - TC) * D;
; #pragma unroll
;       for (int i = 0; i < 4; i++) xv[i] = *(const float4*)(src + i * 256 + lane * 4);
;     } else {
;       const float* xm = r < TC ? P.xcbuf + (size_t)r * D : P.out + (size_t)(r - TC) * D;
;       const half_t* y0 = P.yA + (size_t)(2 * r) * D; const half_t* y1 = y0 + D;
; #pragma unroll
;       for (int i = 0; i < 4; i++) { int c = i * 256 + lane * 4; xv[i] = *(const float4*)(xm + c); ya[i] = *(const h4*)(y0 + c); yb[i] = *(const h4*)(y1 + c); }
;     }
;   };
;     ...
;   const int nrows = TA - r_begin;
;   const int r_lo = r_begin + (int)(((long long)gw * nrows) / nw), r_hi = r_begin + (int)(((long long)(gw + 1) * nrows) / nw);
; #pragma unroll 1
;   for (int r = r_lo; r < r_hi; r += 4) {
;     float4 x0[4], x1[4], x2[4], x3[4]; h4 a0[4], b0[4], a1[4], b1[4], a2[4], b2[4], a3[4], b3[4];
;     const int r1 = r + 1, r2 = r + 2, r3 = r + 3;
;     load_row(r, x0, a0, b0);
;     if (r1 < r_hi) load_row(r1, x1, a1, b1);
;     if (r2 < r_hi) load_row(r2, x2, a2, b2);
;     if (r3 < r_hi) load_row(r3, x3, a3, b3);
.LBB0_151:
	s_cmp_eq_u32 s2, 0
	s_cbranch_scc1 .Lr1_modeA
	v_lshrrev_b32_e32 v152, 6, v172
	v_and_b32_e32 v153, 63, v172
	v_readfirstlane_b32 s5, v152
	v_readlane_b32 s4, v253, 0
	v_lshlrev_b32_e32 v150, 4, v153
	v_lshlrev_b32_e32 v151, 3, v153
	v_lshlrev_b32_e32 v159, 2, v153
	s_nop 2
	s_lshl_b32 s4, s4, 2
	s_add_u32 s4, s4, s5
	s_mul_i32 s5, s4, 66
	s_add_u32 s6, s5, 66
	s_add_u32 s52, s90, 0x28cbc700
	s_addc_u32 s53, s91, 0
	s_add_u32 s54, s90, 0xf8bc700
	s_addc_u32 s55, s91, 0
	s_add_u32 s56, s90, 0xce00000
	s_addc_u32 s57, s91, 0
	s_add_u32 s48, s90, 0xf05c700
	s_addc_u32 s49, s91, 0
	v_readlane_b32 s50, v253, 49
	v_readlane_b32 s51, v253, 50
	v_readlane_b32 s58, v255, 15
	v_readlane_b32 s59, v255, 16
	s_nop 3
	s_sub_u32 s50, s50, 0x800000
	s_subb_u32 s51, s51, 0
	s_add_u32 s58, s58, 0x1000
	s_addc_u32 s59, s59, 0
	s_mov_b32 s8, -1
	s_mov_b32 s7, s5
	s_cmp_lt_u32 s7, 0x800
	s_cselect_b64 s[60:61], s[48:49], s[50:51]
	s_lshl_b32 s10, s7, 12
	s_add_u32 s60, s60, s10
	s_addc_u32 s61, s61, 0
	global_load_dwordx4 a[0:3], v150, s[60:61] offset:0
	global_load_dwordx4 a[4:7], v150, s[60:61] offset:1024
	global_load_dwordx4 a[8:11], v150, s[60:61] offset:2048
	global_load_dwordx4 a[12:15], v150, s[60:61] offset:3072
	s_add_u32 s62, s52, s10
	s_addc_u32 s63, s53, 0
	global_load_dwordx2 a[16:17], v151, s[62:63] offset:0
	global_load_dwordx2 a[18:19], v151, s[62:63] offset:512
	global_load_dwordx2 a[20:21], v151, s[62:63] offset:1024
	global_load_dwordx2 a[22:23], v151, s[62:63] offset:1536
	global_load_dwordx2 a[24:25], v151, s[62:63] offset:2048
	global_load_dwordx2 a[26:27], v151, s[62:63] offset:2560
	global_load_dwordx2 a[28:29], v151, s[62:63] offset:3072
	global_load_dwordx2 a[30:31], v151, s[62:63] offset:3584
	s_add_u32 s7, s7, 1
	s_cmp_lt_u32 s7, 0x800
	s_cselect_b64 s[60:61], s[48:49], s[50:51]
	s_lshl_b32 s10, s7, 12
	s_add_u32 s60, s60, s10
	s_addc_u32 s61, s61, 0
	global_load_dwordx4 a[32:35], v150, s[60:61] offset:0
	global_load_dwordx4 a[36:39], v150, s[60:61] offset:1024
	global_load_dwordx4 a[40:43], v150, s[60:61] offset:2048
	global_load_dwordx4 a[44:47], v150, s[60:61] offset:3072
	s_add_u32 s62, s52, s10
	s_addc_u32 s63, s53, 0
	global_load_dwordx2 a[48:49], v151, s[62:63] offset:0
	global_load_dwordx2 a[50:51], v151, s[62:63] offset:512
	global_load_dwordx2 a[52:53], v151, s[62:63] offset:1024
	global_load_dwordx2 a[54:55], v151, s[62:63] offset:1536
	global_load_dwordx2 a[56:57], v151, s[62:63] offset:2048
	global_load_dwordx2 a[58:59], v151, s[62:63] offset:2560
	global_load_dwordx2 a[60:61], v151, s[62:63] offset:3072
	global_load_dwordx2 a[62:63], v151, s[62:63] offset:3584
	s_add_u32 s7, s7, 1
	s_cmp_lt_u32 s7, 0x800
	s_cselect_b64 s[60:61], s[48:49], s[50:51]
	s_lshl_b32 s10, s7, 12
	s_add_u32 s60, s60, s10
	s_addc_u32 s61, s61, 0
	global_load_dwordx4 a[64:67], v150, s[60:61] offset:0
	global_load_dwordx4 a[68:71], v150, s[60:61] offset:1024
	global_load_dwordx4 a[72:75], v150, s[60:61] offset:2048
	global_load_dwordx4 a[76:79], v150, s[60:61] offset:3072
	s_add_u32 s62, s52, s10
	s_addc_u32 s63, s53, 0
	global_load_dwordx2 a[80:81], v151, s[62:63] offset:0
	global_load_dwordx2 a[82:83], v151, s[62:63] offset:512
	global_load_dwordx2 a[84:85], v151, s[62:63] offset:1024
	global_load_dwordx2 a[86:87], v151, s[62:63] offset:1536
	global_load_dwordx2 a[88:89], v151, s[62:63] offset:2048
	global_load_dwordx2 a[90:91], v151, s[62:63] offset:2560
	global_load_dwordx2 a[92:93], v151, s[62:63] offset:3072
	global_load_dwordx2 a[94:95], v151, s[62:63] offset:3584
	s_add_u32 s7, s7, 1
	s_cmp_lt_u32 s7, 0x800
	s_cselect_b64 s[60:61], s[48:49], s[50:51]
	s_lshl_b32 s10, s7, 12
	s_add_u32 s60, s60, s10
	s_addc_u32 s61, s61, 0
	global_load_dwordx4 a[96:99], v150, s[60:61] offset:0
	global_load_dwordx4 a[100:103], v150, s[60:61] offset:1024
	global_load_dwordx4 a[104:107], v150, s[60:61] offset:2048
	global_load_dwordx4 a[108:111], v150, s[60:61] offset:3072
	s_add_u32 s62, s52, s10
	s_addc_u32 s63, s53, 0
	global_load_dwordx2 a[112:113], v151, s[62:63] offset:0
	global_load_dwordx2 a[114:115], v151, s[62:63] offset:512
	global_load_dwordx2 a[116:117], v151, s[62:63] offset:1024
	global_load_dwordx2 a[118:119], v151, s[62:63] offset:1536
	global_load_dwordx2 a[120:121], v151, s[62:63] offset:2048
	global_load_dwordx2 a[122:123], v151, s[62:63] offset:2560
	global_load_dwordx2 a[124:125], v151, s[62:63] offset:3072
	global_load_dwordx2 a[126:127], v151, s[62:63] offset:3584
	s_add_u32 s7, s7, 1
	s_mov_b32 s98, 15
; DI void row1_phase(const Params& P, int combine_l, int norm_l, int r_begin) {
;     ...
;     const int n = row_mod(r);
;     if (combine_l >= 0) {
;       float* xm = r < TC ? P.xcbuf + (size_t)r * D : P.out + (size_t)(r - TC) * D;
;       const float* g2 = P.mod + (size_t)(combine_l * 9 + n) * 6144 + 5 * 1024;
; #pragma unroll
;       for (int i = 0; i < 4; i++) {
;         int c = i * 256 + lane * 4;
;         float4 g = *(const float4*)(g2 + c); float4 t = xv[i];
;         t.x += g.x * ((float)ya[i][0] + (float)yb[i][0]); t.y += g.y * ((float)ya[i][1] + (float)yb[i][1]);
;         t.z += g.z * ((float)ya[i][2] + (float)yb[i][2]); t.w += g.w * ((float)ya[i][3] + (float)yb[i][3]);
;         *(float4*)(xm + c) = t; xv[i] = t;
;       }
;     }
;     if (norm_l >= 0) {
;       float ss = 0.f;
; #pragma unroll
;       for (int i = 0; i < 4; i++) ss += xv[i].x * xv[i].x + xv[i].y * xv[i].y + xv[i].z * xv[i].z + xv[i].w * xv[i].w;
;       ss = wave_sum(ss);
;       const float rstd = rsqrtf(ss * (1.f / 1024.f) + EPS);
;       const float* g = P.norm1_g + norm_l * 1024;
;       const float* sh = P.mod + (size_t)(norm_l * 9 + n) * 6144; const float* sc = sh + 1024;
; #pragma unroll
;       for (int i = 0; i < 4; i++) {
;         int c = i * 256 + lane * 4;
;         float4 gg = *(const float4*)(g + c), s1 = *(const float4*)(sc + c), s0 = *(const float4*)(sh + c);
.Lr1b_loop:
	s_sub_u32 s9, s5, 0x800
	s_lshr_b32 s9, s9, 13
	s_cmp_lt_u32 s5, 0x800
	s_cselect_b32 s9, 8, s9
	s_cmp_eq_u32 s9, s8
	s_cbranch_scc1 .Lr1b_nr1
	s_mov_b32 s8, s9
	s_waitcnt vmcnt(0)
	s_add_u32 s10, s9, 9
	s_mul_i32 s10, s10, 0x6000
	s_add_u32 s38, s56, s10
	s_addc_u32 s39, s57, 0
	global_load_dwordx4 v[54:57], v150, s[58:59] offset:0
	global_load_dwordx4 v[58:61], v150, s[58:59] offset:1024
	global_load_dwordx4 v[62:65], v150, s[58:59] offset:2048
	global_load_dwordx4 v[66:69], v150, s[58:59] offset:3072
	s_add_u32 s44, s38, 0x1000
	s_addc_u32 s45, s39, 0
	global_load_dwordx4 v[70:73], v150, s[44:45] offset:0
	global_load_dwordx4 v[74:77], v150, s[44:45] offset:1024
	global_load_dwordx4 v[78:81], v150, s[44:45] offset:2048
	global_load_dwordx4 v[82:85], v150, s[44:45] offset:3072
	global_load_dwordx4 v[16:19], v150, s[38:39] offset:0
	global_load_dwordx4 v[20:23], v150, s[38:39] offset:1024
	global_load_dwordx4 v[24:27], v150, s[38:39] offset:2048
	global_load_dwordx4 v[28:31], v150, s[38:39] offset:3072
	s_add_u32 s10, s9, 0
	s_mul_i32 s10, s10, 0x6000
	s_add_u32 s10, s10, 0x5000
	s_add_u32 s38, s56, s10
	s_addc_u32 s39, s57, 0
	global_load_dwordx4 v[32:35], v150, s[38:39] offset:0
	global_load_dwordx4 v[36:39], v150, s[38:39] offset:1024
	global_load_dwordx4 v[40:43], v150, s[38:39] offset:2048
	global_load_dwordx4 v[44:47], v150, s[38:39] offset:3072
	s_waitcnt vmcnt(0)
	v_add_f32_e32 v70, 1.0, v70
	v_add_f32_e32 v71, 1.0, v71
	v_add_f32_e32 v72, 1.0, v72
	v_add_f32_e32 v73, 1.0, v73
	v_add_f32_e32 v74, 1.0, v74
	v_add_f32_e32 v75, 1.0, v75
	v_add_f32_e32 v76, 1.0, v76
	v_add_f32_e32 v77, 1.0, v77
	v_add_f32_e32 v78, 1.0, v78
	v_add_f32_e32 v79, 1.0, v79
	v_add_f32_e32 v80, 1.0, v80
	v_add_f32_e32 v81, 1.0, v81
	v_add_f32_e32 v82, 1.0, v82
	v_add_f32_e32 v83, 1.0, v83
	v_add_f32_e32 v84, 1.0, v84
	v_add_f32_e32 v85, 1.0, v85
	v_mul_f32_e32 v0, v54, v70
	v_mul_f32_e32 v1, v55, v71
	v_mul_f32_e32 v2, v56, v72
	v_mul_f32_e32 v3, v57, v73
	v_mul_f32_e32 v4, v58, v74
	v_mul_f32_e32 v5, v59, v75
	v_mul_f32_e32 v6, v60, v76
	v_mul_f32_e32 v7, v61, v77
	v_mul_f32_e32 v8, v62, v78
	v_mul_f32_e32 v9, v63, v79
	v_mul_f32_e32 v10, v64, v80
	v_mul_f32_e32 v11, v65, v81
	v_mul_f32_e32 v12, v66, v82
	v_mul_f32_e32 v13, v67, v83
	v_mul_f32_e32 v14, v68, v84
	v_mul_f32_e32 v15, v69, v85
.Lr1b_nr1:
	s_waitcnt vmcnt(44)
	v_accvgpr_read_b32 v54, a0
	v_accvgpr_read_b32 v55, a1
	v_accvgpr_read_b32 v56, a2
	v_accvgpr_read_b32 v57, a3
	v_accvgpr_read_b32 v58, a4
	v_accvgpr_read_b32 v59, a5
	v_accvgpr_read_b32 v60, a6
	v_accvgpr_read_b32 v61, a7
	v_accvgpr_read_b32 v62, a8
	v_accvgpr_read_b32 v63, a9
	v_accvgpr_read_b32 v64, a10
	v_accvgpr_read_b32 v65, a11
	v_accvgpr_read_b32 v66, a12
	v_accvgpr_read_b32 v67, a13
	v_accvgpr_read_b32 v68, a14
	v_accvgpr_read_b32 v69, a15
	v_accvgpr_read_b32 v70, a16
	v_accvgpr_read_b32 v71, a17
	v_accvgpr_read_b32 v72, a18
	v_accvgpr_read_b32 v73, a19
	v_accvgpr_read_b32 v74, a20
	v_accvgpr_read_b32 v75, a21
	v_accvgpr_read_b32 v76, a22
	v_accvgpr_read_b32 v77, a23
	v_accvgpr_read_b32 v78, a24
	v_accvgpr_read_b32 v79, a25
	v_accvgpr_read_b32 v80, a26
	v_accvgpr_read_b32 v81, a27
	v_accvgpr_read_b32 v82, a28
	v_accvgpr_read_b32 v83, a29
	v_accvgpr_read_b32 v84, a30
	v_accvgpr_read_b32 v85, a31
	s_lshl_b32 s10, s5, 12
	s_cmp_lt_u32 s5, 0x800
	s_cselect_b64 s[34:35], s[48:49], s[50:51]
	s_add_u32 s34, s34, s10
	s_addc_u32 s35, s35, 0
	s_lshr_b32 s10, s10, 1
	s_add_u32 s36, s54, s10
	s_addc_u32 s37, s55, 0
	s_cmp_lt_u32 s7, 0x800
	s_cselect_b64 s[60:61], s[48:49], s[50:51]
	s_lshl_b32 s10, s7, 12
	s_add_u32 s60, s60, s10
	s_addc_u32 s61, s61, 0
	global_load_dwordx4 a[0:3], v150, s[60:61] offset:0
	global_load_dwordx4 a[4:7], v150, s[60:61] offset:1024
	global_load_dwordx4 a[8:11], v150, s[60:61] offset:2048
	global_load_dwordx4 a[12:15], v150, s[60:61] offset:3072
	s_add_u32 s62, s52, s10
	s_addc_u32 s63, s53, 0
	global_load_dwordx2 a[16:17], v151, s[62:63] offset:0
	global_load_dwordx2 a[18:19], v151, s[62:63] offset:512
	global_load_dwordx2 a[20:21], v151, s[62:63] offset:1024
	global_load_dwordx2 a[22:23], v151, s[62:63] offset:1536
	global_load_dwordx2 a[24:25], v151, s[62:63] offset:2048
	global_load_dwordx2 a[26:27], v151, s[62:63] offset:2560
	global_load_dwordx2 a[28:29], v151, s[62:63] offset:3072
	global_load_dwordx2 a[30:31], v151, s[62:63] offset:3584
	s_add_u32 s7, s7, 1
	v_cvt_f32_f16_e32 v154, v70
	v_cvt_f32_f16_e32 v155, v78
	v_add_f32_e32 v154, v154, v155
	v_fmac_f32_e32 v54, v32, v154
	v_cvt_f32_f16_sdwa v156, v70 dst_sel:DWORD dst_unused:UNUSED_PAD src0_sel:WORD_1
	v_cvt_f32_f16_sdwa v157, v78 dst_sel:DWORD dst_unused:UNUSED_PAD src0_sel:WORD_1
	v_add_f32_e32 v156, v156, v157
	v_fmac_f32_e32 v55, v33, v156
	v_cvt_f32_f16_e32 v154, v71
	v_cvt_f32_f16_e32 v155, v79
	v_add_f32_e32 v154, v154, v155
	v_fmac_f32_e32 v56, v34, v154
	v_cvt_f32_f16_sdwa v156, v71 dst_sel:DWORD dst_unused:UNUSED_PAD src0_sel:WORD_1
	v_cvt_f32_f16_sdwa v157, v79 dst_sel:DWORD dst_unused:UNUSED_PAD src0_sel:WORD_1
	v_add_f32_e32 v156, v156, v157
	v_fmac_f32_e32 v57, v35, v156
	v_cvt_f32_f16_e32 v154, v72
	v_cvt_f32_f16_e32 v155, v80
	v_add_f32_e32 v154, v154, v155
	v_fmac_f32_e32 v58, v36, v154
	v_cvt_f32_f16_sdwa v156, v72 dst_sel:DWORD dst_unused:UNUSED_PAD src0_sel:WORD_1
	v_cvt_f32_f16_sdwa v157, v80 dst_sel:DWORD dst_unused:UNUSED_PAD src0_sel:WORD_1
	v_add_f32_e32 v156, v156, v157
	v_fmac_f32_e32 v59, v37, v156
	v_cvt_f32_f16_e32 v154, v73
	v_cvt_f32_f16_e32 v155, v81
	v_add_f32_e32 v154, v154, v155
	v_fmac_f32_e32 v60, v38, v154
	v_cvt_f32_f16_sdwa v156, v73 dst_sel:DWORD dst_unused:UNUSED_PAD src0_sel:WORD_1
; DI void row1_phase(const Params& P, int combine_l, int norm_l, int r_begin) {
;     ...
; #pragma unroll
;       for (int i = 0; i < 4; i++) {
;         int c = i * 256 + lane * 4;
;         float4 g = *(const float4*)(g2 + c); float4 t = xv[i];
;         t.x += g.x * ((float)ya[i][0] + (float)yb[i][0]); t.y += g.y * ((float)ya[i][1] + (float)yb[i][1]);
;         t.z += g.z * ((float)ya[i][2] + (float)yb[i][2]); t.w += g.w * ((float)ya[i][3] + (float)yb[i][3]);
;         *(float4*)(xm + c) = t; xv[i] = t;
;       }
;     }
;     if (norm_l >= 0) {
;       float ss = 0.f;
; #pragma unroll
;       for (int i = 0; i < 4; i++) ss += xv[i].x * xv[i].x + xv[i].y * xv[i].y + xv[i].z * xv[i].z + xv[i].w * xv[i].w;
;       ss = wave_sum(ss);
;       const float rstd = rsqrtf(ss * (1.f / 1024.f) + EPS);
;       const float* g = P.norm1_g + norm_l * 1024;
;       const float* sh = P.mod + (size_t)(norm_l * 9 + n) * 6144; const float* sc = sh + 1024;
; #pragma unroll
;       for (int i = 0; i < 4; i++) {
;         int c = i * 256 + lane * 4;
;         float4 gg = *(const float4*)(g + c), s1 = *(const float4*)(sc + c), s0 = *(const float4*)(sh + c);
;         h4 o;
;         o[0] = (half_t)(xv[i].x * rstd * gg.x * (1.f + s1.x) + s0.x); o[1] = (half_t)(xv[i].y * rstd * gg.y * (1.f + s1.y) + s0.y);
;         o[2] = (half_t)(xv[i].z * rstd * gg.z * (1.f + s1.z) + s0.z); o[3] = (half_t)(xv[i].w * rstd * gg.w * (1.f + s1.w) + s0.w);
;         *(h4*)(P.hx + (size_t)r * D + c) = o;
;       }
;     }
	v_cvt_f32_f16_sdwa v157, v81 dst_sel:DWORD dst_unused:UNUSED_PAD src0_sel:WORD_1
	v_add_f32_e32 v156, v156, v157
	v_fmac_f32_e32 v61, v39, v156
	v_cvt_f32_f16_e32 v154, v74
	v_cvt_f32_f16_e32 v155, v82
	v_add_f32_e32 v154, v154, v155
	v_fmac_f32_e32 v62, v40, v154
	v_cvt_f32_f16_sdwa v156, v74 dst_sel:DWORD dst_unused:UNUSED_PAD src0_sel:WORD_1
	v_cvt_f32_f16_sdwa v157, v82 dst_sel:DWORD dst_unused:UNUSED_PAD src0_sel:WORD_1
	v_add_f32_e32 v156, v156, v157
	v_fmac_f32_e32 v63, v41, v156
	v_cvt_f32_f16_e32 v154, v75
	v_cvt_f32_f16_e32 v155, v83
	v_add_f32_e32 v154, v154, v155
	v_fmac_f32_e32 v64, v42, v154
	v_cvt_f32_f16_sdwa v156, v75 dst_sel:DWORD dst_unused:UNUSED_PAD src0_sel:WORD_1
	v_cvt_f32_f16_sdwa v157, v83 dst_sel:DWORD dst_unused:UNUSED_PAD src0_sel:WORD_1
	v_add_f32_e32 v156, v156, v157
	v_fmac_f32_e32 v65, v43, v156
	v_cvt_f32_f16_e32 v154, v76
	v_cvt_f32_f16_e32 v155, v84
	v_add_f32_e32 v154, v154, v155
	v_fmac_f32_e32 v66, v44, v154
	v_cvt_f32_f16_sdwa v156, v76 dst_sel:DWORD dst_unused:UNUSED_PAD src0_sel:WORD_1
	v_cvt_f32_f16_sdwa v157, v84 dst_sel:DWORD dst_unused:UNUSED_PAD src0_sel:WORD_1
	v_add_f32_e32 v156, v156, v157
	v_fmac_f32_e32 v67, v45, v156
	v_cvt_f32_f16_e32 v154, v77
	v_cvt_f32_f16_e32 v155, v85
	v_add_f32_e32 v154, v154, v155
	v_fmac_f32_e32 v68, v46, v154
	v_cvt_f32_f16_sdwa v156, v77 dst_sel:DWORD dst_unused:UNUSED_PAD src0_sel:WORD_1
	v_cvt_f32_f16_sdwa v157, v85 dst_sel:DWORD dst_unused:UNUSED_PAD src0_sel:WORD_1
	v_add_f32_e32 v156, v156, v157
	v_fmac_f32_e32 v69, v47, v156
	global_store_dwordx4 v150, v[54:57], s[34:35] offset:0
	global_store_dwordx4 v150, v[58:61], s[34:35] offset:1024
	global_store_dwordx4 v150, v[62:65], s[34:35] offset:2048
	global_store_dwordx4 v150, v[66:69], s[34:35] offset:3072
	v_mul_f32_e32 v152, v54, v54
	v_mul_f32_e32 v153, v55, v55
	v_fmac_f32_e32 v152, v56, v56
	v_fmac_f32_e32 v153, v57, v57
	v_fmac_f32_e32 v152, v58, v58
	v_fmac_f32_e32 v153, v59, v59
	v_fmac_f32_e32 v152, v60, v60
	v_fmac_f32_e32 v153, v61, v61
	v_fmac_f32_e32 v152, v62, v62
	v_fmac_f32_e32 v153, v63, v63
	v_fmac_f32_e32 v152, v64, v64
	v_fmac_f32_e32 v153, v65, v65
	v_fmac_f32_e32 v152, v66, v66
	v_fmac_f32_e32 v153, v67, v67
	v_fmac_f32_e32 v152, v68, v68
	v_fmac_f32_e32 v153, v69, v69
	v_add_f32_e32 v152, v152, v153
	v_xor_b32_e32 v158, 128, v159
	ds_bpermute_b32 v153, v158, v152
	s_waitcnt lgkmcnt(0)
	v_add_f32_e32 v152, v152, v153
	v_xor_b32_e32 v158, 64, v159
	ds_bpermute_b32 v153, v158, v152
	s_waitcnt lgkmcnt(0)
	v_add_f32_e32 v152, v152, v153
	v_xor_b32_e32 v158, 32, v159
	ds_bpermute_b32 v153, v158, v152
	s_waitcnt lgkmcnt(0)
	v_add_f32_e32 v152, v152, v153
	v_xor_b32_e32 v158, 16, v159
	ds_bpermute_b32 v153, v158, v152
	s_waitcnt lgkmcnt(0)
	v_add_f32_e32 v152, v152, v153
	v_xor_b32_e32 v158, 8, v159
	ds_bpermute_b32 v153, v158, v152
	s_waitcnt lgkmcnt(0)
	v_add_f32_e32 v152, v152, v153
	v_xor_b32_e32 v158, 4, v159
	ds_bpermute_b32 v153, v158, v152
	s_waitcnt lgkmcnt(0)
	v_add_f32_e32 v152, v152, v153
	v_mov_b32_e32 v153, 0x358637bd
	v_fmamk_f32 v152, v152, 0x3a800000, v153
	v_rsq_f32_e32 v152, v152
	s_nop 1
	v_mul_f32_e32 v54, v54, v152
	v_mul_f32_e32 v55, v55, v152
	v_mul_f32_e32 v56, v56, v152
	v_mul_f32_e32 v57, v57, v152
	v_mul_f32_e32 v58, v58, v152
	v_mul_f32_e32 v59, v59, v152
	v_mul_f32_e32 v60, v60, v152
	v_mul_f32_e32 v61, v61, v152
	v_mul_f32_e32 v62, v62, v152
	v_mul_f32_e32 v63, v63, v152
	v_mul_f32_e32 v64, v64, v152
	v_mul_f32_e32 v65, v65, v152
	v_mul_f32_e32 v66, v66, v152
	v_mul_f32_e32 v67, v67, v152
	v_mul_f32_e32 v68, v68, v152
	v_mul_f32_e32 v69, v69, v152
	v_fma_f32 v54, v54, v0, v16
	v_fma_f32 v55, v55, v1, v17
	v_fma_f32 v56, v56, v2, v18
	v_fma_f32 v57, v57, v3, v19
	v_fma_f32 v58, v58, v4, v20
	v_fma_f32 v59, v59, v5, v21
	v_fma_f32 v60, v60, v6, v22
	v_fma_f32 v61, v61, v7, v23
	v_fma_f32 v62, v62, v8, v24
	v_fma_f32 v63, v63, v9, v25
	v_fma_f32 v64, v64, v10, v26
	v_fma_f32 v65, v65, v11, v27
	v_fma_f32 v66, v66, v12, v28
	v_fma_f32 v67, v67, v13, v29
	v_fma_f32 v68, v68, v14, v30
	v_fma_f32 v69, v69, v15, v31
	v_cvt_pk_f16_f32 v70, v54, v55
	v_cvt_pk_f16_f32 v71, v56, v57
	v_cvt_pk_f16_f32 v72, v58, v59
	v_cvt_pk_f16_f32 v73, v60, v61
	v_cvt_pk_f16_f32 v74, v62, v63
	v_cvt_pk_f16_f32 v75, v64, v65
	v_cvt_pk_f16_f32 v76, v66, v67
	v_cvt_pk_f16_f32 v77, v68, v69
	global_store_dwordx2 v151, v[70:71], s[36:37] offset:0
	global_store_dwordx2 v151, v[72:73], s[36:37] offset:512
	global_store_dwordx2 v151, v[74:75], s[36:37] offset:1024
	global_store_dwordx2 v151, v[76:77], s[36:37] offset:1536
	s_add_u32 s5, s5, 1
	s_sub_u32 s9, s5, 0x800
	s_lshr_b32 s9, s9, 13
	s_cmp_lt_u32 s5, 0x800
	s_cselect_b32 s9, 8, s9
	s_cmp_eq_u32 s9, s8
	s_cbranch_scc1 .Lr1b_nr2
	s_mov_b32 s8, s9
	s_waitcnt vmcnt(0)
	s_add_u32 s10, s9, 9
	s_mul_i32 s10, s10, 0x6000
	s_add_u32 s38, s56, s10
	s_addc_u32 s39, s57, 0
	global_load_dwordx4 v[54:57], v150, s[58:59] offset:0
	global_load_dwordx4 v[58:61], v150, s[58:59] offset:1024
	global_load_dwordx4 v[62:65], v150, s[58:59] offset:2048
	global_load_dwordx4 v[66:69], v150, s[58:59] offset:3072
	s_add_u32 s44, s38, 0x1000
	s_addc_u32 s45, s39, 0
	global_load_dwordx4 v[70:73], v150, s[44:45] offset:0
	global_load_dwordx4 v[74:77], v150, s[44:45] offset:1024
	global_load_dwordx4 v[78:81], v150, s[44:45] offset:2048
	global_load_dwordx4 v[82:85], v150, s[44:45] offset:3072
	global_load_dwordx4 v[16:19], v150, s[38:39] offset:0
	global_load_dwordx4 v[20:23], v150, s[38:39] offset:1024
	global_load_dwordx4 v[24:27], v150, s[38:39] offset:2048
	global_load_dwordx4 v[28:31], v150, s[38:39] offset:3072
	s_add_u32 s10, s9, 0
	s_mul_i32 s10, s10, 0x6000
	s_add_u32 s10, s10, 0x5000
	s_add_u32 s38, s56, s10
	s_addc_u32 s39, s57, 0
	global_load_dwordx4 v[32:35], v150, s[38:39] offset:0
	global_load_dwordx4 v[36:39], v150, s[38:39] offset:1024
	global_load_dwordx4 v[40:43], v150, s[38:39] offset:2048
	global_load_dwordx4 v[44:47], v150, s[38:39] offset:3072
	s_waitcnt vmcnt(0)
	v_add_f32_e32 v70, 1.0, v70
	v_add_f32_e32 v71, 1.0, v71
	v_add_f32_e32 v72, 1.0, v72
	v_add_f32_e32 v73, 1.0, v73
	v_add_f32_e32 v74, 1.0, v74
	v_add_f32_e32 v75, 1.0, v75
	v_add_f32_e32 v76, 1.0, v76
	v_add_f32_e32 v77, 1.0, v77
	v_add_f32_e32 v78, 1.0, v78
	v_add_f32_e32 v79, 1.0, v79
	v_add_f32_e32 v80, 1.0, v80
	v_add_f32_e32 v81, 1.0, v81
	v_add_f32_e32 v82, 1.0, v82
	v_add_f32_e32 v83, 1.0, v83
	v_add_f32_e32 v84, 1.0, v84
	v_add_f32_e32 v85, 1.0, v85
	v_mul_f32_e32 v0, v54, v70
	v_mul_f32_e32 v1, v55, v71
	v_mul_f32_e32 v2, v56, v72
	v_mul_f32_e32 v3, v57, v73
	v_mul_f32_e32 v4, v58, v74
	v_mul_f32_e32 v5, v59, v75
	v_mul_f32_e32 v6, v60, v76
	v_mul_f32_e32 v7, v61, v77
	v_mul_f32_e32 v8, v62, v78
	v_mul_f32_e32 v9, v63, v79
	v_mul_f32_e32 v10, v64, v80
	v_mul_f32_e32 v11, v65, v81
	v_mul_f32_e32 v12, v66, v82
	v_mul_f32_e32 v13, v67, v83
	v_mul_f32_e32 v14, v68, v84
	v_mul_f32_e32 v15, v69, v85
; DI void row1_phase(const Params& P, int combine_l, int norm_l, int r_begin) {
;     ...
;       for (int i = 0; i < 4; i++) { int c = i * 256 + lane * 4; xv[i] = *(const float4*)(xm + c); ya[i] = *(const h4*)(y0 + c); yb[i] = *(const h4*)(y1 + c); }
;     }
;   };
;   auto process = [&](int r, float4 (&xv)[4], h4 (&ya)[4], h4 (&yb)[4]) {
;     const int n = row_mod(r);
;     if (combine_l >= 0) {
;       float* xm = r < TC ? P.xcbuf + (size_t)r * D : P.out + (size_t)(r - TC) * D;
;       const float* g2 = P.mod + (size_t)(combine_l * 9 + n) * 6144 + 5 * 1024;
; #pragma unroll
;       for (int i = 0; i < 4; i++) {
;         int c = i * 256 + lane * 4;
;         float4 g = *(const float4*)(g2 + c); float4 t = xv[i];
;         t.x += g.x * ((float)ya[i][0] + (float)yb[i][0]); t.y += g.y * ((float)ya[i][1] + (float)yb[i][1]);
;         t.z += g.z * ((float)ya[i][2] + (float)yb[i][2]); t.w += g.w * ((float)ya[i][3] + (float)yb[i][3]);
;         *(float4*)(xm + c) = t; xv[i] = t;
;       }
;     }
;     if (norm_l >= 0) {
;       float ss = 0.f;
; #pragma unroll
;       for (int i = 0; i < 4; i++) ss += xv[i].x * xv[i].x + xv[i].y * xv[i].y + xv[i].z * xv[i].z + xv[i].w * xv[i].w;
;       ss = wave_sum(ss);
.Lr1b_nr2:
	s_waitcnt vmcnt(44)
	v_accvgpr_read_b32 v54, a32
	v_accvgpr_read_b32 v55, a33
	v_accvgpr_read_b32 v56, a34
	v_accvgpr_read_b32 v57, a35
	v_accvgpr_read_b32 v58, a36
	v_accvgpr_read_b32 v59, a37
	v_accvgpr_read_b32 v60, a38
	v_accvgpr_read_b32 v61, a39
	v_accvgpr_read_b32 v62, a40
	v_accvgpr_read_b32 v63, a41
	v_accvgpr_read_b32 v64, a42
	v_accvgpr_read_b32 v65, a43
	v_accvgpr_read_b32 v66, a44
	v_accvgpr_read_b32 v67, a45
	v_accvgpr_read_b32 v68, a46
	v_accvgpr_read_b32 v69, a47
	v_accvgpr_read_b32 v70, a48
	v_accvgpr_read_b32 v71, a49
	v_accvgpr_read_b32 v72, a50
	v_accvgpr_read_b32 v73, a51
	v_accvgpr_read_b32 v74, a52
	v_accvgpr_read_b32 v75, a53
	v_accvgpr_read_b32 v76, a54
	v_accvgpr_read_b32 v77, a55
	v_accvgpr_read_b32 v78, a56
	v_accvgpr_read_b32 v79, a57
	v_accvgpr_read_b32 v80, a58
	v_accvgpr_read_b32 v81, a59
	v_accvgpr_read_b32 v82, a60
	v_accvgpr_read_b32 v83, a61
	v_accvgpr_read_b32 v84, a62
	v_accvgpr_read_b32 v85, a63
	s_lshl_b32 s10, s5, 12
	s_cmp_lt_u32 s5, 0x800
	s_cselect_b64 s[34:35], s[48:49], s[50:51]
	s_add_u32 s34, s34, s10
	s_addc_u32 s35, s35, 0
	s_lshr_b32 s10, s10, 1
	s_add_u32 s36, s54, s10
	s_addc_u32 s37, s55, 0
	s_cmp_lt_u32 s7, 0x800
	s_cselect_b64 s[60:61], s[48:49], s[50:51]
	s_lshl_b32 s10, s7, 12
	s_add_u32 s60, s60, s10
	s_addc_u32 s61, s61, 0
	global_load_dwordx4 a[32:35], v150, s[60:61] offset:0
	global_load_dwordx4 a[36:39], v150, s[60:61] offset:1024
	global_load_dwordx4 a[40:43], v150, s[60:61] offset:2048
	global_load_dwordx4 a[44:47], v150, s[60:61] offset:3072
	s_add_u32 s62, s52, s10
	s_addc_u32 s63, s53, 0
	global_load_dwordx2 a[48:49], v151, s[62:63] offset:0
	global_load_dwordx2 a[50:51], v151, s[62:63] offset:512
	global_load_dwordx2 a[52:53], v151, s[62:63] offset:1024
	global_load_dwordx2 a[54:55], v151, s[62:63] offset:1536
	global_load_dwordx2 a[56:57], v151, s[62:63] offset:2048
	global_load_dwordx2 a[58:59], v151, s[62:63] offset:2560
	global_load_dwordx2 a[60:61], v151, s[62:63] offset:3072
	global_load_dwordx2 a[62:63], v151, s[62:63] offset:3584
	s_add_u32 s7, s7, 1
	v_cvt_f32_f16_e32 v154, v70
	v_cvt_f32_f16_e32 v155, v78
	v_add_f32_e32 v154, v154, v155
	v_fmac_f32_e32 v54, v32, v154
	v_cvt_f32_f16_sdwa v156, v70 dst_sel:DWORD dst_unused:UNUSED_PAD src0_sel:WORD_1
	v_cvt_f32_f16_sdwa v157, v78 dst_sel:DWORD dst_unused:UNUSED_PAD src0_sel:WORD_1
	v_add_f32_e32 v156, v156, v157
	v_fmac_f32_e32 v55, v33, v156
	v_cvt_f32_f16_e32 v154, v71
	v_cvt_f32_f16_e32 v155, v79
	v_add_f32_e32 v154, v154, v155
	v_fmac_f32_e32 v56, v34, v154
	v_cvt_f32_f16_sdwa v156, v71 dst_sel:DWORD dst_unused:UNUSED_PAD src0_sel:WORD_1
	v_cvt_f32_f16_sdwa v157, v79 dst_sel:DWORD dst_unused:UNUSED_PAD src0_sel:WORD_1
	v_add_f32_e32 v156, v156, v157
	v_fmac_f32_e32 v57, v35, v156
	v_cvt_f32_f16_e32 v154, v72
	v_cvt_f32_f16_e32 v155, v80
	v_add_f32_e32 v154, v154, v155
	v_fmac_f32_e32 v58, v36, v154
	v_cvt_f32_f16_sdwa v156, v72 dst_sel:DWORD dst_unused:UNUSED_PAD src0_sel:WORD_1
	v_cvt_f32_f16_sdwa v157, v80 dst_sel:DWORD dst_unused:UNUSED_PAD src0_sel:WORD_1
	v_add_f32_e32 v156, v156, v157
	v_fmac_f32_e32 v59, v37, v156
	v_cvt_f32_f16_e32 v154, v73
	v_cvt_f32_f16_e32 v155, v81
	v_add_f32_e32 v154, v154, v155
	v_fmac_f32_e32 v60, v38, v154
	v_cvt_f32_f16_sdwa v156, v73 dst_sel:DWORD dst_unused:UNUSED_PAD src0_sel:WORD_1
	v_cvt_f32_f16_sdwa v157, v81 dst_sel:DWORD dst_unused:UNUSED_PAD src0_sel:WORD_1
	v_add_f32_e32 v156, v156, v157
	v_fmac_f32_e32 v61, v39, v156
	v_cvt_f32_f16_e32 v154, v74
	v_cvt_f32_f16_e32 v155, v82
	v_add_f32_e32 v154, v154, v155
	v_fmac_f32_e32 v62, v40, v154
	v_cvt_f32_f16_sdwa v156, v74 dst_sel:DWORD dst_unused:UNUSED_PAD src0_sel:WORD_1
	v_cvt_f32_f16_sdwa v157, v82 dst_sel:DWORD dst_unused:UNUSED_PAD src0_sel:WORD_1
	v_add_f32_e32 v156, v156, v157
	v_fmac_f32_e32 v63, v41, v156
	v_cvt_f32_f16_e32 v154, v75
	v_cvt_f32_f16_e32 v155, v83
	v_add_f32_e32 v154, v154, v155
	v_fmac_f32_e32 v64, v42, v154
	v_cvt_f32_f16_sdwa v156, v75 dst_sel:DWORD dst_unused:UNUSED_PAD src0_sel:WORD_1
	v_cvt_f32_f16_sdwa v157, v83 dst_sel:DWORD dst_unused:UNUSED_PAD src0_sel:WORD_1
	v_add_f32_e32 v156, v156, v157
	v_fmac_f32_e32 v65, v43, v156
	v_cvt_f32_f16_e32 v154, v76
	v_cvt_f32_f16_e32 v155, v84
	v_add_f32_e32 v154, v154, v155
	v_fmac_f32_e32 v66, v44, v154
	v_cvt_f32_f16_sdwa v156, v76 dst_sel:DWORD dst_unused:UNUSED_PAD src0_sel:WORD_1
	v_cvt_f32_f16_sdwa v157, v84 dst_sel:DWORD dst_unused:UNUSED_PAD src0_sel:WORD_1
	v_add_f32_e32 v156, v156, v157
	v_fmac_f32_e32 v67, v45, v156
	v_cvt_f32_f16_e32 v154, v77
	v_cvt_f32_f16_e32 v155, v85
	v_add_f32_e32 v154, v154, v155
	v_fmac_f32_e32 v68, v46, v154
	v_cvt_f32_f16_sdwa v156, v77 dst_sel:DWORD dst_unused:UNUSED_PAD src0_sel:WORD_1
	v_cvt_f32_f16_sdwa v157, v85 dst_sel:DWORD dst_unused:UNUSED_PAD src0_sel:WORD_1
	v_add_f32_e32 v156, v156, v157
	v_fmac_f32_e32 v69, v47, v156
	global_store_dwordx4 v150, v[54:57], s[34:35] offset:0
	global_store_dwordx4 v150, v[58:61], s[34:35] offset:1024
	global_store_dwordx4 v150, v[62:65], s[34:35] offset:2048
	global_store_dwordx4 v150, v[66:69], s[34:35] offset:3072
	v_mul_f32_e32 v152, v54, v54
	v_mul_f32_e32 v153, v55, v55
	v_fmac_f32_e32 v152, v56, v56
	v_fmac_f32_e32 v153, v57, v57
	v_fmac_f32_e32 v152, v58, v58
	v_fmac_f32_e32 v153, v59, v59
	v_fmac_f32_e32 v152, v60, v60
	v_fmac_f32_e32 v153, v61, v61
	v_fmac_f32_e32 v152, v62, v62
	v_fmac_f32_e32 v153, v63, v63
	v_fmac_f32_e32 v152, v64, v64
	v_fmac_f32_e32 v153, v65, v65
	v_fmac_f32_e32 v152, v66, v66
	v_fmac_f32_e32 v153, v67, v67
	v_fmac_f32_e32 v152, v68, v68
	v_fmac_f32_e32 v153, v69, v69
	v_add_f32_e32 v152, v152, v153
	v_xor_b32_e32 v158, 128, v159
	ds_bpermute_b32 v153, v158, v152
	s_waitcnt lgkmcnt(0)
; DI void row1_phase(const Params& P, int combine_l, int norm_l, int r_begin) {
;     ...
;       float ss = 0.f;
; #pragma unroll
;       for (int i = 0; i < 4; i++) ss += xv[i].x * xv[i].x + xv[i].y * xv[i].y + xv[i].z * xv[i].z + xv[i].w * xv[i].w;
;       ss = wave_sum(ss);
;       const float rstd = rsqrtf(ss * (1.f / 1024.f) + EPS);
;       const float* g = P.norm1_g + norm_l * 1024;
;       const float* sh = P.mod + (size_t)(norm_l * 9 + n) * 6144; const float* sc = sh + 1024;
; #pragma unroll
;       for (int i = 0; i < 4; i++) {
;         int c = i * 256 + lane * 4;
;         float4 gg = *(const float4*)(g + c), s1 = *(const float4*)(sc + c), s0 = *(const float4*)(sh + c);
;         h4 o;
;         o[0] = (half_t)(xv[i].x * rstd * gg.x * (1.f + s1.x) + s0.x); o[1] = (half_t)(xv[i].y * rstd * gg.y * (1.f + s1.y) + s0.y);
;         o[2] = (half_t)(xv[i].z * rstd * gg.z * (1.f + s1.z) + s0.z); o[3] = (half_t)(xv[i].w * rstd * gg.w * (1.f + s1.w) + s0.w);
;         *(h4*)(P.hx + (size_t)r * D + c) = o;
;       }
;     }
	v_add_f32_e32 v152, v152, v153
	v_xor_b32_e32 v158, 64, v159
	ds_bpermute_b32 v153, v158, v152
	s_waitcnt lgkmcnt(0)
	v_add_f32_e32 v152, v152, v153
	v_xor_b32_e32 v158, 32, v159
	ds_bpermute_b32 v153, v158, v152
	s_waitcnt lgkmcnt(0)
	v_add_f32_e32 v152, v152, v153
	v_xor_b32_e32 v158, 16, v159
	ds_bpermute_b32 v153, v158, v152
	s_waitcnt lgkmcnt(0)
	v_add_f32_e32 v152, v152, v153
	v_xor_b32_e32 v158, 8, v159
	ds_bpermute_b32 v153, v158, v152
	s_waitcnt lgkmcnt(0)
	v_add_f32_e32 v152, v152, v153
	v_xor_b32_e32 v158, 4, v159
	ds_bpermute_b32 v153, v158, v152
	s_waitcnt lgkmcnt(0)
	v_add_f32_e32 v152, v152, v153
	v_mov_b32_e32 v153, 0x358637bd
	v_fmamk_f32 v152, v152, 0x3a800000, v153
	v_rsq_f32_e32 v152, v152
	s_nop 1
	v_mul_f32_e32 v54, v54, v152
	v_mul_f32_e32 v55, v55, v152
	v_mul_f32_e32 v56, v56, v152
	v_mul_f32_e32 v57, v57, v152
	v_mul_f32_e32 v58, v58, v152
	v_mul_f32_e32 v59, v59, v152
	v_mul_f32_e32 v60, v60, v152
	v_mul_f32_e32 v61, v61, v152
	v_mul_f32_e32 v62, v62, v152
	v_mul_f32_e32 v63, v63, v152
	v_mul_f32_e32 v64, v64, v152
	v_mul_f32_e32 v65, v65, v152
	v_mul_f32_e32 v66, v66, v152
	v_mul_f32_e32 v67, v67, v152
	v_mul_f32_e32 v68, v68, v152
	v_mul_f32_e32 v69, v69, v152
	v_fma_f32 v54, v54, v0, v16
	v_fma_f32 v55, v55, v1, v17
	v_fma_f32 v56, v56, v2, v18
	v_fma_f32 v57, v57, v3, v19
	v_fma_f32 v58, v58, v4, v20
	v_fma_f32 v59, v59, v5, v21
	v_fma_f32 v60, v60, v6, v22
	v_fma_f32 v61, v61, v7, v23
	v_fma_f32 v62, v62, v8, v24
	v_fma_f32 v63, v63, v9, v25
	v_fma_f32 v64, v64, v10, v26
	v_fma_f32 v65, v65, v11, v27
	v_fma_f32 v66, v66, v12, v28
	v_fma_f32 v67, v67, v13, v29
	v_fma_f32 v68, v68, v14, v30
	v_fma_f32 v69, v69, v15, v31
	v_cvt_pk_f16_f32 v70, v54, v55
	v_cvt_pk_f16_f32 v71, v56, v57
	v_cvt_pk_f16_f32 v72, v58, v59
	v_cvt_pk_f16_f32 v73, v60, v61
	v_cvt_pk_f16_f32 v74, v62, v63
	v_cvt_pk_f16_f32 v75, v64, v65
	v_cvt_pk_f16_f32 v76, v66, v67
	v_cvt_pk_f16_f32 v77, v68, v69
	global_store_dwordx2 v151, v[70:71], s[36:37] offset:0
	global_store_dwordx2 v151, v[72:73], s[36:37] offset:512
	global_store_dwordx2 v151, v[74:75], s[36:37] offset:1024
	global_store_dwordx2 v151, v[76:77], s[36:37] offset:1536
	s_add_u32 s5, s5, 1
	s_sub_u32 s9, s5, 0x800
	s_lshr_b32 s9, s9, 13
	s_cmp_lt_u32 s5, 0x800
	s_cselect_b32 s9, 8, s9
	s_cmp_eq_u32 s9, s8
	s_cbranch_scc1 .Lr1b_nr3
	s_mov_b32 s8, s9
	s_waitcnt vmcnt(0)
	s_add_u32 s10, s9, 9
	s_mul_i32 s10, s10, 0x6000
	s_add_u32 s38, s56, s10
	s_addc_u32 s39, s57, 0
	global_load_dwordx4 v[54:57], v150, s[58:59] offset:0
	global_load_dwordx4 v[58:61], v150, s[58:59] offset:1024
	global_load_dwordx4 v[62:65], v150, s[58:59] offset:2048
	global_load_dwordx4 v[66:69], v150, s[58:59] offset:3072
	s_add_u32 s44, s38, 0x1000
	s_addc_u32 s45, s39, 0
	global_load_dwordx4 v[70:73], v150, s[44:45] offset:0
	global_load_dwordx4 v[74:77], v150, s[44:45] offset:1024
	global_load_dwordx4 v[78:81], v150, s[44:45] offset:2048
	global_load_dwordx4 v[82:85], v150, s[44:45] offset:3072
	global_load_dwordx4 v[16:19], v150, s[38:39] offset:0
	global_load_dwordx4 v[20:23], v150, s[38:39] offset:1024
	global_load_dwordx4 v[24:27], v150, s[38:39] offset:2048
	global_load_dwordx4 v[28:31], v150, s[38:39] offset:3072
	s_add_u32 s10, s9, 0
	s_mul_i32 s10, s10, 0x6000
	s_add_u32 s10, s10, 0x5000
	s_add_u32 s38, s56, s10
	s_addc_u32 s39, s57, 0
	global_load_dwordx4 v[32:35], v150, s[38:39] offset:0
	global_load_dwordx4 v[36:39], v150, s[38:39] offset:1024
	global_load_dwordx4 v[40:43], v150, s[38:39] offset:2048
	global_load_dwordx4 v[44:47], v150, s[38:39] offset:3072
	s_waitcnt vmcnt(0)
	v_add_f32_e32 v70, 1.0, v70
	v_add_f32_e32 v71, 1.0, v71
	v_add_f32_e32 v72, 1.0, v72
	v_add_f32_e32 v73, 1.0, v73
	v_add_f32_e32 v74, 1.0, v74
	v_add_f32_e32 v75, 1.0, v75
	v_add_f32_e32 v76, 1.0, v76
	v_add_f32_e32 v77, 1.0, v77
	v_add_f32_e32 v78, 1.0, v78
	v_add_f32_e32 v79, 1.0, v79
	v_add_f32_e32 v80, 1.0, v80
	v_add_f32_e32 v81, 1.0, v81
	v_add_f32_e32 v82, 1.0, v82
	v_add_f32_e32 v83, 1.0, v83
	v_add_f32_e32 v84, 1.0, v84
	v_add_f32_e32 v85, 1.0, v85
	v_mul_f32_e32 v0, v54, v70
	v_mul_f32_e32 v1, v55, v71
	v_mul_f32_e32 v2, v56, v72
	v_mul_f32_e32 v3, v57, v73
	v_mul_f32_e32 v4, v58, v74
	v_mul_f32_e32 v5, v59, v75
	v_mul_f32_e32 v6, v60, v76
	v_mul_f32_e32 v7, v61, v77
	v_mul_f32_e32 v8, v62, v78
	v_mul_f32_e32 v9, v63, v79
	v_mul_f32_e32 v10, v64, v80
	v_mul_f32_e32 v11, v65, v81
	v_mul_f32_e32 v12, v66, v82
	v_mul_f32_e32 v13, v67, v83
	v_mul_f32_e32 v14, v68, v84
	v_mul_f32_e32 v15, v69, v85
; DI void row1_phase(const Params& P, int combine_l, int norm_l, int r_begin) {
;     ...
;       for (int i = 0; i < 4; i++) { int c = i * 256 + lane * 4; xv[i] = *(const float4*)(xm + c); ya[i] = *(const h4*)(y0 + c); yb[i] = *(const h4*)(y1 + c); }
;     }
;   };
;   auto process = [&](int r, float4 (&xv)[4], h4 (&ya)[4], h4 (&yb)[4]) {
;     const int n = row_mod(r);
;     if (combine_l >= 0) {
;       float* xm = r < TC ? P.xcbuf + (size_t)r * D : P.out + (size_t)(r - TC) * D;
;       const float* g2 = P.mod + (size_t)(combine_l * 9 + n) * 6144 + 5 * 1024;
; #pragma unroll
;       for (int i = 0; i < 4; i++) {
;         int c = i * 256 + lane * 4;
;         float4 g = *(const float4*)(g2 + c); float4 t = xv[i];
;         t.x += g.x * ((float)ya[i][0] + (float)yb[i][0]); t.y += g.y * ((float)ya[i][1] + (float)yb[i][1]);
;         t.z += g.z * ((float)ya[i][2] + (float)yb[i][2]); t.w += g.w * ((float)ya[i][3] + (float)yb[i][3]);
;         *(float4*)(xm + c) = t; xv[i] = t;
;       }
;     }
;     if (norm_l >= 0) {
;       float ss = 0.f;
; #pragma unroll
;       for (int i = 0; i < 4; i++) ss += xv[i].x * xv[i].x + xv[i].y * xv[i].y + xv[i].z * xv[i].z + xv[i].w * xv[i].w;
;       ss = wave_sum(ss);
.Lr1b_nr3:
	s_waitcnt vmcnt(44)
	v_accvgpr_read_b32 v54, a64
	v_accvgpr_read_b32 v55, a65
	v_accvgpr_read_b32 v56, a66
	v_accvgpr_read_b32 v57, a67
	v_accvgpr_read_b32 v58, a68
	v_accvgpr_read_b32 v59, a69
	v_accvgpr_read_b32 v60, a70
	v_accvgpr_read_b32 v61, a71
	v_accvgpr_read_b32 v62, a72
	v_accvgpr_read_b32 v63, a73
	v_accvgpr_read_b32 v64, a74
	v_accvgpr_read_b32 v65, a75
	v_accvgpr_read_b32 v66, a76
	v_accvgpr_read_b32 v67, a77
	v_accvgpr_read_b32 v68, a78
	v_accvgpr_read_b32 v69, a79
	v_accvgpr_read_b32 v70, a80
	v_accvgpr_read_b32 v71, a81
	v_accvgpr_read_b32 v72, a82
	v_accvgpr_read_b32 v73, a83
	v_accvgpr_read_b32 v74, a84
	v_accvgpr_read_b32 v75, a85
	v_accvgpr_read_b32 v76, a86
	v_accvgpr_read_b32 v77, a87
	v_accvgpr_read_b32 v78, a88
	v_accvgpr_read_b32 v79, a89
	v_accvgpr_read_b32 v80, a90
	v_accvgpr_read_b32 v81, a91
	v_accvgpr_read_b32 v82, a92
	v_accvgpr_read_b32 v83, a93
	v_accvgpr_read_b32 v84, a94
	v_accvgpr_read_b32 v85, a95
	s_lshl_b32 s10, s5, 12
	s_cmp_lt_u32 s5, 0x800
	s_cselect_b64 s[34:35], s[48:49], s[50:51]
	s_add_u32 s34, s34, s10
	s_addc_u32 s35, s35, 0
	s_lshr_b32 s10, s10, 1
	s_add_u32 s36, s54, s10
	s_addc_u32 s37, s55, 0
	s_cmp_lt_u32 s7, 0x800
	s_cselect_b64 s[60:61], s[48:49], s[50:51]
	s_lshl_b32 s10, s7, 12
	s_add_u32 s60, s60, s10
	s_addc_u32 s61, s61, 0
	global_load_dwordx4 a[64:67], v150, s[60:61] offset:0
	global_load_dwordx4 a[68:71], v150, s[60:61] offset:1024
	global_load_dwordx4 a[72:75], v150, s[60:61] offset:2048
	global_load_dwordx4 a[76:79], v150, s[60:61] offset:3072
	s_add_u32 s62, s52, s10
	s_addc_u32 s63, s53, 0
	global_load_dwordx2 a[80:81], v151, s[62:63] offset:0
	global_load_dwordx2 a[82:83], v151, s[62:63] offset:512
	global_load_dwordx2 a[84:85], v151, s[62:63] offset:1024
	global_load_dwordx2 a[86:87], v151, s[62:63] offset:1536
	global_load_dwordx2 a[88:89], v151, s[62:63] offset:2048
	global_load_dwordx2 a[90:91], v151, s[62:63] offset:2560
	global_load_dwordx2 a[92:93], v151, s[62:63] offset:3072
	global_load_dwordx2 a[94:95], v151, s[62:63] offset:3584
	s_add_u32 s7, s7, 1
	v_cvt_f32_f16_e32 v154, v70
	v_cvt_f32_f16_e32 v155, v78
	v_add_f32_e32 v154, v154, v155
	v_fmac_f32_e32 v54, v32, v154
	v_cvt_f32_f16_sdwa v156, v70 dst_sel:DWORD dst_unused:UNUSED_PAD src0_sel:WORD_1
	v_cvt_f32_f16_sdwa v157, v78 dst_sel:DWORD dst_unused:UNUSED_PAD src0_sel:WORD_1
	v_add_f32_e32 v156, v156, v157
	v_fmac_f32_e32 v55, v33, v156
	v_cvt_f32_f16_e32 v154, v71
	v_cvt_f32_f16_e32 v155, v79
	v_add_f32_e32 v154, v154, v155
	v_fmac_f32_e32 v56, v34, v154
	v_cvt_f32_f16_sdwa v156, v71 dst_sel:DWORD dst_unused:UNUSED_PAD src0_sel:WORD_1
	v_cvt_f32_f16_sdwa v157, v79 dst_sel:DWORD dst_unused:UNUSED_PAD src0_sel:WORD_1
	v_add_f32_e32 v156, v156, v157
	v_fmac_f32_e32 v57, v35, v156
	v_cvt_f32_f16_e32 v154, v72
	v_cvt_f32_f16_e32 v155, v80
	v_add_f32_e32 v154, v154, v155
	v_fmac_f32_e32 v58, v36, v154
	v_cvt_f32_f16_sdwa v156, v72 dst_sel:DWORD dst_unused:UNUSED_PAD src0_sel:WORD_1
	v_cvt_f32_f16_sdwa v157, v80 dst_sel:DWORD dst_unused:UNUSED_PAD src0_sel:WORD_1
	v_add_f32_e32 v156, v156, v157
	v_fmac_f32_e32 v59, v37, v156
	v_cvt_f32_f16_e32 v154, v73
	v_cvt_f32_f16_e32 v155, v81
	v_add_f32_e32 v154, v154, v155
	v_fmac_f32_e32 v60, v38, v154
	v_cvt_f32_f16_sdwa v156, v73 dst_sel:DWORD dst_unused:UNUSED_PAD src0_sel:WORD_1
	v_cvt_f32_f16_sdwa v157, v81 dst_sel:DWORD dst_unused:UNUSED_PAD src0_sel:WORD_1
	v_add_f32_e32 v156, v156, v157
	v_fmac_f32_e32 v61, v39, v156
	v_cvt_f32_f16_e32 v154, v74
	v_cvt_f32_f16_e32 v155, v82
	v_add_f32_e32 v154, v154, v155
	v_fmac_f32_e32 v62, v40, v154
	v_cvt_f32_f16_sdwa v156, v74 dst_sel:DWORD dst_unused:UNUSED_PAD src0_sel:WORD_1
	v_cvt_f32_f16_sdwa v157, v82 dst_sel:DWORD dst_unused:UNUSED_PAD src0_sel:WORD_1
	v_add_f32_e32 v156, v156, v157
	v_fmac_f32_e32 v63, v41, v156
	v_cvt_f32_f16_e32 v154, v75
	v_cvt_f32_f16_e32 v155, v83
	v_add_f32_e32 v154, v154, v155
	v_fmac_f32_e32 v64, v42, v154
	v_cvt_f32_f16_sdwa v156, v75 dst_sel:DWORD dst_unused:UNUSED_PAD src0_sel:WORD_1
	v_cvt_f32_f16_sdwa v157, v83 dst_sel:DWORD dst_unused:UNUSED_PAD src0_sel:WORD_1
	v_add_f32_e32 v156, v156, v157
	v_fmac_f32_e32 v65, v43, v156
	v_cvt_f32_f16_e32 v154, v76
	v_cvt_f32_f16_e32 v155, v84
	v_add_f32_e32 v154, v154, v155
	v_fmac_f32_e32 v66, v44, v154
	v_cvt_f32_f16_sdwa v156, v76 dst_sel:DWORD dst_unused:UNUSED_PAD src0_sel:WORD_1
	v_cvt_f32_f16_sdwa v157, v84 dst_sel:DWORD dst_unused:UNUSED_PAD src0_sel:WORD_1
	v_add_f32_e32 v156, v156, v157
	v_fmac_f32_e32 v67, v45, v156
	v_cvt_f32_f16_e32 v154, v77
	v_cvt_f32_f16_e32 v155, v85
	v_add_f32_e32 v154, v154, v155
	v_fmac_f32_e32 v68, v46, v154
	v_cvt_f32_f16_sdwa v156, v77 dst_sel:DWORD dst_unused:UNUSED_PAD src0_sel:WORD_1
	v_cvt_f32_f16_sdwa v157, v85 dst_sel:DWORD dst_unused:UNUSED_PAD src0_sel:WORD_1
	v_add_f32_e32 v156, v156, v157
	v_fmac_f32_e32 v69, v47, v156
	global_store_dwordx4 v150, v[54:57], s[34:35] offset:0
	global_store_dwordx4 v150, v[58:61], s[34:35] offset:1024
	global_store_dwordx4 v150, v[62:65], s[34:35] offset:2048
	global_store_dwordx4 v150, v[66:69], s[34:35] offset:3072
	v_mul_f32_e32 v152, v54, v54
	v_mul_f32_e32 v153, v55, v55
	v_fmac_f32_e32 v152, v56, v56
	v_fmac_f32_e32 v153, v57, v57
	v_fmac_f32_e32 v152, v58, v58
	v_fmac_f32_e32 v153, v59, v59
	v_fmac_f32_e32 v152, v60, v60
	v_fmac_f32_e32 v153, v61, v61
	v_fmac_f32_e32 v152, v62, v62
	v_fmac_f32_e32 v153, v63, v63
	v_fmac_f32_e32 v152, v64, v64
	v_fmac_f32_e32 v153, v65, v65
	v_fmac_f32_e32 v152, v66, v66
	v_fmac_f32_e32 v153, v67, v67
	v_fmac_f32_e32 v152, v68, v68
	v_fmac_f32_e32 v153, v69, v69
	v_add_f32_e32 v152, v152, v153
	v_xor_b32_e32 v158, 128, v159
	ds_bpermute_b32 v153, v158, v152
	s_waitcnt lgkmcnt(0)
; DI void row1_phase(const Params& P, int combine_l, int norm_l, int r_begin) {
;     ...
;       float ss = 0.f;
; #pragma unroll
;       for (int i = 0; i < 4; i++) ss += xv[i].x * xv[i].x + xv[i].y * xv[i].y + xv[i].z * xv[i].z + xv[i].w * xv[i].w;
;       ss = wave_sum(ss);
;       const float rstd = rsqrtf(ss * (1.f / 1024.f) + EPS);
;       const float* g = P.norm1_g + norm_l * 1024;
;       const float* sh = P.mod + (size_t)(norm_l * 9 + n) * 6144; const float* sc = sh + 1024;
; #pragma unroll
;       for (int i = 0; i < 4; i++) {
;         int c = i * 256 + lane * 4;
;         float4 gg = *(const float4*)(g + c), s1 = *(const float4*)(sc + c), s0 = *(const float4*)(sh + c);
;         h4 o;
;         o[0] = (half_t)(xv[i].x * rstd * gg.x * (1.f + s1.x) + s0.x); o[1] = (half_t)(xv[i].y * rstd * gg.y * (1.f + s1.y) + s0.y);
;         o[2] = (half_t)(xv[i].z * rstd * gg.z * (1.f + s1.z) + s0.z); o[3] = (half_t)(xv[i].w * rstd * gg.w * (1.f + s1.w) + s0.w);
;         *(h4*)(P.hx + (size_t)r * D + c) = o;
;       }
;     }
	v_add_f32_e32 v152, v152, v153
	v_xor_b32_e32 v158, 64, v159
	ds_bpermute_b32 v153, v158, v152
	s_waitcnt lgkmcnt(0)
	v_add_f32_e32 v152, v152, v153
	v_xor_b32_e32 v158, 32, v159
	ds_bpermute_b32 v153, v158, v152
	s_waitcnt lgkmcnt(0)
	v_add_f32_e32 v152, v152, v153
	v_xor_b32_e32 v158, 16, v159
	ds_bpermute_b32 v153, v158, v152
	s_waitcnt lgkmcnt(0)
	v_add_f32_e32 v152, v152, v153
	v_xor_b32_e32 v158, 8, v159
	ds_bpermute_b32 v153, v158, v152
	s_waitcnt lgkmcnt(0)
	v_add_f32_e32 v152, v152, v153
	v_xor_b32_e32 v158, 4, v159
	ds_bpermute_b32 v153, v158, v152
	s_waitcnt lgkmcnt(0)
	v_add_f32_e32 v152, v152, v153
	v_mov_b32_e32 v153, 0x358637bd
	v_fmamk_f32 v152, v152, 0x3a800000, v153
	v_rsq_f32_e32 v152, v152
	s_nop 1
	v_mul_f32_e32 v54, v54, v152
	v_mul_f32_e32 v55, v55, v152
	v_mul_f32_e32 v56, v56, v152
	v_mul_f32_e32 v57, v57, v152
	v_mul_f32_e32 v58, v58, v152
	v_mul_f32_e32 v59, v59, v152
	v_mul_f32_e32 v60, v60, v152
	v_mul_f32_e32 v61, v61, v152
	v_mul_f32_e32 v62, v62, v152
	v_mul_f32_e32 v63, v63, v152
	v_mul_f32_e32 v64, v64, v152
	v_mul_f32_e32 v65, v65, v152
	v_mul_f32_e32 v66, v66, v152
	v_mul_f32_e32 v67, v67, v152
	v_mul_f32_e32 v68, v68, v152
	v_mul_f32_e32 v69, v69, v152
	v_fma_f32 v54, v54, v0, v16
	v_fma_f32 v55, v55, v1, v17
	v_fma_f32 v56, v56, v2, v18
	v_fma_f32 v57, v57, v3, v19
	v_fma_f32 v58, v58, v4, v20
	v_fma_f32 v59, v59, v5, v21
	v_fma_f32 v60, v60, v6, v22
	v_fma_f32 v61, v61, v7, v23
	v_fma_f32 v62, v62, v8, v24
	v_fma_f32 v63, v63, v9, v25
	v_fma_f32 v64, v64, v10, v26
	v_fma_f32 v65, v65, v11, v27
	v_fma_f32 v66, v66, v12, v28
	v_fma_f32 v67, v67, v13, v29
	v_fma_f32 v68, v68, v14, v30
	v_fma_f32 v69, v69, v15, v31
	v_cvt_pk_f16_f32 v70, v54, v55
	v_cvt_pk_f16_f32 v71, v56, v57
	v_cvt_pk_f16_f32 v72, v58, v59
	v_cvt_pk_f16_f32 v73, v60, v61
	v_cvt_pk_f16_f32 v74, v62, v63
	v_cvt_pk_f16_f32 v75, v64, v65
	v_cvt_pk_f16_f32 v76, v66, v67
	v_cvt_pk_f16_f32 v77, v68, v69
	global_store_dwordx2 v151, v[70:71], s[36:37] offset:0
	global_store_dwordx2 v151, v[72:73], s[36:37] offset:512
	global_store_dwordx2 v151, v[74:75], s[36:37] offset:1024
	global_store_dwordx2 v151, v[76:77], s[36:37] offset:1536
	s_add_u32 s5, s5, 1
	s_sub_u32 s9, s5, 0x800
	s_lshr_b32 s9, s9, 13
	s_cmp_lt_u32 s5, 0x800
	s_cselect_b32 s9, 8, s9
	s_cmp_eq_u32 s9, s8
	s_cbranch_scc1 .Lr1b_nr4
	s_mov_b32 s8, s9
	s_waitcnt vmcnt(0)
	s_add_u32 s10, s9, 9
	s_mul_i32 s10, s10, 0x6000
	s_add_u32 s38, s56, s10
	s_addc_u32 s39, s57, 0
	global_load_dwordx4 v[54:57], v150, s[58:59] offset:0
	global_load_dwordx4 v[58:61], v150, s[58:59] offset:1024
	global_load_dwordx4 v[62:65], v150, s[58:59] offset:2048
	global_load_dwordx4 v[66:69], v150, s[58:59] offset:3072
	s_add_u32 s44, s38, 0x1000
	s_addc_u32 s45, s39, 0
	global_load_dwordx4 v[70:73], v150, s[44:45] offset:0
	global_load_dwordx4 v[74:77], v150, s[44:45] offset:1024
	global_load_dwordx4 v[78:81], v150, s[44:45] offset:2048
	global_load_dwordx4 v[82:85], v150, s[44:45] offset:3072
	global_load_dwordx4 v[16:19], v150, s[38:39] offset:0
	global_load_dwordx4 v[20:23], v150, s[38:39] offset:1024
	global_load_dwordx4 v[24:27], v150, s[38:39] offset:2048
	global_load_dwordx4 v[28:31], v150, s[38:39] offset:3072
	s_add_u32 s10, s9, 0
	s_mul_i32 s10, s10, 0x6000
	s_add_u32 s10, s10, 0x5000
	s_add_u32 s38, s56, s10
	s_addc_u32 s39, s57, 0
	global_load_dwordx4 v[32:35], v150, s[38:39] offset:0
	global_load_dwordx4 v[36:39], v150, s[38:39] offset:1024
	global_load_dwordx4 v[40:43], v150, s[38:39] offset:2048
	global_load_dwordx4 v[44:47], v150, s[38:39] offset:3072
	s_waitcnt vmcnt(0)
	v_add_f32_e32 v70, 1.0, v70
	v_add_f32_e32 v71, 1.0, v71
	v_add_f32_e32 v72, 1.0, v72
	v_add_f32_e32 v73, 1.0, v73
	v_add_f32_e32 v74, 1.0, v74
	v_add_f32_e32 v75, 1.0, v75
	v_add_f32_e32 v76, 1.0, v76
	v_add_f32_e32 v77, 1.0, v77
	v_add_f32_e32 v78, 1.0, v78
	v_add_f32_e32 v79, 1.0, v79
	v_add_f32_e32 v80, 1.0, v80
	v_add_f32_e32 v81, 1.0, v81
	v_add_f32_e32 v82, 1.0, v82
	v_add_f32_e32 v83, 1.0, v83
	v_add_f32_e32 v84, 1.0, v84
	v_add_f32_e32 v85, 1.0, v85
	v_mul_f32_e32 v0, v54, v70
	v_mul_f32_e32 v1, v55, v71
	v_mul_f32_e32 v2, v56, v72
	v_mul_f32_e32 v3, v57, v73
	v_mul_f32_e32 v4, v58, v74
	v_mul_f32_e32 v5, v59, v75
	v_mul_f32_e32 v6, v60, v76
	v_mul_f32_e32 v7, v61, v77
	v_mul_f32_e32 v8, v62, v78
	v_mul_f32_e32 v9, v63, v79
	v_mul_f32_e32 v10, v64, v80
	v_mul_f32_e32 v11, v65, v81
	v_mul_f32_e32 v12, v66, v82
	v_mul_f32_e32 v13, v67, v83
	v_mul_f32_e32 v14, v68, v84
	v_mul_f32_e32 v15, v69, v85
; DI void row1_phase(const Params& P, int combine_l, int norm_l, int r_begin) {
;     ...
;       for (int i = 0; i < 4; i++) { int c = i * 256 + lane * 4; xv[i] = *(const float4*)(xm + c); ya[i] = *(const h4*)(y0 + c); yb[i] = *(const h4*)(y1 + c); }
;     }
;   };
;   auto process = [&](int r, float4 (&xv)[4], h4 (&ya)[4], h4 (&yb)[4]) {
;     const int n = row_mod(r);
;     if (combine_l >= 0) {
;       float* xm = r < TC ? P.xcbuf + (size_t)r * D : P.out + (size_t)(r - TC) * D;
;       const float* g2 = P.mod + (size_t)(combine_l * 9 + n) * 6144 + 5 * 1024;
; #pragma unroll
;       for (int i = 0; i < 4; i++) {
;         int c = i * 256 + lane * 4;
;         float4 g = *(const float4*)(g2 + c); float4 t = xv[i];
;         t.x += g.x * ((float)ya[i][0] + (float)yb[i][0]); t.y += g.y * ((float)ya[i][1] + (float)yb[i][1]);
;         t.z += g.z * ((float)ya[i][2] + (float)yb[i][2]); t.w += g.w * ((float)ya[i][3] + (float)yb[i][3]);
;         *(float4*)(xm + c) = t; xv[i] = t;
;       }
;     }
;     if (norm_l >= 0) {
;       float ss = 0.f;
; #pragma unroll
;       for (int i = 0; i < 4; i++) ss += xv[i].x * xv[i].x + xv[i].y * xv[i].y + xv[i].z * xv[i].z + xv[i].w * xv[i].w;
;       ss = wave_sum(ss);
.Lr1b_nr4:
	s_waitcnt vmcnt(44)
	v_accvgpr_read_b32 v54, a96
	v_accvgpr_read_b32 v55, a97
	v_accvgpr_read_b32 v56, a98
	v_accvgpr_read_b32 v57, a99
	v_accvgpr_read_b32 v58, a100
	v_accvgpr_read_b32 v59, a101
	v_accvgpr_read_b32 v60, a102
	v_accvgpr_read_b32 v61, a103
	v_accvgpr_read_b32 v62, a104
	v_accvgpr_read_b32 v63, a105
	v_accvgpr_read_b32 v64, a106
	v_accvgpr_read_b32 v65, a107
	v_accvgpr_read_b32 v66, a108
	v_accvgpr_read_b32 v67, a109
	v_accvgpr_read_b32 v68, a110
	v_accvgpr_read_b32 v69, a111
	v_accvgpr_read_b32 v70, a112
	v_accvgpr_read_b32 v71, a113
	v_accvgpr_read_b32 v72, a114
	v_accvgpr_read_b32 v73, a115
	v_accvgpr_read_b32 v74, a116
	v_accvgpr_read_b32 v75, a117
	v_accvgpr_read_b32 v76, a118
	v_accvgpr_read_b32 v77, a119
	v_accvgpr_read_b32 v78, a120
	v_accvgpr_read_b32 v79, a121
	v_accvgpr_read_b32 v80, a122
	v_accvgpr_read_b32 v81, a123
	v_accvgpr_read_b32 v82, a124
	v_accvgpr_read_b32 v83, a125
	v_accvgpr_read_b32 v84, a126
	v_accvgpr_read_b32 v85, a127
	s_lshl_b32 s10, s5, 12
	s_cmp_lt_u32 s5, 0x800
	s_cselect_b64 s[34:35], s[48:49], s[50:51]
	s_add_u32 s34, s34, s10
	s_addc_u32 s35, s35, 0
	s_lshr_b32 s10, s10, 1
	s_add_u32 s36, s54, s10
	s_addc_u32 s37, s55, 0
	s_cmp_lt_u32 s7, 0x800
	s_cselect_b64 s[60:61], s[48:49], s[50:51]
	s_lshl_b32 s10, s7, 12
	s_add_u32 s60, s60, s10
	s_addc_u32 s61, s61, 0
	global_load_dwordx4 a[96:99], v150, s[60:61] offset:0
	global_load_dwordx4 a[100:103], v150, s[60:61] offset:1024
	global_load_dwordx4 a[104:107], v150, s[60:61] offset:2048
	global_load_dwordx4 a[108:111], v150, s[60:61] offset:3072
	s_add_u32 s62, s52, s10
	s_addc_u32 s63, s53, 0
	global_load_dwordx2 a[112:113], v151, s[62:63] offset:0
	global_load_dwordx2 a[114:115], v151, s[62:63] offset:512
	global_load_dwordx2 a[116:117], v151, s[62:63] offset:1024
	global_load_dwordx2 a[118:119], v151, s[62:63] offset:1536
	global_load_dwordx2 a[120:121], v151, s[62:63] offset:2048
	global_load_dwordx2 a[122:123], v151, s[62:63] offset:2560
	global_load_dwordx2 a[124:125], v151, s[62:63] offset:3072
	global_load_dwordx2 a[126:127], v151, s[62:63] offset:3584
	s_add_u32 s7, s7, 1
	v_cvt_f32_f16_e32 v154, v70
	v_cvt_f32_f16_e32 v155, v78
	v_add_f32_e32 v154, v154, v155
	v_fmac_f32_e32 v54, v32, v154
	v_cvt_f32_f16_sdwa v156, v70 dst_sel:DWORD dst_unused:UNUSED_PAD src0_sel:WORD_1
	v_cvt_f32_f16_sdwa v157, v78 dst_sel:DWORD dst_unused:UNUSED_PAD src0_sel:WORD_1
	v_add_f32_e32 v156, v156, v157
	v_fmac_f32_e32 v55, v33, v156
	v_cvt_f32_f16_e32 v154, v71
	v_cvt_f32_f16_e32 v155, v79
	v_add_f32_e32 v154, v154, v155
	v_fmac_f32_e32 v56, v34, v154
	v_cvt_f32_f16_sdwa v156, v71 dst_sel:DWORD dst_unused:UNUSED_PAD src0_sel:WORD_1
	v_cvt_f32_f16_sdwa v157, v79 dst_sel:DWORD dst_unused:UNUSED_PAD src0_sel:WORD_1
	v_add_f32_e32 v156, v156, v157
	v_fmac_f32_e32 v57, v35, v156
	v_cvt_f32_f16_e32 v154, v72
	v_cvt_f32_f16_e32 v155, v80
	v_add_f32_e32 v154, v154, v155
	v_fmac_f32_e32 v58, v36, v154
	v_cvt_f32_f16_sdwa v156, v72 dst_sel:DWORD dst_unused:UNUSED_PAD src0_sel:WORD_1
	v_cvt_f32_f16_sdwa v157, v80 dst_sel:DWORD dst_unused:UNUSED_PAD src0_sel:WORD_1
	v_add_f32_e32 v156, v156, v157
	v_fmac_f32_e32 v59, v37, v156
	v_cvt_f32_f16_e32 v154, v73
	v_cvt_f32_f16_e32 v155, v81
	v_add_f32_e32 v154, v154, v155
	v_fmac_f32_e32 v60, v38, v154
	v_cvt_f32_f16_sdwa v156, v73 dst_sel:DWORD dst_unused:UNUSED_PAD src0_sel:WORD_1
	v_cvt_f32_f16_sdwa v157, v81 dst_sel:DWORD dst_unused:UNUSED_PAD src0_sel:WORD_1
	v_add_f32_e32 v156, v156, v157
	v_fmac_f32_e32 v61, v39, v156
	v_cvt_f32_f16_e32 v154, v74
	v_cvt_f32_f16_e32 v155, v82
	v_add_f32_e32 v154, v154, v155
	v_fmac_f32_e32 v62, v40, v154
	v_cvt_f32_f16_sdwa v156, v74 dst_sel:DWORD dst_unused:UNUSED_PAD src0_sel:WORD_1
	v_cvt_f32_f16_sdwa v157, v82 dst_sel:DWORD dst_unused:UNUSED_PAD src0_sel:WORD_1
	v_add_f32_e32 v156, v156, v157
	v_fmac_f32_e32 v63, v41, v156
	v_cvt_f32_f16_e32 v154, v75
	v_cvt_f32_f16_e32 v155, v83
	v_add_f32_e32 v154, v154, v155
	v_fmac_f32_e32 v64, v42, v154
	v_cvt_f32_f16_sdwa v156, v75 dst_sel:DWORD dst_unused:UNUSED_PAD src0_sel:WORD_1
	v_cvt_f32_f16_sdwa v157, v83 dst_sel:DWORD dst_unused:UNUSED_PAD src0_sel:WORD_1
	v_add_f32_e32 v156, v156, v157
	v_fmac_f32_e32 v65, v43, v156
	v_cvt_f32_f16_e32 v154, v76
	v_cvt_f32_f16_e32 v155, v84
	v_add_f32_e32 v154, v154, v155
	v_fmac_f32_e32 v66, v44, v154
	v_cvt_f32_f16_sdwa v156, v76 dst_sel:DWORD dst_unused:UNUSED_PAD src0_sel:WORD_1
	v_cvt_f32_f16_sdwa v157, v84 dst_sel:DWORD dst_unused:UNUSED_PAD src0_sel:WORD_1
	v_add_f32_e32 v156, v156, v157
	v_fmac_f32_e32 v67, v45, v156
	v_cvt_f32_f16_e32 v154, v77
	v_cvt_f32_f16_e32 v155, v85
	v_add_f32_e32 v154, v154, v155
	v_fmac_f32_e32 v68, v46, v154
	v_cvt_f32_f16_sdwa v156, v77 dst_sel:DWORD dst_unused:UNUSED_PAD src0_sel:WORD_1
	v_cvt_f32_f16_sdwa v157, v85 dst_sel:DWORD dst_unused:UNUSED_PAD src0_sel:WORD_1
	v_add_f32_e32 v156, v156, v157
	v_fmac_f32_e32 v69, v47, v156
	global_store_dwordx4 v150, v[54:57], s[34:35] offset:0
	global_store_dwordx4 v150, v[58:61], s[34:35] offset:1024
	global_store_dwordx4 v150, v[62:65], s[34:35] offset:2048
	global_store_dwordx4 v150, v[66:69], s[34:35] offset:3072
	v_mul_f32_e32 v152, v54, v54
	v_mul_f32_e32 v153, v55, v55
	v_fmac_f32_e32 v152, v56, v56
	v_fmac_f32_e32 v153, v57, v57
	v_fmac_f32_e32 v152, v58, v58
	v_fmac_f32_e32 v153, v59, v59
	v_fmac_f32_e32 v152, v60, v60
	v_fmac_f32_e32 v153, v61, v61
	v_fmac_f32_e32 v152, v62, v62
	v_fmac_f32_e32 v153, v63, v63
	v_fmac_f32_e32 v152, v64, v64
	v_fmac_f32_e32 v153, v65, v65
	v_fmac_f32_e32 v152, v66, v66
	v_fmac_f32_e32 v153, v67, v67
	v_fmac_f32_e32 v152, v68, v68
	v_fmac_f32_e32 v153, v69, v69
	v_add_f32_e32 v152, v152, v153
	v_xor_b32_e32 v158, 128, v159
	ds_bpermute_b32 v153, v158, v152
	s_waitcnt lgkmcnt(0)
; DI void row1_phase(const Params& P, int combine_l, int norm_l, int r_begin) {
;     ...
;       float ss = 0.f;
; #pragma unroll
;       for (int i = 0; i < 4; i++) ss += xv[i].x * xv[i].x + xv[i].y * xv[i].y + xv[i].z * xv[i].z + xv[i].w * xv[i].w;
;       ss = wave_sum(ss);
;       const float rstd = rsqrtf(ss * (1.f / 1024.f) + EPS);
;       const float* g = P.norm1_g + norm_l * 1024;
;       const float* sh = P.mod + (size_t)(norm_l * 9 + n) * 6144; const float* sc = sh + 1024;
; #pragma unroll
;       for (int i = 0; i < 4; i++) {
;         int c = i * 256 + lane * 4;
;         float4 gg = *(const float4*)(g + c), s1 = *(const float4*)(sc + c), s0 = *(const float4*)(sh + c);
;         h4 o;
;         o[0] = (half_t)(xv[i].x * rstd * gg.x * (1.f + s1.x) + s0.x); o[1] = (half_t)(xv[i].y * rstd * gg.y * (1.f + s1.y) + s0.y);
;         o[2] = (half_t)(xv[i].z * rstd * gg.z * (1.f + s1.z) + s0.z); o[3] = (half_t)(xv[i].w * rstd * gg.w * (1.f + s1.w) + s0.w);
;         *(h4*)(P.hx + (size_t)r * D + c) = o;
;       }
;     }
;   };
;   const int nrows = TA - r_begin;
;   const int r_lo = r_begin + (int)(((long long)gw * nrows) / nw), r_hi = r_begin + (int)(((long long)(gw + 1) * nrows) / nw);
; #pragma unroll 1
;   for (int r = r_lo; r < r_hi; r += 4) {
;     float4 x0[4], x1[4], x2[4], x3[4]; h4 a0[4], b0[4], a1[4], b1[4], a2[4], b2[4], a3[4], b3[4];
;     const int r1 = r + 1, r2 = r + 2, r3 = r + 3;
;     load_row(r, x0, a0, b0);
;     if (r1 < r_hi) load_row(r1, x1, a1, b1);
;     if (r2 < r_hi) load_row(r2, x2, a2, b2);
;     if (r3 < r_hi) load_row(r3, x3, a3, b3);
;     process(r, x0, a0, b0);
;     if (r1 < r_hi) process(r1, x1, a1, b1);
;     if (r2 < r_hi) process(r2, x2, a2, b2);
;     if (r3 < r_hi) process(r3, x3, a3, b3);
;   }
	v_add_f32_e32 v152, v152, v153
	v_xor_b32_e32 v158, 64, v159
	ds_bpermute_b32 v153, v158, v152
	s_waitcnt lgkmcnt(0)
	v_add_f32_e32 v152, v152, v153
	v_xor_b32_e32 v158, 32, v159
	ds_bpermute_b32 v153, v158, v152
	s_waitcnt lgkmcnt(0)
	v_add_f32_e32 v152, v152, v153
	v_xor_b32_e32 v158, 16, v159
	ds_bpermute_b32 v153, v158, v152
	s_waitcnt lgkmcnt(0)
	v_add_f32_e32 v152, v152, v153
	v_xor_b32_e32 v158, 8, v159
	ds_bpermute_b32 v153, v158, v152
	s_waitcnt lgkmcnt(0)
	v_add_f32_e32 v152, v152, v153
	v_xor_b32_e32 v158, 4, v159
	ds_bpermute_b32 v153, v158, v152
	s_waitcnt lgkmcnt(0)
	v_add_f32_e32 v152, v152, v153
	v_mov_b32_e32 v153, 0x358637bd
	v_fmamk_f32 v152, v152, 0x3a800000, v153
	v_rsq_f32_e32 v152, v152
	s_nop 1
	v_mul_f32_e32 v54, v54, v152
	v_mul_f32_e32 v55, v55, v152
	v_mul_f32_e32 v56, v56, v152
	v_mul_f32_e32 v57, v57, v152
	v_mul_f32_e32 v58, v58, v152
	v_mul_f32_e32 v59, v59, v152
	v_mul_f32_e32 v60, v60, v152
	v_mul_f32_e32 v61, v61, v152
	v_mul_f32_e32 v62, v62, v152
	v_mul_f32_e32 v63, v63, v152
	v_mul_f32_e32 v64, v64, v152
	v_mul_f32_e32 v65, v65, v152
	v_mul_f32_e32 v66, v66, v152
	v_mul_f32_e32 v67, v67, v152
	v_mul_f32_e32 v68, v68, v152
	v_mul_f32_e32 v69, v69, v152
	v_fma_f32 v54, v54, v0, v16
	v_fma_f32 v55, v55, v1, v17
	v_fma_f32 v56, v56, v2, v18
	v_fma_f32 v57, v57, v3, v19
	v_fma_f32 v58, v58, v4, v20
	v_fma_f32 v59, v59, v5, v21
	v_fma_f32 v60, v60, v6, v22
	v_fma_f32 v61, v61, v7, v23
	v_fma_f32 v62, v62, v8, v24
	v_fma_f32 v63, v63, v9, v25
	v_fma_f32 v64, v64, v10, v26
	v_fma_f32 v65, v65, v11, v27
	v_fma_f32 v66, v66, v12, v28
	v_fma_f32 v67, v67, v13, v29
	v_fma_f32 v68, v68, v14, v30
	v_fma_f32 v69, v69, v15, v31
	v_cvt_pk_f16_f32 v70, v54, v55
	v_cvt_pk_f16_f32 v71, v56, v57
	v_cvt_pk_f16_f32 v72, v58, v59
	v_cvt_pk_f16_f32 v73, v60, v61
	v_cvt_pk_f16_f32 v74, v62, v63
	v_cvt_pk_f16_f32 v75, v64, v65
	v_cvt_pk_f16_f32 v76, v66, v67
	v_cvt_pk_f16_f32 v77, v68, v69
	global_store_dwordx2 v151, v[70:71], s[36:37] offset:0
	global_store_dwordx2 v151, v[72:73], s[36:37] offset:512
	global_store_dwordx2 v151, v[74:75], s[36:37] offset:1024
	global_store_dwordx2 v151, v[76:77], s[36:37] offset:1536
	s_add_u32 s5, s5, 1
	s_sub_u32 s98, s98, 1
	s_cmp_lg_u32 s98, 0
	s_cbranch_scc1 .Lr1b_loop
	s_sub_u32 s9, s5, 0x800
	s_lshr_b32 s9, s9, 13
	s_cmp_lt_u32 s5, 0x800
	s_cselect_b32 s9, 8, s9
	s_cmp_eq_u32 s9, s8
	s_cbranch_scc1 .Lr1b_nr5
	s_mov_b32 s8, s9
	s_waitcnt vmcnt(0)
	s_add_u32 s10, s9, 9
	s_mul_i32 s10, s10, 0x6000
	s_add_u32 s38, s56, s10
	s_addc_u32 s39, s57, 0
	global_load_dwordx4 v[54:57], v150, s[58:59] offset:0
	global_load_dwordx4 v[58:61], v150, s[58:59] offset:1024
	global_load_dwordx4 v[62:65], v150, s[58:59] offset:2048
	global_load_dwordx4 v[66:69], v150, s[58:59] offset:3072
	s_add_u32 s44, s38, 0x1000
	s_addc_u32 s45, s39, 0
	global_load_dwordx4 v[70:73], v150, s[44:45] offset:0
	global_load_dwordx4 v[74:77], v150, s[44:45] offset:1024
	global_load_dwordx4 v[78:81], v150, s[44:45] offset:2048
	global_load_dwordx4 v[82:85], v150, s[44:45] offset:3072
	global_load_dwordx4 v[16:19], v150, s[38:39] offset:0
	global_load_dwordx4 v[20:23], v150, s[38:39] offset:1024
	global_load_dwordx4 v[24:27], v150, s[38:39] offset:2048
	global_load_dwordx4 v[28:31], v150, s[38:39] offset:3072
	s_add_u32 s10, s9, 0
	s_mul_i32 s10, s10, 0x6000
	s_add_u32 s10, s10, 0x5000
	s_add_u32 s38, s56, s10
	s_addc_u32 s39, s57, 0
	global_load_dwordx4 v[32:35], v150, s[38:39] offset:0
	global_load_dwordx4 v[36:39], v150, s[38:39] offset:1024
	global_load_dwordx4 v[40:43], v150, s[38:39] offset:2048
	global_load_dwordx4 v[44:47], v150, s[38:39] offset:3072
	s_waitcnt vmcnt(0)
	v_add_f32_e32 v70, 1.0, v70
	v_add_f32_e32 v71, 1.0, v71
	v_add_f32_e32 v72, 1.0, v72
	v_add_f32_e32 v73, 1.0, v73
	v_add_f32_e32 v74, 1.0, v74
	v_add_f32_e32 v75, 1.0, v75
	v_add_f32_e32 v76, 1.0, v76
	v_add_f32_e32 v77, 1.0, v77
	v_add_f32_e32 v78, 1.0, v78
	v_add_f32_e32 v79, 1.0, v79
	v_add_f32_e32 v80, 1.0, v80
	v_add_f32_e32 v81, 1.0, v81
	v_add_f32_e32 v82, 1.0, v82
	v_add_f32_e32 v83, 1.0, v83
	v_add_f32_e32 v84, 1.0, v84
	v_add_f32_e32 v85, 1.0, v85
	v_mul_f32_e32 v0, v54, v70
	v_mul_f32_e32 v1, v55, v71
	v_mul_f32_e32 v2, v56, v72
	v_mul_f32_e32 v3, v57, v73
	v_mul_f32_e32 v4, v58, v74
	v_mul_f32_e32 v5, v59, v75
	v_mul_f32_e32 v6, v60, v76
	v_mul_f32_e32 v7, v61, v77
	v_mul_f32_e32 v8, v62, v78
	v_mul_f32_e32 v9, v63, v79
	v_mul_f32_e32 v10, v64, v80
	v_mul_f32_e32 v11, v65, v81
	v_mul_f32_e32 v12, v66, v82
	v_mul_f32_e32 v13, v67, v83
	v_mul_f32_e32 v14, v68, v84
	v_mul_f32_e32 v15, v69, v85

; DI void row1_phase(const Params& P, int combine_l, int norm_l, int r_begin) {
;     ...
;     const int n = row_mod(r);
;     if (combine_l >= 0) {
;       float* xm = r < TC ? P.xcbuf + (size_t)r * D : P.out + (size_t)(r - TC) * D;
;       const float* g2 = P.mod + (size_t)(combine_l * 9 + n) * 6144 + 5 * 1024;
; #pragma unroll
;       for (int i = 0; i < 4; i++) {
;         int c = i * 256 + lane * 4;
;         float4 g = *(const float4*)(g2 + c); float4 t = xv[i];
;         t.x += g.x * ((float)ya[i][0] + (float)yb[i][0]); t.y += g.y * ((float)ya[i][1] + (float)yb[i][1]);
;         t.z += g.z * ((float)ya[i][2] + (float)yb[i][2]); t.w += g.w * ((float)ya[i][3] + (float)yb[i][3]);
;         *(float4*)(xm + c) = t; xv[i] = t;
;       }
;     }
;     if (norm_l >= 0) {
;       float ss = 0.f;
; #pragma unroll
;       for (int i = 0; i < 4; i++) ss += xv[i].x * xv[i].x + xv[i].y * xv[i].y + xv[i].z * xv[i].z + xv[i].w * xv[i].w;
;       ss = wave_sum(ss);
.Lr1b_nr7:
	s_waitcnt vmcnt(44)
	v_accvgpr_read_b32 v54, a64
	v_accvgpr_read_b32 v55, a65
	v_accvgpr_read_b32 v56, a66
	v_accvgpr_read_b32 v57, a67
	v_accvgpr_read_b32 v58, a68
	v_accvgpr_read_b32 v59, a69
	v_accvgpr_read_b32 v60, a70
	v_accvgpr_read_b32 v61, a71
	v_accvgpr_read_b32 v62, a72
	v_accvgpr_read_b32 v63, a73
	v_accvgpr_read_b32 v64, a74
	v_accvgpr_read_b32 v65, a75
	v_accvgpr_read_b32 v66, a76
	v_accvgpr_read_b32 v67, a77
	v_accvgpr_read_b32 v68, a78
	v_accvgpr_read_b32 v69, a79
	v_accvgpr_read_b32 v70, a80
	v_accvgpr_read_b32 v71, a81
	v_accvgpr_read_b32 v72, a82
	v_accvgpr_read_b32 v73, a83
	v_accvgpr_read_b32 v74, a84
	v_accvgpr_read_b32 v75, a85
	v_accvgpr_read_b32 v76, a86
	v_accvgpr_read_b32 v77, a87
	v_accvgpr_read_b32 v78, a88
	v_accvgpr_read_b32 v79, a89
	v_accvgpr_read_b32 v80, a90
	v_accvgpr_read_b32 v81, a91
	v_accvgpr_read_b32 v82, a92
	v_accvgpr_read_b32 v83, a93
	v_accvgpr_read_b32 v84, a94
	v_accvgpr_read_b32 v85, a95
	s_lshl_b32 s10, s5, 12
	s_cmp_lt_u32 s5, 0x800
	s_cselect_b64 s[34:35], s[48:49], s[50:51]
	s_add_u32 s34, s34, s10
	s_addc_u32 s35, s35, 0
	s_lshr_b32 s10, s10, 1
	s_add_u32 s36, s54, s10
	s_addc_u32 s37, s55, 0
	v_cvt_f32_f16_e32 v154, v70
	v_cvt_f32_f16_e32 v155, v78
	v_add_f32_e32 v154, v154, v155
	v_fmac_f32_e32 v54, v32, v154
	v_cvt_f32_f16_sdwa v156, v70 dst_sel:DWORD dst_unused:UNUSED_PAD src0_sel:WORD_1
	v_cvt_f32_f16_sdwa v157, v78 dst_sel:DWORD dst_unused:UNUSED_PAD src0_sel:WORD_1
	v_add_f32_e32 v156, v156, v157
	v_fmac_f32_e32 v55, v33, v156
	v_cvt_f32_f16_e32 v154, v71
	v_cvt_f32_f16_e32 v155, v79
	v_add_f32_e32 v154, v154, v155
	v_fmac_f32_e32 v56, v34, v154
	v_cvt_f32_f16_sdwa v156, v71 dst_sel:DWORD dst_unused:UNUSED_PAD src0_sel:WORD_1
	v_cvt_f32_f16_sdwa v157, v79 dst_sel:DWORD dst_unused:UNUSED_PAD src0_sel:WORD_1
	v_add_f32_e32 v156, v156, v157
	v_fmac_f32_e32 v57, v35, v156
	v_cvt_f32_f16_e32 v154, v72
	v_cvt_f32_f16_e32 v155, v80
	v_add_f32_e32 v154, v154, v155
	v_fmac_f32_e32 v58, v36, v154
	v_cvt_f32_f16_sdwa v156, v72 dst_sel:DWORD dst_unused:UNUSED_PAD src0_sel:WORD_1
	v_cvt_f32_f16_sdwa v157, v80 dst_sel:DWORD dst_unused:UNUSED_PAD src0_sel:WORD_1
	v_add_f32_e32 v156, v156, v157
	v_fmac_f32_e32 v59, v37, v156
	v_cvt_f32_f16_e32 v154, v73
	v_cvt_f32_f16_e32 v155, v81
	v_add_f32_e32 v154, v154, v155
	v_fmac_f32_e32 v60, v38, v154
	v_cvt_f32_f16_sdwa v156, v73 dst_sel:DWORD dst_unused:UNUSED_PAD src0_sel:WORD_1
	v_cvt_f32_f16_sdwa v157, v81 dst_sel:DWORD dst_unused:UNUSED_PAD src0_sel:WORD_1
	v_add_f32_e32 v156, v156, v157
	v_fmac_f32_e32 v61, v39, v156
	v_cvt_f32_f16_e32 v154, v74
	v_cvt_f32_f16_e32 v155, v82
	v_add_f32_e32 v154, v154, v155
	v_fmac_f32_e32 v62, v40, v154
	v_cvt_f32_f16_sdwa v156, v74 dst_sel:DWORD dst_unused:UNUSED_PAD src0_sel:WORD_1
	v_cvt_f32_f16_sdwa v157, v82 dst_sel:DWORD dst_unused:UNUSED_PAD src0_sel:WORD_1
	v_add_f32_e32 v156, v156, v157
	v_fmac_f32_e32 v63, v41, v156
	v_cvt_f32_f16_e32 v154, v75
	v_cvt_f32_f16_e32 v155, v83
	v_add_f32_e32 v154, v154, v155
	v_fmac_f32_e32 v64, v42, v154
	v_cvt_f32_f16_sdwa v156, v75 dst_sel:DWORD dst_unused:UNUSED_PAD src0_sel:WORD_1
	v_cvt_f32_f16_sdwa v157, v83 dst_sel:DWORD dst_unused:UNUSED_PAD src0_sel:WORD_1
	v_add_f32_e32 v156, v156, v157
	v_fmac_f32_e32 v65, v43, v156
	v_cvt_f32_f16_e32 v154, v76
	v_cvt_f32_f16_e32 v155, v84
	v_add_f32_e32 v154, v154, v155
	v_fmac_f32_e32 v66, v44, v154
	v_cvt_f32_f16_sdwa v156, v76 dst_sel:DWORD dst_unused:UNUSED_PAD src0_sel:WORD_1
	v_cvt_f32_f16_sdwa v157, v84 dst_sel:DWORD dst_unused:UNUSED_PAD src0_sel:WORD_1
	v_add_f32_e32 v156, v156, v157
	v_fmac_f32_e32 v67, v45, v156
	v_cvt_f32_f16_e32 v154, v77
	v_cvt_f32_f16_e32 v155, v85
	v_add_f32_e32 v154, v154, v155
	v_fmac_f32_e32 v68, v46, v154
	v_cvt_f32_f16_sdwa v156, v77 dst_sel:DWORD dst_unused:UNUSED_PAD src0_sel:WORD_1
	v_cvt_f32_f16_sdwa v157, v85 dst_sel:DWORD dst_unused:UNUSED_PAD src0_sel:WORD_1
	v_add_f32_e32 v156, v156, v157
	v_fmac_f32_e32 v69, v47, v156
	global_store_dwordx4 v150, v[54:57], s[34:35] offset:0
	global_store_dwordx4 v150, v[58:61], s[34:35] offset:1024
	global_store_dwordx4 v150, v[62:65], s[34:35] offset:2048
	global_store_dwordx4 v150, v[66:69], s[34:35] offset:3072
	v_mul_f32_e32 v152, v54, v54
	v_mul_f32_e32 v153, v55, v55
	v_fmac_f32_e32 v152, v56, v56
	v_fmac_f32_e32 v153, v57, v57
	v_fmac_f32_e32 v152, v58, v58
	v_fmac_f32_e32 v153, v59, v59
	v_fmac_f32_e32 v152, v60, v60
	v_fmac_f32_e32 v153, v61, v61
	v_fmac_f32_e32 v152, v62, v62
	v_fmac_f32_e32 v153, v63, v63
	v_fmac_f32_e32 v152, v64, v64
	v_fmac_f32_e32 v153, v65, v65
	v_fmac_f32_e32 v152, v66, v66
	v_fmac_f32_e32 v153, v67, v67
	v_fmac_f32_e32 v152, v68, v68
	v_fmac_f32_e32 v153, v69, v69
	v_add_f32_e32 v152, v152, v153
	v_xor_b32_e32 v158, 128, v159
	ds_bpermute_b32 v153, v158, v152
	s_waitcnt lgkmcnt(0)
	v_add_f32_e32 v152, v152, v153
	v_xor_b32_e32 v158, 64, v159
	ds_bpermute_b32 v153, v158, v152
	s_waitcnt lgkmcnt(0)
	v_add_f32_e32 v152, v152, v153
	v_xor_b32_e32 v158, 32, v159
	ds_bpermute_b32 v153, v158, v152
	s_waitcnt lgkmcnt(0)
	v_add_f32_e32 v152, v152, v153
	v_xor_b32_e32 v158, 16, v159
	ds_bpermute_b32 v153, v158, v152
	s_waitcnt lgkmcnt(0)
	v_add_f32_e32 v152, v152, v153
	v_xor_b32_e32 v158, 8, v159
	ds_bpermute_b32 v153, v158, v152
	s_waitcnt lgkmcnt(0)
	v_add_f32_e32 v152, v152, v153
	v_xor_b32_e32 v158, 4, v159
	ds_bpermute_b32 v153, v158, v152
	s_waitcnt lgkmcnt(0)
; DI void row1_phase(const Params& P, int combine_l, int norm_l, int r_begin) {
;     ...
;     const int n = row_mod(r);
;     if (combine_l >= 0) {
;       float* xm = r < TC ? P.xcbuf + (size_t)r * D : P.out + (size_t)(r - TC) * D;
;       const float* g2 = P.mod + (size_t)(combine_l * 9 + n) * 6144 + 5 * 1024;
; #pragma unroll
;       for (int i = 0; i < 4; i++) {
;         int c = i * 256 + lane * 4;
;         float4 g = *(const float4*)(g2 + c); float4 t = xv[i];
;         t.x += g.x * ((float)ya[i][0] + (float)yb[i][0]); t.y += g.y * ((float)ya[i][1] + (float)yb[i][1]);
;     ...
;       ss = wave_sum(ss);
;       const float rstd = rsqrtf(ss * (1.f / 1024.f) + EPS);
;       const float* g = P.norm1_g + norm_l * 1024;
;       const float* sh = P.mod + (size_t)(norm_l * 9 + n) * 6144; const float* sc = sh + 1024;
; #pragma unroll
;       for (int i = 0; i < 4; i++) {
;         int c = i * 256 + lane * 4;
;         float4 gg = *(const float4*)(g + c), s1 = *(const float4*)(sc + c), s0 = *(const float4*)(sh + c);
;         h4 o;
;         o[0] = (half_t)(xv[i].x * rstd * gg.x * (1.f + s1.x) + s0.x); o[1] = (half_t)(xv[i].y * rstd * gg.y * (1.f + s1.y) + s0.y);
;         o[2] = (half_t)(xv[i].z * rstd * gg.z * (1.f + s1.z) + s0.z); o[3] = (half_t)(xv[i].w * rstd * gg.w * (1.f + s1.w) + s0.w);
;         *(h4*)(P.hx + (size_t)r * D + c) = o;
;       }
;     }
	v_add_f32_e32 v152, v152, v153
	v_mov_b32_e32 v153, 0x358637bd
	v_fmamk_f32 v152, v152, 0x3a800000, v153
	v_rsq_f32_e32 v152, v152
	s_nop 1
	v_mul_f32_e32 v54, v54, v152
	v_mul_f32_e32 v55, v55, v152
	v_mul_f32_e32 v56, v56, v152
	v_mul_f32_e32 v57, v57, v152
	v_mul_f32_e32 v58, v58, v152
	v_mul_f32_e32 v59, v59, v152
	v_mul_f32_e32 v60, v60, v152
	v_mul_f32_e32 v61, v61, v152
	v_mul_f32_e32 v62, v62, v152
	v_mul_f32_e32 v63, v63, v152
	v_mul_f32_e32 v64, v64, v152
	v_mul_f32_e32 v65, v65, v152
	v_mul_f32_e32 v66, v66, v152
	v_mul_f32_e32 v67, v67, v152
	v_mul_f32_e32 v68, v68, v152
	v_mul_f32_e32 v69, v69, v152
	v_fma_f32 v54, v54, v0, v16
	v_fma_f32 v55, v55, v1, v17
	v_fma_f32 v56, v56, v2, v18
	v_fma_f32 v57, v57, v3, v19
	v_fma_f32 v58, v58, v4, v20
	v_fma_f32 v59, v59, v5, v21
	v_fma_f32 v60, v60, v6, v22
	v_fma_f32 v61, v61, v7, v23
	v_fma_f32 v62, v62, v8, v24
	v_fma_f32 v63, v63, v9, v25
	v_fma_f32 v64, v64, v10, v26
	v_fma_f32 v65, v65, v11, v27
	v_fma_f32 v66, v66, v12, v28
	v_fma_f32 v67, v67, v13, v29
	v_fma_f32 v68, v68, v14, v30
	v_fma_f32 v69, v69, v15, v31
	v_cvt_pk_f16_f32 v70, v54, v55
	v_cvt_pk_f16_f32 v71, v56, v57
	v_cvt_pk_f16_f32 v72, v58, v59
	v_cvt_pk_f16_f32 v73, v60, v61
	v_cvt_pk_f16_f32 v74, v62, v63
	v_cvt_pk_f16_f32 v75, v64, v65
	v_cvt_pk_f16_f32 v76, v66, v67
	v_cvt_pk_f16_f32 v77, v68, v69
	global_store_dwordx2 v151, v[70:71], s[36:37] offset:0
	global_store_dwordx2 v151, v[72:73], s[36:37] offset:512
	global_store_dwordx2 v151, v[74:75], s[36:37] offset:1024
	global_store_dwordx2 v151, v[76:77], s[36:37] offset:1536
	s_add_u32 s5, s5, 1
	s_sub_u32 s9, s5, 0x800
	s_lshr_b32 s9, s9, 13
	s_cmp_lt_u32 s5, 0x800
	s_cselect_b32 s9, 8, s9
	s_cmp_eq_u32 s9, s8
	s_cbranch_scc1 .Lr1b_nr8
	s_mov_b32 s8, s9
	s_waitcnt vmcnt(0)
	s_add_u32 s10, s9, 9
	s_mul_i32 s10, s10, 0x6000
	s_add_u32 s38, s56, s10
	s_addc_u32 s39, s57, 0
	global_load_dwordx4 v[54:57], v150, s[58:59] offset:0
	global_load_dwordx4 v[58:61], v150, s[58:59] offset:1024
	global_load_dwordx4 v[62:65], v150, s[58:59] offset:2048
	global_load_dwordx4 v[66:69], v150, s[58:59] offset:3072
	s_add_u32 s44, s38, 0x1000
	s_addc_u32 s45, s39, 0
	global_load_dwordx4 v[70:73], v150, s[44:45] offset:0
	global_load_dwordx4 v[74:77], v150, s[44:45] offset:1024
	global_load_dwordx4 v[78:81], v150, s[44:45] offset:2048
	global_load_dwordx4 v[82:85], v150, s[44:45] offset:3072
	global_load_dwordx4 v[16:19], v150, s[38:39] offset:0
	global_load_dwordx4 v[20:23], v150, s[38:39] offset:1024
	global_load_dwordx4 v[24:27], v150, s[38:39] offset:2048
	global_load_dwordx4 v[28:31], v150, s[38:39] offset:3072
	s_add_u32 s10, s9, 0
	s_mul_i32 s10, s10, 0x6000
	s_add_u32 s10, s10, 0x5000
	s_add_u32 s38, s56, s10
	s_addc_u32 s39, s57, 0
	global_load_dwordx4 v[32:35], v150, s[38:39] offset:0
	global_load_dwordx4 v[36:39], v150, s[38:39] offset:1024
	global_load_dwordx4 v[40:43], v150, s[38:39] offset:2048
	global_load_dwordx4 v[44:47], v150, s[38:39] offset:3072
	s_waitcnt vmcnt(0)
	v_add_f32_e32 v70, 1.0, v70
	v_add_f32_e32 v71, 1.0, v71
	v_add_f32_e32 v72, 1.0, v72
	v_add_f32_e32 v73, 1.0, v73
	v_add_f32_e32 v74, 1.0, v74
	v_add_f32_e32 v75, 1.0, v75
	v_add_f32_e32 v76, 1.0, v76
	v_add_f32_e32 v77, 1.0, v77
	v_add_f32_e32 v78, 1.0, v78
	v_add_f32_e32 v79, 1.0, v79
	v_add_f32_e32 v80, 1.0, v80
	v_add_f32_e32 v81, 1.0, v81
	v_add_f32_e32 v82, 1.0, v82
	v_add_f32_e32 v83, 1.0, v83
	v_add_f32_e32 v84, 1.0, v84
	v_add_f32_e32 v85, 1.0, v85
	v_mul_f32_e32 v0, v54, v70
	v_mul_f32_e32 v1, v55, v71
	v_mul_f32_e32 v2, v56, v72
	v_mul_f32_e32 v3, v57, v73
	v_mul_f32_e32 v4, v58, v74
	v_mul_f32_e32 v5, v59, v75
	v_mul_f32_e32 v6, v60, v76
	v_mul_f32_e32 v7, v61, v77
	v_mul_f32_e32 v8, v62, v78
	v_mul_f32_e32 v9, v63, v79
	v_mul_f32_e32 v10, v64, v80
	v_mul_f32_e32 v11, v65, v81
	v_mul_f32_e32 v12, v66, v82
	v_mul_f32_e32 v13, v67, v83
	v_mul_f32_e32 v14, v68, v84
	v_mul_f32_e32 v15, v69, v85
.Lr1b_nr8:
	s_waitcnt vmcnt(32)
	v_accvgpr_read_b32 v54, a96
	v_accvgpr_read_b32 v55, a97
	v_accvgpr_read_b32 v56, a98
	v_accvgpr_read_b32 v57, a99
	v_accvgpr_read_b32 v58, a100
	v_accvgpr_read_b32 v59, a101
	v_accvgpr_read_b32 v60, a102
	v_accvgpr_read_b32 v61, a103
	v_accvgpr_read_b32 v62, a104
	v_accvgpr_read_b32 v63, a105
	v_accvgpr_read_b32 v64, a106
	v_accvgpr_read_b32 v65, a107
	v_accvgpr_read_b32 v66, a108
	v_accvgpr_read_b32 v67, a109
	v_accvgpr_read_b32 v68, a110
	v_accvgpr_read_b32 v69, a111
	v_accvgpr_read_b32 v70, a112
	v_accvgpr_read_b32 v71, a113
	v_accvgpr_read_b32 v72, a114
	v_accvgpr_read_b32 v73, a115
	v_accvgpr_read_b32 v74, a116
	v_accvgpr_read_b32 v75, a117
	v_accvgpr_read_b32 v76, a118
	v_accvgpr_read_b32 v77, a119
	v_accvgpr_read_b32 v78, a120
	v_accvgpr_read_b32 v79, a121
	v_accvgpr_read_b32 v80, a122
	v_accvgpr_read_b32 v81, a123
	v_accvgpr_read_b32 v82, a124
	v_accvgpr_read_b32 v83, a125
	v_accvgpr_read_b32 v84, a126
	v_accvgpr_read_b32 v85, a127
	s_lshl_b32 s10, s5, 12
	s_cmp_lt_u32 s5, 0x800
	s_cselect_b64 s[34:35], s[48:49], s[50:51]
	s_add_u32 s34, s34, s10
	s_addc_u32 s35, s35, 0
	s_lshr_b32 s10, s10, 1
	s_add_u32 s36, s54, s10
	s_addc_u32 s37, s55, 0
	v_cvt_f32_f16_e32 v154, v70
	v_cvt_f32_f16_e32 v155, v78
	v_add_f32_e32 v154, v154, v155
	v_fmac_f32_e32 v54, v32, v154
	v_cvt_f32_f16_sdwa v156, v70 dst_sel:DWORD dst_unused:UNUSED_PAD src0_sel:WORD_1
	v_cvt_f32_f16_sdwa v157, v78 dst_sel:DWORD dst_unused:UNUSED_PAD src0_sel:WORD_1
	v_add_f32_e32 v156, v156, v157
	v_fmac_f32_e32 v55, v33, v156
	v_cvt_f32_f16_e32 v154, v71
	v_cvt_f32_f16_e32 v155, v79
	v_add_f32_e32 v154, v154, v155
	v_fmac_f32_e32 v56, v34, v154
	v_cvt_f32_f16_sdwa v156, v71 dst_sel:DWORD dst_unused:UNUSED_PAD src0_sel:WORD_1
; DI void row1_phase(const Params& P, int combine_l, int norm_l, int r_begin) {
;     ...
; #pragma unroll
;       for (int i = 0; i < 4; i++) {
;         int c = i * 256 + lane * 4;
;         float4 g = *(const float4*)(g2 + c); float4 t = xv[i];
;         t.x += g.x * ((float)ya[i][0] + (float)yb[i][0]); t.y += g.y * ((float)ya[i][1] + (float)yb[i][1]);
;         t.z += g.z * ((float)ya[i][2] + (float)yb[i][2]); t.w += g.w * ((float)ya[i][3] + (float)yb[i][3]);
;         *(float4*)(xm + c) = t; xv[i] = t;
;       }
;     }
;     if (norm_l >= 0) {
;       float ss = 0.f;
; #pragma unroll
;       for (int i = 0; i < 4; i++) ss += xv[i].x * xv[i].x + xv[i].y * xv[i].y + xv[i].z * xv[i].z + xv[i].w * xv[i].w;
;       ss = wave_sum(ss);
;       const float rstd = rsqrtf(ss * (1.f / 1024.f) + EPS);
;       const float* g = P.norm1_g + norm_l * 1024;
;       const float* sh = P.mod + (size_t)(norm_l * 9 + n) * 6144; const float* sc = sh + 1024;
; #pragma unroll
;       for (int i = 0; i < 4; i++) {
;         int c = i * 256 + lane * 4;
;         float4 gg = *(const float4*)(g + c), s1 = *(const float4*)(sc + c), s0 = *(const float4*)(sh + c);
;         h4 o;
;         o[0] = (half_t)(xv[i].x * rstd * gg.x * (1.f + s1.x) + s0.x); o[1] = (half_t)(xv[i].y * rstd * gg.y * (1.f + s1.y) + s0.y);
;         o[2] = (half_t)(xv[i].z * rstd * gg.z * (1.f + s1.z) + s0.z); o[3] = (half_t)(xv[i].w * rstd * gg.w * (1.f + s1.w) + s0.w);
;         *(h4*)(P.hx + (size_t)r * D + c) = o;
;       }
;     }
	v_cvt_f32_f16_sdwa v157, v79 dst_sel:DWORD dst_unused:UNUSED_PAD src0_sel:WORD_1
	v_add_f32_e32 v156, v156, v157
	v_fmac_f32_e32 v57, v35, v156
	v_cvt_f32_f16_e32 v154, v72
	v_cvt_f32_f16_e32 v155, v80
	v_add_f32_e32 v154, v154, v155
	v_fmac_f32_e32 v58, v36, v154
	v_cvt_f32_f16_sdwa v156, v72 dst_sel:DWORD dst_unused:UNUSED_PAD src0_sel:WORD_1
	v_cvt_f32_f16_sdwa v157, v80 dst_sel:DWORD dst_unused:UNUSED_PAD src0_sel:WORD_1
	v_add_f32_e32 v156, v156, v157
	v_fmac_f32_e32 v59, v37, v156
	v_cvt_f32_f16_e32 v154, v73
	v_cvt_f32_f16_e32 v155, v81
	v_add_f32_e32 v154, v154, v155
	v_fmac_f32_e32 v60, v38, v154
	v_cvt_f32_f16_sdwa v156, v73 dst_sel:DWORD dst_unused:UNUSED_PAD src0_sel:WORD_1
	v_cvt_f32_f16_sdwa v157, v81 dst_sel:DWORD dst_unused:UNUSED_PAD src0_sel:WORD_1
	v_add_f32_e32 v156, v156, v157
	v_fmac_f32_e32 v61, v39, v156
	v_cvt_f32_f16_e32 v154, v74
	v_cvt_f32_f16_e32 v155, v82
	v_add_f32_e32 v154, v154, v155
	v_fmac_f32_e32 v62, v40, v154
	v_cvt_f32_f16_sdwa v156, v74 dst_sel:DWORD dst_unused:UNUSED_PAD src0_sel:WORD_1
	v_cvt_f32_f16_sdwa v157, v82 dst_sel:DWORD dst_unused:UNUSED_PAD src0_sel:WORD_1
	v_add_f32_e32 v156, v156, v157
	v_fmac_f32_e32 v63, v41, v156
	v_cvt_f32_f16_e32 v154, v75
	v_cvt_f32_f16_e32 v155, v83
	v_add_f32_e32 v154, v154, v155
	v_fmac_f32_e32 v64, v42, v154
	v_cvt_f32_f16_sdwa v156, v75 dst_sel:DWORD dst_unused:UNUSED_PAD src0_sel:WORD_1
	v_cvt_f32_f16_sdwa v157, v83 dst_sel:DWORD dst_unused:UNUSED_PAD src0_sel:WORD_1
	v_add_f32_e32 v156, v156, v157
	v_fmac_f32_e32 v65, v43, v156
	v_cvt_f32_f16_e32 v154, v76
	v_cvt_f32_f16_e32 v155, v84
	v_add_f32_e32 v154, v154, v155
	v_fmac_f32_e32 v66, v44, v154
	v_cvt_f32_f16_sdwa v156, v76 dst_sel:DWORD dst_unused:UNUSED_PAD src0_sel:WORD_1
	v_cvt_f32_f16_sdwa v157, v84 dst_sel:DWORD dst_unused:UNUSED_PAD src0_sel:WORD_1
	v_add_f32_e32 v156, v156, v157
	v_fmac_f32_e32 v67, v45, v156
	v_cvt_f32_f16_e32 v154, v77
	v_cvt_f32_f16_e32 v155, v85
	v_add_f32_e32 v154, v154, v155
	v_fmac_f32_e32 v68, v46, v154
	v_cvt_f32_f16_sdwa v156, v77 dst_sel:DWORD dst_unused:UNUSED_PAD src0_sel:WORD_1
	v_cvt_f32_f16_sdwa v157, v85 dst_sel:DWORD dst_unused:UNUSED_PAD src0_sel:WORD_1
	v_add_f32_e32 v156, v156, v157
	v_fmac_f32_e32 v69, v47, v156
	global_store_dwordx4 v150, v[54:57], s[34:35] offset:0
	global_store_dwordx4 v150, v[58:61], s[34:35] offset:1024
	global_store_dwordx4 v150, v[62:65], s[34:35] offset:2048
	global_store_dwordx4 v150, v[66:69], s[34:35] offset:3072
	v_mul_f32_e32 v152, v54, v54
	v_mul_f32_e32 v153, v55, v55
	v_fmac_f32_e32 v152, v56, v56
	v_fmac_f32_e32 v153, v57, v57
	v_fmac_f32_e32 v152, v58, v58
	v_fmac_f32_e32 v153, v59, v59
	v_fmac_f32_e32 v152, v60, v60
	v_fmac_f32_e32 v153, v61, v61
	v_fmac_f32_e32 v152, v62, v62
	v_fmac_f32_e32 v153, v63, v63
	v_fmac_f32_e32 v152, v64, v64
	v_fmac_f32_e32 v153, v65, v65
	v_fmac_f32_e32 v152, v66, v66
	v_fmac_f32_e32 v153, v67, v67
	v_fmac_f32_e32 v152, v68, v68
	v_fmac_f32_e32 v153, v69, v69
	v_add_f32_e32 v152, v152, v153
	v_xor_b32_e32 v158, 128, v159
	ds_bpermute_b32 v153, v158, v152
	s_waitcnt lgkmcnt(0)
	v_add_f32_e32 v152, v152, v153
	v_xor_b32_e32 v158, 64, v159
	ds_bpermute_b32 v153, v158, v152
	s_waitcnt lgkmcnt(0)
	v_add_f32_e32 v152, v152, v153
	v_xor_b32_e32 v158, 32, v159
	ds_bpermute_b32 v153, v158, v152
	s_waitcnt lgkmcnt(0)
	v_add_f32_e32 v152, v152, v153
	v_xor_b32_e32 v158, 16, v159
	ds_bpermute_b32 v153, v158, v152
	s_waitcnt lgkmcnt(0)
	v_add_f32_e32 v152, v152, v153
	v_xor_b32_e32 v158, 8, v159
	ds_bpermute_b32 v153, v158, v152
	s_waitcnt lgkmcnt(0)
	v_add_f32_e32 v152, v152, v153
	v_xor_b32_e32 v158, 4, v159
	ds_bpermute_b32 v153, v158, v152
	s_waitcnt lgkmcnt(0)
	v_add_f32_e32 v152, v152, v153
	v_mov_b32_e32 v153, 0x358637bd
	v_fmamk_f32 v152, v152, 0x3a800000, v153
	v_rsq_f32_e32 v152, v152
	s_nop 1
	v_mul_f32_e32 v54, v54, v152
	v_mul_f32_e32 v55, v55, v152
	v_mul_f32_e32 v56, v56, v152
	v_mul_f32_e32 v57, v57, v152
	v_mul_f32_e32 v58, v58, v152
	v_mul_f32_e32 v59, v59, v152
	v_mul_f32_e32 v60, v60, v152
	v_mul_f32_e32 v61, v61, v152
	v_mul_f32_e32 v62, v62, v152
	v_mul_f32_e32 v63, v63, v152
	v_mul_f32_e32 v64, v64, v152
	v_mul_f32_e32 v65, v65, v152
	v_mul_f32_e32 v66, v66, v152
	v_mul_f32_e32 v67, v67, v152
	v_mul_f32_e32 v68, v68, v152
	v_mul_f32_e32 v69, v69, v152
	v_fma_f32 v54, v54, v0, v16
	v_fma_f32 v55, v55, v1, v17
	v_fma_f32 v56, v56, v2, v18
	v_fma_f32 v57, v57, v3, v19
	v_fma_f32 v58, v58, v4, v20
	v_fma_f32 v59, v59, v5, v21
	v_fma_f32 v60, v60, v6, v22
	v_fma_f32 v61, v61, v7, v23
	v_fma_f32 v62, v62, v8, v24
	v_fma_f32 v63, v63, v9, v25
	v_fma_f32 v64, v64, v10, v26
	v_fma_f32 v65, v65, v11, v27
	v_fma_f32 v66, v66, v12, v28
	v_fma_f32 v67, v67, v13, v29
	v_fma_f32 v68, v68, v14, v30
	v_fma_f32 v69, v69, v15, v31
	v_cvt_pk_f16_f32 v70, v54, v55
	v_cvt_pk_f16_f32 v71, v56, v57
	v_cvt_pk_f16_f32 v72, v58, v59
	v_cvt_pk_f16_f32 v73, v60, v61
	v_cvt_pk_f16_f32 v74, v62, v63
	v_cvt_pk_f16_f32 v75, v64, v65
	v_cvt_pk_f16_f32 v76, v66, v67
	v_cvt_pk_f16_f32 v77, v68, v69
	global_store_dwordx2 v151, v[70:71], s[36:37] offset:0
	global_store_dwordx2 v151, v[72:73], s[36:37] offset:512
	global_store_dwordx2 v151, v[74:75], s[36:37] offset:1024
	global_store_dwordx2 v151, v[76:77], s[36:37] offset:1536
	s_add_u32 s5, s5, 1
	s_sub_u32 s9, s5, 0x800
	s_lshr_b32 s9, s9, 13
	s_cmp_lt_u32 s5, 0x800
	s_cselect_b32 s9, 8, s9
	s_cmp_eq_u32 s9, s8
	s_cbranch_scc1 .Lr1b_nr9
; DI void row1_phase(const Params& P, int combine_l, int norm_l, int r_begin) {
;     ...
;     const int n = row_mod(r);
;     if (combine_l >= 0) {
;       float* xm = r < TC ? P.xcbuf + (size_t)r * D : P.out + (size_t)(r - TC) * D;
;       const float* g2 = P.mod + (size_t)(combine_l * 9 + n) * 6144 + 5 * 1024;
; #pragma unroll
;       for (int i = 0; i < 4; i++) {
;         int c = i * 256 + lane * 4;
;         float4 g = *(const float4*)(g2 + c); float4 t = xv[i];
;         t.x += g.x * ((float)ya[i][0] + (float)yb[i][0]); t.y += g.y * ((float)ya[i][1] + (float)yb[i][1]);
;         t.z += g.z * ((float)ya[i][2] + (float)yb[i][2]); t.w += g.w * ((float)ya[i][3] + (float)yb[i][3]);
;         *(float4*)(xm + c) = t; xv[i] = t;
	s_mov_b32 s8, s9
	s_waitcnt vmcnt(0)
	s_add_u32 s10, s9, 9
	s_mul_i32 s10, s10, 0x6000
	s_add_u32 s38, s56, s10
	s_addc_u32 s39, s57, 0
	global_load_dwordx4 v[54:57], v150, s[58:59] offset:0
	global_load_dwordx4 v[58:61], v150, s[58:59] offset:1024
	global_load_dwordx4 v[62:65], v150, s[58:59] offset:2048
	global_load_dwordx4 v[66:69], v150, s[58:59] offset:3072
	s_add_u32 s44, s38, 0x1000
	s_addc_u32 s45, s39, 0
	global_load_dwordx4 v[70:73], v150, s[44:45] offset:0
	global_load_dwordx4 v[74:77], v150, s[44:45] offset:1024
	global_load_dwordx4 v[78:81], v150, s[44:45] offset:2048
	global_load_dwordx4 v[82:85], v150, s[44:45] offset:3072
	global_load_dwordx4 v[16:19], v150, s[38:39] offset:0
	global_load_dwordx4 v[20:23], v150, s[38:39] offset:1024
	global_load_dwordx4 v[24:27], v150, s[38:39] offset:2048
	global_load_dwordx4 v[28:31], v150, s[38:39] offset:3072
	s_add_u32 s10, s9, 0
	s_mul_i32 s10, s10, 0x6000
	s_add_u32 s10, s10, 0x5000
	s_add_u32 s38, s56, s10
	s_addc_u32 s39, s57, 0
	global_load_dwordx4 v[32:35], v150, s[38:39] offset:0
	global_load_dwordx4 v[36:39], v150, s[38:39] offset:1024
	global_load_dwordx4 v[40:43], v150, s[38:39] offset:2048
	global_load_dwordx4 v[44:47], v150, s[38:39] offset:3072
	s_waitcnt vmcnt(0)
	v_add_f32_e32 v70, 1.0, v70
	v_add_f32_e32 v71, 1.0, v71
	v_add_f32_e32 v72, 1.0, v72
	v_add_f32_e32 v73, 1.0, v73
	v_add_f32_e32 v74, 1.0, v74
	v_add_f32_e32 v75, 1.0, v75
	v_add_f32_e32 v76, 1.0, v76
	v_add_f32_e32 v77, 1.0, v77
	v_add_f32_e32 v78, 1.0, v78
	v_add_f32_e32 v79, 1.0, v79
	v_add_f32_e32 v80, 1.0, v80
	v_add_f32_e32 v81, 1.0, v81
	v_add_f32_e32 v82, 1.0, v82
	v_add_f32_e32 v83, 1.0, v83
	v_add_f32_e32 v84, 1.0, v84
	v_add_f32_e32 v85, 1.0, v85
	v_mul_f32_e32 v0, v54, v70
	v_mul_f32_e32 v1, v55, v71
	v_mul_f32_e32 v2, v56, v72
	v_mul_f32_e32 v3, v57, v73
	v_mul_f32_e32 v4, v58, v74
	v_mul_f32_e32 v5, v59, v75
	v_mul_f32_e32 v6, v60, v76
	v_mul_f32_e32 v7, v61, v77
	v_mul_f32_e32 v8, v62, v78
	v_mul_f32_e32 v9, v63, v79
	v_mul_f32_e32 v10, v64, v80
	v_mul_f32_e32 v11, v65, v81
	v_mul_f32_e32 v12, v66, v82
	v_mul_f32_e32 v13, v67, v83
	v_mul_f32_e32 v14, v68, v84
	v_mul_f32_e32 v15, v69, v85
.Lr1b_nr9:
	s_waitcnt vmcnt(20)
	v_accvgpr_read_b32 v54, a0
	v_accvgpr_read_b32 v55, a1
	v_accvgpr_read_b32 v56, a2
	v_accvgpr_read_b32 v57, a3
	v_accvgpr_read_b32 v58, a4
	v_accvgpr_read_b32 v59, a5
	v_accvgpr_read_b32 v60, a6
	v_accvgpr_read_b32 v61, a7
	v_accvgpr_read_b32 v62, a8
	v_accvgpr_read_b32 v63, a9
	v_accvgpr_read_b32 v64, a10
	v_accvgpr_read_b32 v65, a11
	v_accvgpr_read_b32 v66, a12
	v_accvgpr_read_b32 v67, a13
	v_accvgpr_read_b32 v68, a14
	v_accvgpr_read_b32 v69, a15
	v_accvgpr_read_b32 v70, a16
	v_accvgpr_read_b32 v71, a17
	v_accvgpr_read_b32 v72, a18
	v_accvgpr_read_b32 v73, a19
	v_accvgpr_read_b32 v74, a20
	v_accvgpr_read_b32 v75, a21
	v_accvgpr_read_b32 v76, a22
	v_accvgpr_read_b32 v77, a23
	v_accvgpr_read_b32 v78, a24
	v_accvgpr_read_b32 v79, a25
	v_accvgpr_read_b32 v80, a26
	v_accvgpr_read_b32 v81, a27
	v_accvgpr_read_b32 v82, a28
	v_accvgpr_read_b32 v83, a29
	v_accvgpr_read_b32 v84, a30
	v_accvgpr_read_b32 v85, a31
	s_lshl_b32 s10, s5, 12
	s_cmp_lt_u32 s5, 0x800
	s_cselect_b64 s[34:35], s[48:49], s[50:51]
	s_add_u32 s34, s34, s10
	s_addc_u32 s35, s35, 0
	s_lshr_b32 s10, s10, 1
	s_add_u32 s36, s54, s10
	s_addc_u32 s37, s55, 0
	v_cvt_f32_f16_e32 v154, v70
	v_cvt_f32_f16_e32 v155, v78
	v_add_f32_e32 v154, v154, v155
	v_fmac_f32_e32 v54, v32, v154
	v_cvt_f32_f16_sdwa v156, v70 dst_sel:DWORD dst_unused:UNUSED_PAD src0_sel:WORD_1
	v_cvt_f32_f16_sdwa v157, v78 dst_sel:DWORD dst_unused:UNUSED_PAD src0_sel:WORD_1
	v_add_f32_e32 v156, v156, v157
	v_fmac_f32_e32 v55, v33, v156
	v_cvt_f32_f16_e32 v154, v71
	v_cvt_f32_f16_e32 v155, v79
	v_add_f32_e32 v154, v154, v155
	v_fmac_f32_e32 v56, v34, v154
	v_cvt_f32_f16_sdwa v156, v71 dst_sel:DWORD dst_unused:UNUSED_PAD src0_sel:WORD_1
	v_cvt_f32_f16_sdwa v157, v79 dst_sel:DWORD dst_unused:UNUSED_PAD src0_sel:WORD_1
	v_add_f32_e32 v156, v156, v157
	v_fmac_f32_e32 v57, v35, v156
	v_cvt_f32_f16_e32 v154, v72
	v_cvt_f32_f16_e32 v155, v80
	v_add_f32_e32 v154, v154, v155
	v_fmac_f32_e32 v58, v36, v154
	v_cvt_f32_f16_sdwa v156, v72 dst_sel:DWORD dst_unused:UNUSED_PAD src0_sel:WORD_1
	v_cvt_f32_f16_sdwa v157, v80 dst_sel:DWORD dst_unused:UNUSED_PAD src0_sel:WORD_1
	v_add_f32_e32 v156, v156, v157
	v_fmac_f32_e32 v59, v37, v156
	v_cvt_f32_f16_e32 v154, v73
	v_cvt_f32_f16_e32 v155, v81
	v_add_f32_e32 v154, v154, v155
	v_fmac_f32_e32 v60, v38, v154
	v_cvt_f32_f16_sdwa v156, v73 dst_sel:DWORD dst_unused:UNUSED_PAD src0_sel:WORD_1
	v_cvt_f32_f16_sdwa v157, v81 dst_sel:DWORD dst_unused:UNUSED_PAD src0_sel:WORD_1
	v_add_f32_e32 v156, v156, v157
	v_fmac_f32_e32 v61, v39, v156
	v_cvt_f32_f16_e32 v154, v74
	v_cvt_f32_f16_e32 v155, v82
	v_add_f32_e32 v154, v154, v155
	v_fmac_f32_e32 v62, v40, v154
	v_cvt_f32_f16_sdwa v156, v74 dst_sel:DWORD dst_unused:UNUSED_PAD src0_sel:WORD_1
	v_cvt_f32_f16_sdwa v157, v82 dst_sel:DWORD dst_unused:UNUSED_PAD src0_sel:WORD_1
	v_add_f32_e32 v156, v156, v157
	v_fmac_f32_e32 v63, v41, v156
	v_cvt_f32_f16_e32 v154, v75
	v_cvt_f32_f16_e32 v155, v83
	v_add_f32_e32 v154, v154, v155
	v_fmac_f32_e32 v64, v42, v154
	v_cvt_f32_f16_sdwa v156, v75 dst_sel:DWORD dst_unused:UNUSED_PAD src0_sel:WORD_1
	v_cvt_f32_f16_sdwa v157, v83 dst_sel:DWORD dst_unused:UNUSED_PAD src0_sel:WORD_1
	v_add_f32_e32 v156, v156, v157
	v_fmac_f32_e32 v65, v43, v156
	v_cvt_f32_f16_e32 v154, v76
	v_cvt_f32_f16_e32 v155, v84
	v_add_f32_e32 v154, v154, v155
	v_fmac_f32_e32 v66, v44, v154
	v_cvt_f32_f16_sdwa v156, v76 dst_sel:DWORD dst_unused:UNUSED_PAD src0_sel:WORD_1
	v_cvt_f32_f16_sdwa v157, v84 dst_sel:DWORD dst_unused:UNUSED_PAD src0_sel:WORD_1
	v_add_f32_e32 v156, v156, v157
	v_fmac_f32_e32 v67, v45, v156
	v_cvt_f32_f16_e32 v154, v77
	v_cvt_f32_f16_e32 v155, v85
	v_add_f32_e32 v154, v154, v155
	v_fmac_f32_e32 v68, v46, v154
	v_cvt_f32_f16_sdwa v156, v77 dst_sel:DWORD dst_unused:UNUSED_PAD src0_sel:WORD_1
	v_cvt_f32_f16_sdwa v157, v85 dst_sel:DWORD dst_unused:UNUSED_PAD src0_sel:WORD_1
	v_add_f32_e32 v156, v156, v157
	v_fmac_f32_e32 v69, v47, v156
	global_store_dwordx4 v150, v[54:57], s[34:35] offset:0
	global_store_dwordx4 v150, v[58:61], s[34:35] offset:1024
	global_store_dwordx4 v150, v[62:65], s[34:35] offset:2048
	global_store_dwordx4 v150, v[66:69], s[34:35] offset:3072
	v_mul_f32_e32 v152, v54, v54
	v_mul_f32_e32 v153, v55, v55
	v_fmac_f32_e32 v152, v56, v56
	v_fmac_f32_e32 v153, v57, v57
	v_fmac_f32_e32 v152, v58, v58
	v_fmac_f32_e32 v153, v59, v59
	v_fmac_f32_e32 v152, v60, v60
	v_fmac_f32_e32 v153, v61, v61
	v_fmac_f32_e32 v152, v62, v62
	v_fmac_f32_e32 v153, v63, v63
	v_fmac_f32_e32 v152, v64, v64
	v_fmac_f32_e32 v153, v65, v65
	v_fmac_f32_e32 v152, v66, v66
	v_fmac_f32_e32 v153, v67, v67
	v_fmac_f32_e32 v152, v68, v68
	v_fmac_f32_e32 v153, v69, v69
	v_add_f32_e32 v152, v152, v153
	v_xor_b32_e32 v158, 128, v159
	ds_bpermute_b32 v153, v158, v152
	s_waitcnt lgkmcnt(0)
; DI void row1_phase(const Params& P, int combine_l, int norm_l, int r_begin) {
;     ...
;     const int n = row_mod(r);
;     if (combine_l >= 0) {
;       float* xm = r < TC ? P.xcbuf + (size_t)r * D : P.out + (size_t)(r - TC) * D;
;       const float* g2 = P.mod + (size_t)(combine_l * 9 + n) * 6144 + 5 * 1024;
;     ...
;       float ss = 0.f;
; #pragma unroll
;       for (int i = 0; i < 4; i++) ss += xv[i].x * xv[i].x + xv[i].y * xv[i].y + xv[i].z * xv[i].z + xv[i].w * xv[i].w;
;       ss = wave_sum(ss);
;       const float rstd = rsqrtf(ss * (1.f / 1024.f) + EPS);
;       const float* g = P.norm1_g + norm_l * 1024;
;       const float* sh = P.mod + (size_t)(norm_l * 9 + n) * 6144; const float* sc = sh + 1024;
; #pragma unroll
;       for (int i = 0; i < 4; i++) {
;         int c = i * 256 + lane * 4;
;         float4 gg = *(const float4*)(g + c), s1 = *(const float4*)(sc + c), s0 = *(const float4*)(sh + c);
;         h4 o;
;         o[0] = (half_t)(xv[i].x * rstd * gg.x * (1.f + s1.x) + s0.x); o[1] = (half_t)(xv[i].y * rstd * gg.y * (1.f + s1.y) + s0.y);
;         o[2] = (half_t)(xv[i].z * rstd * gg.z * (1.f + s1.z) + s0.z); o[3] = (half_t)(xv[i].w * rstd * gg.w * (1.f + s1.w) + s0.w);
;         *(h4*)(P.hx + (size_t)r * D + c) = o;
;       }
	v_add_f32_e32 v152, v152, v153
	v_xor_b32_e32 v158, 64, v159
	ds_bpermute_b32 v153, v158, v152
	s_waitcnt lgkmcnt(0)
	v_add_f32_e32 v152, v152, v153
	v_xor_b32_e32 v158, 32, v159
	ds_bpermute_b32 v153, v158, v152
	s_waitcnt lgkmcnt(0)
	v_add_f32_e32 v152, v152, v153
	v_xor_b32_e32 v158, 16, v159
	ds_bpermute_b32 v153, v158, v152
	s_waitcnt lgkmcnt(0)
	v_add_f32_e32 v152, v152, v153
	v_xor_b32_e32 v158, 8, v159
	ds_bpermute_b32 v153, v158, v152
	s_waitcnt lgkmcnt(0)
	v_add_f32_e32 v152, v152, v153
	v_xor_b32_e32 v158, 4, v159
	ds_bpermute_b32 v153, v158, v152
	s_waitcnt lgkmcnt(0)
	v_add_f32_e32 v152, v152, v153
	v_mov_b32_e32 v153, 0x358637bd
	v_fmamk_f32 v152, v152, 0x3a800000, v153
	v_rsq_f32_e32 v152, v152
	s_nop 1
	v_mul_f32_e32 v54, v54, v152
	v_mul_f32_e32 v55, v55, v152
	v_mul_f32_e32 v56, v56, v152
	v_mul_f32_e32 v57, v57, v152
	v_mul_f32_e32 v58, v58, v152
	v_mul_f32_e32 v59, v59, v152
	v_mul_f32_e32 v60, v60, v152
	v_mul_f32_e32 v61, v61, v152
	v_mul_f32_e32 v62, v62, v152
	v_mul_f32_e32 v63, v63, v152
	v_mul_f32_e32 v64, v64, v152
	v_mul_f32_e32 v65, v65, v152
	v_mul_f32_e32 v66, v66, v152
	v_mul_f32_e32 v67, v67, v152
	v_mul_f32_e32 v68, v68, v152
	v_mul_f32_e32 v69, v69, v152
	v_fma_f32 v54, v54, v0, v16
	v_fma_f32 v55, v55, v1, v17
	v_fma_f32 v56, v56, v2, v18
	v_fma_f32 v57, v57, v3, v19
	v_fma_f32 v58, v58, v4, v20
	v_fma_f32 v59, v59, v5, v21
	v_fma_f32 v60, v60, v6, v22
	v_fma_f32 v61, v61, v7, v23
	v_fma_f32 v62, v62, v8, v24
	v_fma_f32 v63, v63, v9, v25
	v_fma_f32 v64, v64, v10, v26
	v_fma_f32 v65, v65, v11, v27
	v_fma_f32 v66, v66, v12, v28
	v_fma_f32 v67, v67, v13, v29
	v_fma_f32 v68, v68, v14, v30
	v_fma_f32 v69, v69, v15, v31
	v_cvt_pk_f16_f32 v70, v54, v55
	v_cvt_pk_f16_f32 v71, v56, v57
	v_cvt_pk_f16_f32 v72, v58, v59
	v_cvt_pk_f16_f32 v73, v60, v61
	v_cvt_pk_f16_f32 v74, v62, v63
	v_cvt_pk_f16_f32 v75, v64, v65
	v_cvt_pk_f16_f32 v76, v66, v67
	v_cvt_pk_f16_f32 v77, v68, v69
	global_store_dwordx2 v151, v[70:71], s[36:37] offset:0
	global_store_dwordx2 v151, v[72:73], s[36:37] offset:512
	global_store_dwordx2 v151, v[74:75], s[36:37] offset:1024
	global_store_dwordx2 v151, v[76:77], s[36:37] offset:1536
	s_add_u32 s5, s5, 1
	s_sub_u32 s9, s5, 0x800
	s_lshr_b32 s9, s9, 13
	s_cmp_lt_u32 s5, 0x800
	s_cselect_b32 s9, 8, s9
	s_cmp_eq_u32 s9, s8
	s_cbranch_scc1 .Lr1b_nr10
	s_mov_b32 s8, s9
	s_waitcnt vmcnt(0)
	s_add_u32 s10, s9, 9
	s_mul_i32 s10, s10, 0x6000
	s_add_u32 s38, s56, s10
	s_addc_u32 s39, s57, 0
	global_load_dwordx4 v[54:57], v150, s[58:59] offset:0
	global_load_dwordx4 v[58:61], v150, s[58:59] offset:1024
	global_load_dwordx4 v[62:65], v150, s[58:59] offset:2048
	global_load_dwordx4 v[66:69], v150, s[58:59] offset:3072
	s_add_u32 s44, s38, 0x1000
	s_addc_u32 s45, s39, 0
	global_load_dwordx4 v[70:73], v150, s[44:45] offset:0
	global_load_dwordx4 v[74:77], v150, s[44:45] offset:1024
	global_load_dwordx4 v[78:81], v150, s[44:45] offset:2048
	global_load_dwordx4 v[82:85], v150, s[44:45] offset:3072
	global_load_dwordx4 v[16:19], v150, s[38:39] offset:0
	global_load_dwordx4 v[20:23], v150, s[38:39] offset:1024
	global_load_dwordx4 v[24:27], v150, s[38:39] offset:2048
	global_load_dwordx4 v[28:31], v150, s[38:39] offset:3072
	s_add_u32 s10, s9, 0
	s_mul_i32 s10, s10, 0x6000
	s_add_u32 s10, s10, 0x5000
	s_add_u32 s38, s56, s10
	s_addc_u32 s39, s57, 0
	global_load_dwordx4 v[32:35], v150, s[38:39] offset:0
	global_load_dwordx4 v[36:39], v150, s[38:39] offset:1024
	global_load_dwordx4 v[40:43], v150, s[38:39] offset:2048
	global_load_dwordx4 v[44:47], v150, s[38:39] offset:3072
	s_waitcnt vmcnt(0)
	v_add_f32_e32 v70, 1.0, v70
	v_add_f32_e32 v71, 1.0, v71
	v_add_f32_e32 v72, 1.0, v72
	v_add_f32_e32 v73, 1.0, v73
	v_add_f32_e32 v74, 1.0, v74
	v_add_f32_e32 v75, 1.0, v75
	v_add_f32_e32 v76, 1.0, v76
	v_add_f32_e32 v77, 1.0, v77
	v_add_f32_e32 v78, 1.0, v78
	v_add_f32_e32 v79, 1.0, v79
	v_add_f32_e32 v80, 1.0, v80
	v_add_f32_e32 v81, 1.0, v81
	v_add_f32_e32 v82, 1.0, v82
	v_add_f32_e32 v83, 1.0, v83
	v_add_f32_e32 v84, 1.0, v84
	v_add_f32_e32 v85, 1.0, v85
	v_mul_f32_e32 v0, v54, v70
	v_mul_f32_e32 v1, v55, v71
	v_mul_f32_e32 v2, v56, v72
	v_mul_f32_e32 v3, v57, v73
	v_mul_f32_e32 v4, v58, v74
	v_mul_f32_e32 v5, v59, v75
	v_mul_f32_e32 v6, v60, v76
	v_mul_f32_e32 v7, v61, v77
	v_mul_f32_e32 v8, v62, v78
	v_mul_f32_e32 v9, v63, v79
	v_mul_f32_e32 v10, v64, v80
	v_mul_f32_e32 v11, v65, v81
	v_mul_f32_e32 v12, v66, v82
	v_mul_f32_e32 v13, v67, v83
	v_mul_f32_e32 v14, v68, v84
	v_mul_f32_e32 v15, v69, v85
; DI void row1_phase(const Params& P, int combine_l, int norm_l, int r_begin) {
;     ...
;       float* xm = r < TC ? P.xcbuf + (size_t)r * D : P.out + (size_t)(r - TC) * D;
;       const float* g2 = P.mod + (size_t)(combine_l * 9 + n) * 6144 + 5 * 1024;
; #pragma unroll
;       for (int i = 0; i < 4; i++) {
;         int c = i * 256 + lane * 4;
;         float4 g = *(const float4*)(g2 + c); float4 t = xv[i];
;         t.x += g.x * ((float)ya[i][0] + (float)yb[i][0]); t.y += g.y * ((float)ya[i][1] + (float)yb[i][1]);
;         t.z += g.z * ((float)ya[i][2] + (float)yb[i][2]); t.w += g.w * ((float)ya[i][3] + (float)yb[i][3]);
;         *(float4*)(xm + c) = t; xv[i] = t;
;       }
;     }
;     if (norm_l >= 0) {
;       float ss = 0.f;
; #pragma unroll
;       for (int i = 0; i < 4; i++) ss += xv[i].x * xv[i].x + xv[i].y * xv[i].y + xv[i].z * xv[i].z + xv[i].w * xv[i].w;
;       ss = wave_sum(ss);
;       const float rstd = rsqrtf(ss * (1.f / 1024.f) + EPS);
;       const float* g = P.norm1_g + norm_l * 1024;
;       const float* sh = P.mod + (size_t)(norm_l * 9 + n) * 6144; const float* sc = sh + 1024;
; #pragma unroll
;       for (int i = 0; i < 4; i++) {
;         int c = i * 256 + lane * 4;
;         float4 gg = *(const float4*)(g + c), s1 = *(const float4*)(sc + c), s0 = *(const float4*)(sh + c);
;         h4 o;
;         o[0] = (half_t)(xv[i].x * rstd * gg.x * (1.f + s1.x) + s0.x); o[1] = (half_t)(xv[i].y * rstd * gg.y * (1.f + s1.y) + s0.y);
;         o[2] = (half_t)(xv[i].z * rstd * gg.z * (1.f + s1.z) + s0.z); o[3] = (half_t)(xv[i].w * rstd * gg.w * (1.f + s1.w) + s0.w);
;         *(h4*)(P.hx + (size_t)r * D + c) = o;
;       }
.Lr1b_nr10:
	s_waitcnt vmcnt(8)
	v_accvgpr_read_b32 v54, a32
	v_accvgpr_read_b32 v55, a33
	v_accvgpr_read_b32 v56, a34
	v_accvgpr_read_b32 v57, a35
	v_accvgpr_read_b32 v58, a36
	v_accvgpr_read_b32 v59, a37
	v_accvgpr_read_b32 v60, a38
	v_accvgpr_read_b32 v61, a39
	v_accvgpr_read_b32 v62, a40
	v_accvgpr_read_b32 v63, a41
	v_accvgpr_read_b32 v64, a42
	v_accvgpr_read_b32 v65, a43
	v_accvgpr_read_b32 v66, a44
	v_accvgpr_read_b32 v67, a45
	v_accvgpr_read_b32 v68, a46
	v_accvgpr_read_b32 v69, a47
	v_accvgpr_read_b32 v70, a48
	v_accvgpr_read_b32 v71, a49
	v_accvgpr_read_b32 v72, a50
	v_accvgpr_read_b32 v73, a51
	v_accvgpr_read_b32 v74, a52
	v_accvgpr_read_b32 v75, a53
	v_accvgpr_read_b32 v76, a54
	v_accvgpr_read_b32 v77, a55
	v_accvgpr_read_b32 v78, a56
	v_accvgpr_read_b32 v79, a57
	v_accvgpr_read_b32 v80, a58
	v_accvgpr_read_b32 v81, a59
	v_accvgpr_read_b32 v82, a60
	v_accvgpr_read_b32 v83, a61
	v_accvgpr_read_b32 v84, a62
	v_accvgpr_read_b32 v85, a63
	s_lshl_b32 s10, s5, 12
	s_cmp_lt_u32 s5, 0x800
	s_cselect_b64 s[34:35], s[48:49], s[50:51]
	s_add_u32 s34, s34, s10
	s_addc_u32 s35, s35, 0
	s_lshr_b32 s10, s10, 1
	s_add_u32 s36, s54, s10
	s_addc_u32 s37, s55, 0
	v_cvt_f32_f16_e32 v154, v70
	v_cvt_f32_f16_e32 v155, v78
	v_add_f32_e32 v154, v154, v155
	v_fmac_f32_e32 v54, v32, v154
	v_cvt_f32_f16_sdwa v156, v70 dst_sel:DWORD dst_unused:UNUSED_PAD src0_sel:WORD_1
	v_cvt_f32_f16_sdwa v157, v78 dst_sel:DWORD dst_unused:UNUSED_PAD src0_sel:WORD_1
	v_add_f32_e32 v156, v156, v157
	v_fmac_f32_e32 v55, v33, v156
	v_cvt_f32_f16_e32 v154, v71
	v_cvt_f32_f16_e32 v155, v79
	v_add_f32_e32 v154, v154, v155
	v_fmac_f32_e32 v56, v34, v154
	v_cvt_f32_f16_sdwa v156, v71 dst_sel:DWORD dst_unused:UNUSED_PAD src0_sel:WORD_1
	v_cvt_f32_f16_sdwa v157, v79 dst_sel:DWORD dst_unused:UNUSED_PAD src0_sel:WORD_1
	v_add_f32_e32 v156, v156, v157
	v_fmac_f32_e32 v57, v35, v156
	v_cvt_f32_f16_e32 v154, v72
	v_cvt_f32_f16_e32 v155, v80
	v_add_f32_e32 v154, v154, v155
	v_fmac_f32_e32 v58, v36, v154
	v_cvt_f32_f16_sdwa v156, v72 dst_sel:DWORD dst_unused:UNUSED_PAD src0_sel:WORD_1
	v_cvt_f32_f16_sdwa v157, v80 dst_sel:DWORD dst_unused:UNUSED_PAD src0_sel:WORD_1
	v_add_f32_e32 v156, v156, v157
	v_fmac_f32_e32 v59, v37, v156
	v_cvt_f32_f16_e32 v154, v73
	v_cvt_f32_f16_e32 v155, v81
	v_add_f32_e32 v154, v154, v155
	v_fmac_f32_e32 v60, v38, v154
	v_cvt_f32_f16_sdwa v156, v73 dst_sel:DWORD dst_unused:UNUSED_PAD src0_sel:WORD_1
	v_cvt_f32_f16_sdwa v157, v81 dst_sel:DWORD dst_unused:UNUSED_PAD src0_sel:WORD_1
	v_add_f32_e32 v156, v156, v157
	v_fmac_f32_e32 v61, v39, v156
	v_cvt_f32_f16_e32 v154, v74
	v_cvt_f32_f16_e32 v155, v82
	v_add_f32_e32 v154, v154, v155
	v_fmac_f32_e32 v62, v40, v154
	v_cvt_f32_f16_sdwa v156, v74 dst_sel:DWORD dst_unused:UNUSED_PAD src0_sel:WORD_1
	v_cvt_f32_f16_sdwa v157, v82 dst_sel:DWORD dst_unused:UNUSED_PAD src0_sel:WORD_1
	v_add_f32_e32 v156, v156, v157
	v_fmac_f32_e32 v63, v41, v156
	v_cvt_f32_f16_e32 v154, v75
	v_cvt_f32_f16_e32 v155, v83
	v_add_f32_e32 v154, v154, v155
	v_fmac_f32_e32 v64, v42, v154
	v_cvt_f32_f16_sdwa v156, v75 dst_sel:DWORD dst_unused:UNUSED_PAD src0_sel:WORD_1
	v_cvt_f32_f16_sdwa v157, v83 dst_sel:DWORD dst_unused:UNUSED_PAD src0_sel:WORD_1
	v_add_f32_e32 v156, v156, v157
	v_fmac_f32_e32 v65, v43, v156
	v_cvt_f32_f16_e32 v154, v76
	v_cvt_f32_f16_e32 v155, v84
	v_add_f32_e32 v154, v154, v155
	v_fmac_f32_e32 v66, v44, v154
	v_cvt_f32_f16_sdwa v156, v76 dst_sel:DWORD dst_unused:UNUSED_PAD src0_sel:WORD_1
	v_cvt_f32_f16_sdwa v157, v84 dst_sel:DWORD dst_unused:UNUSED_PAD src0_sel:WORD_1
	v_add_f32_e32 v156, v156, v157
	v_fmac_f32_e32 v67, v45, v156
	v_cvt_f32_f16_e32 v154, v77
	v_cvt_f32_f16_e32 v155, v85
	v_add_f32_e32 v154, v154, v155
	v_fmac_f32_e32 v68, v46, v154
	v_cvt_f32_f16_sdwa v156, v77 dst_sel:DWORD dst_unused:UNUSED_PAD src0_sel:WORD_1
	v_cvt_f32_f16_sdwa v157, v85 dst_sel:DWORD dst_unused:UNUSED_PAD src0_sel:WORD_1
	v_add_f32_e32 v156, v156, v157
	v_fmac_f32_e32 v69, v47, v156
	global_store_dwordx4 v150, v[54:57], s[34:35] offset:0
	global_store_dwordx4 v150, v[58:61], s[34:35] offset:1024
	global_store_dwordx4 v150, v[62:65], s[34:35] offset:2048
	global_store_dwordx4 v150, v[66:69], s[34:35] offset:3072
	v_mul_f32_e32 v152, v54, v54
	v_mul_f32_e32 v153, v55, v55
	v_fmac_f32_e32 v152, v56, v56
	v_fmac_f32_e32 v153, v57, v57
	v_fmac_f32_e32 v152, v58, v58
	v_fmac_f32_e32 v153, v59, v59
	v_fmac_f32_e32 v152, v60, v60
	v_fmac_f32_e32 v153, v61, v61
	v_fmac_f32_e32 v152, v62, v62
	v_fmac_f32_e32 v153, v63, v63
	v_fmac_f32_e32 v152, v64, v64
	v_fmac_f32_e32 v153, v65, v65
	v_fmac_f32_e32 v152, v66, v66
	v_fmac_f32_e32 v153, v67, v67
	v_fmac_f32_e32 v152, v68, v68
	v_fmac_f32_e32 v153, v69, v69
	v_add_f32_e32 v152, v152, v153
	v_xor_b32_e32 v158, 128, v159
	ds_bpermute_b32 v153, v158, v152
	s_waitcnt lgkmcnt(0)
	v_add_f32_e32 v152, v152, v153
	v_xor_b32_e32 v158, 64, v159
	ds_bpermute_b32 v153, v158, v152
	s_waitcnt lgkmcnt(0)
	v_add_f32_e32 v152, v152, v153
	v_xor_b32_e32 v158, 32, v159
	ds_bpermute_b32 v153, v158, v152
	s_waitcnt lgkmcnt(0)
	v_add_f32_e32 v152, v152, v153
	v_xor_b32_e32 v158, 16, v159
	ds_bpermute_b32 v153, v158, v152
	s_waitcnt lgkmcnt(0)
	v_add_f32_e32 v152, v152, v153
	v_xor_b32_e32 v158, 8, v159
	ds_bpermute_b32 v153, v158, v152
	s_waitcnt lgkmcnt(0)
	v_add_f32_e32 v152, v152, v153
	v_xor_b32_e32 v158, 4, v159
	ds_bpermute_b32 v153, v158, v152
	s_waitcnt lgkmcnt(0)
	v_add_f32_e32 v152, v152, v153
	v_mov_b32_e32 v153, 0x358637bd
	v_fmamk_f32 v152, v152, 0x3a800000, v153
	v_rsq_f32_e32 v152, v152
	s_nop 1
	v_mul_f32_e32 v54, v54, v152
	v_mul_f32_e32 v55, v55, v152
	v_mul_f32_e32 v56, v56, v152
	v_mul_f32_e32 v57, v57, v152
	v_mul_f32_e32 v58, v58, v152
	v_mul_f32_e32 v59, v59, v152
	v_mul_f32_e32 v60, v60, v152
	v_mul_f32_e32 v61, v61, v152
	v_mul_f32_e32 v62, v62, v152
	v_mul_f32_e32 v63, v63, v152
	v_mul_f32_e32 v64, v64, v152
	v_mul_f32_e32 v65, v65, v152
	v_mul_f32_e32 v66, v66, v152
	v_mul_f32_e32 v67, v67, v152
	v_mul_f32_e32 v68, v68, v152
	v_mul_f32_e32 v69, v69, v152
	v_fma_f32 v54, v54, v0, v16
	v_fma_f32 v55, v55, v1, v17
	v_fma_f32 v56, v56, v2, v18
	v_fma_f32 v57, v57, v3, v19
	v_fma_f32 v58, v58, v4, v20
	v_fma_f32 v59, v59, v5, v21
	v_fma_f32 v60, v60, v6, v22
	v_fma_f32 v61, v61, v7, v23
	v_fma_f32 v62, v62, v8, v24
	v_fma_f32 v63, v63, v9, v25
	v_fma_f32 v64, v64, v10, v26
	v_fma_f32 v65, v65, v11, v27
	v_fma_f32 v66, v66, v12, v28
	v_fma_f32 v67, v67, v13, v29
	v_fma_f32 v68, v68, v14, v30
	v_fma_f32 v69, v69, v15, v31
	v_cvt_pk_f16_f32 v70, v54, v55
	v_cvt_pk_f16_f32 v71, v56, v57
	v_cvt_pk_f16_f32 v72, v58, v59
	v_cvt_pk_f16_f32 v73, v60, v61
	v_cvt_pk_f16_f32 v74, v62, v63
	v_cvt_pk_f16_f32 v75, v64, v65
	v_cvt_pk_f16_f32 v76, v66, v67
	v_cvt_pk_f16_f32 v77, v68, v69
	global_store_dwordx2 v151, v[70:71], s[36:37] offset:0
	global_store_dwordx2 v151, v[72:73], s[36:37] offset:512
	global_store_dwordx2 v151, v[74:75], s[36:37] offset:1024
	global_store_dwordx2 v151, v[76:77], s[36:37] offset:1536
	s_add_u32 s5, s5, 1
	s_waitcnt vmcnt(0)
	s_branch .Lr1_done
; #define TIDX tid_opaque()
; DI void row1_phase(const Params& P, int combine_l, int norm_l, int r_begin) {
;   const int lane = TIDX & 63, gw = blockIdx.x * 4 + (TIDX >> 6), nw = gridDim.x * 4;
;   auto load_row = [&](int r, float4 (&xv)[4], h4 (&ya)[4], h4 (&yb)[4]) {
;     if (combine_l < 0) {
;       const float* src = r < TC ? P.ctx + (size_t)r * D : P.x + (size_t)(r - TC) * D;
; #pragma unroll
;       for (int i = 0; i < 4; i++) xv[i] = *(const float4*)(src + i * 256 + lane * 4);
;     ...
;   const int nrows = TA - r_begin;
;   const int r_lo = r_begin + (int)(((long long)gw * nrows) / nw), r_hi = r_begin + (int)(((long long)(gw + 1) * nrows) / nw);
; #pragma unroll 1
;   for (int r = r_lo; r < r_hi; r += 4) {
;     float4 x0[4], x1[4], x2[4], x3[4]; h4 a0[4], b0[4], a1[4], b1[4], a2[4], b2[4], a3[4], b3[4];
;     const int r1 = r + 1, r2 = r + 2, r3 = r + 3;
;     load_row(r, x0, a0, b0);
;     if (r1 < r_hi) load_row(r1, x1, a1, b1);
;     if (r2 < r_hi) load_row(r2, x2, a2, b2);
;     if (r3 < r_hi) load_row(r3, x3, a3, b3);
.Lr1_modeA:
	v_lshrrev_b32_e32 v152, 6, v172
	v_and_b32_e32 v153, 63, v172
	v_readfirstlane_b32 s5, v152
	v_readlane_b32 s4, v253, 0
	v_lshlrev_b32_e32 v150, 4, v153
	v_lshlrev_b32_e32 v151, 3, v153
	v_lshlrev_b32_e32 v159, 2, v153
	s_nop 2
	s_lshl_b32 s4, s4, 2
	s_add_u32 s4, s4, s5
	s_mul_i32 s5, s4, 66
	s_add_u32 s6, s5, 66
	s_add_u32 s52, s90, 0x28cbc700
	s_addc_u32 s53, s91, 0
	s_add_u32 s54, s90, 0xf8bc700
	s_addc_u32 s55, s91, 0
	s_add_u32 s56, s90, 0xce00000
	s_addc_u32 s57, s91, 0
	v_readlane_b32 s48, v255, 7
	v_readlane_b32 s49, v255, 8
	v_readlane_b32 s50, v255, 3
	v_readlane_b32 s51, v255, 4
	v_readlane_b32 s58, v255, 15
	v_readlane_b32 s59, v255, 16
	s_nop 3
	s_sub_u32 s50, s50, 0x800000
	s_subb_u32 s51, s51, 0
	s_mov_b32 s8, -1
	s_mov_b32 s7, s5
	s_cmp_lt_u32 s7, 0x800
	s_cselect_b64 s[60:61], s[48:49], s[50:51]
	s_lshl_b32 s10, s7, 12
	s_add_u32 s60, s60, s10
	s_addc_u32 s61, s61, 0
	global_load_dwordx4 a[0:3], v150, s[60:61] offset:0
	global_load_dwordx4 a[4:7], v150, s[60:61] offset:1024
	global_load_dwordx4 a[8:11], v150, s[60:61] offset:2048
	global_load_dwordx4 a[12:15], v150, s[60:61] offset:3072
	s_add_u32 s7, s7, 1
	s_cmp_lt_u32 s7, 0x800
	s_cselect_b64 s[60:61], s[48:49], s[50:51]
	s_lshl_b32 s10, s7, 12
	s_add_u32 s60, s60, s10
	s_addc_u32 s61, s61, 0
	global_load_dwordx4 a[32:35], v150, s[60:61] offset:0
	global_load_dwordx4 a[36:39], v150, s[60:61] offset:1024
	global_load_dwordx4 a[40:43], v150, s[60:61] offset:2048
	global_load_dwordx4 a[44:47], v150, s[60:61] offset:3072
	s_add_u32 s7, s7, 1
	s_cmp_lt_u32 s7, 0x800
	s_cselect_b64 s[60:61], s[48:49], s[50:51]
	s_lshl_b32 s10, s7, 12
	s_add_u32 s60, s60, s10
	s_addc_u32 s61, s61, 0
	global_load_dwordx4 a[64:67], v150, s[60:61] offset:0
	global_load_dwordx4 a[68:71], v150, s[60:61] offset:1024
	global_load_dwordx4 a[72:75], v150, s[60:61] offset:2048
	global_load_dwordx4 a[76:79], v150, s[60:61] offset:3072
	s_add_u32 s7, s7, 1
	s_cmp_lt_u32 s7, 0x800
	s_cselect_b64 s[60:61], s[48:49], s[50:51]
	s_lshl_b32 s10, s7, 12
	s_add_u32 s60, s60, s10
	s_addc_u32 s61, s61, 0
	global_load_dwordx4 a[96:99], v150, s[60:61] offset:0
	global_load_dwordx4 a[100:103], v150, s[60:61] offset:1024
	global_load_dwordx4 a[104:107], v150, s[60:61] offset:2048
	global_load_dwordx4 a[108:111], v150, s[60:61] offset:3072
	s_add_u32 s7, s7, 1
	s_mov_b32 s98, 15
.Lr1a_loop:
	s_sub_u32 s9, s5, 0x800
	s_lshr_b32 s9, s9, 13
	s_cmp_lt_u32 s5, 0x800
	s_cselect_b32 s9, 8, s9
	s_cmp_eq_u32 s9, s8
	s_cbranch_scc1 .Lr1a_nr1
	s_mov_b32 s8, s9
	s_waitcnt vmcnt(0)
	s_add_u32 s10, s9, 0
	s_mul_i32 s10, s10, 0x6000
	s_add_u32 s38, s56, s10
	s_addc_u32 s39, s57, 0
	global_load_dwordx4 v[54:57], v150, s[58:59] offset:0
	global_load_dwordx4 v[58:61], v150, s[58:59] offset:1024
	global_load_dwordx4 v[62:65], v150, s[58:59] offset:2048
	global_load_dwordx4 v[66:69], v150, s[58:59] offset:3072
	s_add_u32 s44, s38, 0x1000
	s_addc_u32 s45, s39, 0
	global_load_dwordx4 v[70:73], v150, s[44:45] offset:0
	global_load_dwordx4 v[74:77], v150, s[44:45] offset:1024
	global_load_dwordx4 v[78:81], v150, s[44:45] offset:2048
	global_load_dwordx4 v[82:85], v150, s[44:45] offset:3072
	global_load_dwordx4 v[16:19], v150, s[38:39] offset:0
	global_load_dwordx4 v[20:23], v150, s[38:39] offset:1024
	global_load_dwordx4 v[24:27], v150, s[38:39] offset:2048
	global_load_dwordx4 v[28:31], v150, s[38:39] offset:3072
	s_waitcnt vmcnt(0)
	v_add_f32_e32 v70, 1.0, v70
	v_add_f32_e32 v71, 1.0, v71
	v_add_f32_e32 v72, 1.0, v72
	v_add_f32_e32 v73, 1.0, v73
	v_add_f32_e32 v74, 1.0, v74
	v_add_f32_e32 v75, 1.0, v75
	v_add_f32_e32 v76, 1.0, v76
	v_add_f32_e32 v77, 1.0, v77
	v_add_f32_e32 v78, 1.0, v78
	v_add_f32_e32 v79, 1.0, v79
	v_add_f32_e32 v80, 1.0, v80
	v_add_f32_e32 v81, 1.0, v81
	v_add_f32_e32 v82, 1.0, v82
	v_add_f32_e32 v83, 1.0, v83
	v_add_f32_e32 v84, 1.0, v84
	v_add_f32_e32 v85, 1.0, v85
	v_mul_f32_e32 v0, v54, v70
	v_mul_f32_e32 v1, v55, v71
	v_mul_f32_e32 v2, v56, v72
	v_mul_f32_e32 v3, v57, v73
	v_mul_f32_e32 v4, v58, v74
	v_mul_f32_e32 v5, v59, v75
	v_mul_f32_e32 v6, v60, v76
	v_mul_f32_e32 v7, v61, v77
	v_mul_f32_e32 v8, v62, v78
	v_mul_f32_e32 v9, v63, v79
	v_mul_f32_e32 v10, v64, v80
	v_mul_f32_e32 v11, v65, v81
	v_mul_f32_e32 v12, v66, v82
	v_mul_f32_e32 v13, v67, v83
	v_mul_f32_e32 v14, v68, v84
	v_mul_f32_e32 v15, v69, v85
; DI void row1_phase(const Params& P, int combine_l, int norm_l, int r_begin) {
;     ...
;   auto load_row = [&](int r, float4 (&xv)[4], h4 (&ya)[4], h4 (&yb)[4]) {
;     if (combine_l < 0) {
;       const float* src = r < TC ? P.ctx + (size_t)r * D : P.x + (size_t)(r - TC) * D;
; #pragma unroll
;       for (int i = 0; i < 4; i++) xv[i] = *(const float4*)(src + i * 256 + lane * 4);
;     ...
;       float ss = 0.f;
; #pragma unroll
;       for (int i = 0; i < 4; i++) ss += xv[i].x * xv[i].x + xv[i].y * xv[i].y + xv[i].z * xv[i].z + xv[i].w * xv[i].w;
;       ss = wave_sum(ss);
;       const float rstd = rsqrtf(ss * (1.f / 1024.f) + EPS);
;       const float* g = P.norm1_g + norm_l * 1024;
;       const float* sh = P.mod + (size_t)(norm_l * 9 + n) * 6144; const float* sc = sh + 1024;
; #pragma unroll
;       for (int i = 0; i < 4; i++) {
;         int c = i * 256 + lane * 4;
;         float4 gg = *(const float4*)(g + c), s1 = *(const float4*)(sc + c), s0 = *(const float4*)(sh + c);
;         h4 o;
;         o[0] = (half_t)(xv[i].x * rstd * gg.x * (1.f + s1.x) + s0.x); o[1] = (half_t)(xv[i].y * rstd * gg.y * (1.f + s1.y) + s0.y);
;         o[2] = (half_t)(xv[i].z * rstd * gg.z * (1.f + s1.z) + s0.z); o[3] = (half_t)(xv[i].w * rstd * gg.w * (1.f + s1.w) + s0.w);
;         *(h4*)(P.hx + (size_t)r * D + c) = o;
;       }
.Lr1a_nr1:
	s_waitcnt vmcnt(16)
	v_accvgpr_read_b32 v54, a0
	v_accvgpr_read_b32 v55, a1
	v_accvgpr_read_b32 v56, a2
	v_accvgpr_read_b32 v57, a3
	v_accvgpr_read_b32 v58, a4
	v_accvgpr_read_b32 v59, a5
	v_accvgpr_read_b32 v60, a6
	v_accvgpr_read_b32 v61, a7
	v_accvgpr_read_b32 v62, a8
	v_accvgpr_read_b32 v63, a9
	v_accvgpr_read_b32 v64, a10
	v_accvgpr_read_b32 v65, a11
	v_accvgpr_read_b32 v66, a12
	v_accvgpr_read_b32 v67, a13
	v_accvgpr_read_b32 v68, a14
	v_accvgpr_read_b32 v69, a15
	s_lshl_b32 s10, s5, 12
	s_lshr_b32 s10, s10, 1
	s_add_u32 s36, s54, s10
	s_addc_u32 s37, s55, 0
	s_cmp_lt_u32 s7, 0x800
	s_cselect_b64 s[60:61], s[48:49], s[50:51]
	s_lshl_b32 s10, s7, 12
	s_add_u32 s60, s60, s10
	s_addc_u32 s61, s61, 0
	global_load_dwordx4 a[0:3], v150, s[60:61] offset:0
	global_load_dwordx4 a[4:7], v150, s[60:61] offset:1024
	global_load_dwordx4 a[8:11], v150, s[60:61] offset:2048
	global_load_dwordx4 a[12:15], v150, s[60:61] offset:3072
	s_add_u32 s7, s7, 1
	v_mul_f32_e32 v152, v54, v54
	v_mul_f32_e32 v153, v55, v55
	v_fmac_f32_e32 v152, v56, v56
	v_fmac_f32_e32 v153, v57, v57
	v_fmac_f32_e32 v152, v58, v58
	v_fmac_f32_e32 v153, v59, v59
	v_fmac_f32_e32 v152, v60, v60
	v_fmac_f32_e32 v153, v61, v61
	v_fmac_f32_e32 v152, v62, v62
	v_fmac_f32_e32 v153, v63, v63
	v_fmac_f32_e32 v152, v64, v64
	v_fmac_f32_e32 v153, v65, v65
	v_fmac_f32_e32 v152, v66, v66
	v_fmac_f32_e32 v153, v67, v67
	v_fmac_f32_e32 v152, v68, v68
	v_fmac_f32_e32 v153, v69, v69
	v_add_f32_e32 v152, v152, v153
	v_xor_b32_e32 v158, 128, v159
	ds_bpermute_b32 v153, v158, v152
	s_waitcnt lgkmcnt(0)
	v_add_f32_e32 v152, v152, v153
	v_xor_b32_e32 v158, 64, v159
	ds_bpermute_b32 v153, v158, v152
	s_waitcnt lgkmcnt(0)
	v_add_f32_e32 v152, v152, v153
	v_xor_b32_e32 v158, 32, v159
	ds_bpermute_b32 v153, v158, v152
	s_waitcnt lgkmcnt(0)
	v_add_f32_e32 v152, v152, v153
	v_xor_b32_e32 v158, 16, v159
	ds_bpermute_b32 v153, v158, v152
	s_waitcnt lgkmcnt(0)
	v_add_f32_e32 v152, v152, v153
	v_xor_b32_e32 v158, 8, v159
	ds_bpermute_b32 v153, v158, v152
	s_waitcnt lgkmcnt(0)
	v_add_f32_e32 v152, v152, v153
	v_xor_b32_e32 v158, 4, v159
	ds_bpermute_b32 v153, v158, v152
	s_waitcnt lgkmcnt(0)
	v_add_f32_e32 v152, v152, v153
	v_mov_b32_e32 v153, 0x358637bd
	v_fmamk_f32 v152, v152, 0x3a800000, v153
	v_rsq_f32_e32 v152, v152
	s_nop 1
	v_mul_f32_e32 v54, v54, v152
	v_mul_f32_e32 v55, v55, v152
	v_mul_f32_e32 v56, v56, v152
	v_mul_f32_e32 v57, v57, v152
	v_mul_f32_e32 v58, v58, v152
	v_mul_f32_e32 v59, v59, v152
	v_mul_f32_e32 v60, v60, v152
	v_mul_f32_e32 v61, v61, v152
	v_mul_f32_e32 v62, v62, v152
	v_mul_f32_e32 v63, v63, v152
	v_mul_f32_e32 v64, v64, v152
	v_mul_f32_e32 v65, v65, v152
	v_mul_f32_e32 v66, v66, v152
	v_mul_f32_e32 v67, v67, v152
	v_mul_f32_e32 v68, v68, v152
	v_mul_f32_e32 v69, v69, v152
	v_fma_f32 v54, v54, v0, v16
	v_fma_f32 v55, v55, v1, v17
	v_fma_f32 v56, v56, v2, v18
	v_fma_f32 v57, v57, v3, v19
	v_fma_f32 v58, v58, v4, v20
	v_fma_f32 v59, v59, v5, v21
	v_fma_f32 v60, v60, v6, v22
	v_fma_f32 v61, v61, v7, v23
	v_fma_f32 v62, v62, v8, v24
	v_fma_f32 v63, v63, v9, v25
	v_fma_f32 v64, v64, v10, v26
	v_fma_f32 v65, v65, v11, v27
	v_fma_f32 v66, v66, v12, v28
	v_fma_f32 v67, v67, v13, v29
	v_fma_f32 v68, v68, v14, v30
	v_fma_f32 v69, v69, v15, v31
	v_cvt_pk_f16_f32 v70, v54, v55
	v_cvt_pk_f16_f32 v71, v56, v57
	v_cvt_pk_f16_f32 v72, v58, v59
	v_cvt_pk_f16_f32 v73, v60, v61
	v_cvt_pk_f16_f32 v74, v62, v63
	v_cvt_pk_f16_f32 v75, v64, v65
	v_cvt_pk_f16_f32 v76, v66, v67
	v_cvt_pk_f16_f32 v77, v68, v69
	global_store_dwordx2 v151, v[70:71], s[36:37] offset:0
	global_store_dwordx2 v151, v[72:73], s[36:37] offset:512
	global_store_dwordx2 v151, v[74:75], s[36:37] offset:1024
	global_store_dwordx2 v151, v[76:77], s[36:37] offset:1536
	s_add_u32 s5, s5, 1
	s_sub_u32 s9, s5, 0x800
	s_lshr_b32 s9, s9, 13
	s_cmp_lt_u32 s5, 0x800
	s_cselect_b32 s9, 8, s9
	s_cmp_eq_u32 s9, s8
	s_cbranch_scc1 .Lr1a_nr2
	s_mov_b32 s8, s9
	s_waitcnt vmcnt(0)
	s_add_u32 s10, s9, 0
	s_mul_i32 s10, s10, 0x6000
	s_add_u32 s38, s56, s10
	s_addc_u32 s39, s57, 0
	global_load_dwordx4 v[54:57], v150, s[58:59] offset:0
	global_load_dwordx4 v[58:61], v150, s[58:59] offset:1024
	global_load_dwordx4 v[62:65], v150, s[58:59] offset:2048
	global_load_dwordx4 v[66:69], v150, s[58:59] offset:3072
	s_add_u32 s44, s38, 0x1000
	s_addc_u32 s45, s39, 0
	global_load_dwordx4 v[70:73], v150, s[44:45] offset:0
	global_load_dwordx4 v[74:77], v150, s[44:45] offset:1024
	global_load_dwordx4 v[78:81], v150, s[44:45] offset:2048
	global_load_dwordx4 v[82:85], v150, s[44:45] offset:3072
	global_load_dwordx4 v[16:19], v150, s[38:39] offset:0
	global_load_dwordx4 v[20:23], v150, s[38:39] offset:1024
	global_load_dwordx4 v[24:27], v150, s[38:39] offset:2048
	global_load_dwordx4 v[28:31], v150, s[38:39] offset:3072
	s_waitcnt vmcnt(0)
	v_add_f32_e32 v70, 1.0, v70
	v_add_f32_e32 v71, 1.0, v71
	v_add_f32_e32 v72, 1.0, v72
	v_add_f32_e32 v73, 1.0, v73
	v_add_f32_e32 v74, 1.0, v74
	v_add_f32_e32 v75, 1.0, v75
	v_add_f32_e32 v76, 1.0, v76
	v_add_f32_e32 v77, 1.0, v77
	v_add_f32_e32 v78, 1.0, v78
	v_add_f32_e32 v79, 1.0, v79
	v_add_f32_e32 v80, 1.0, v80
	v_add_f32_e32 v81, 1.0, v81
	v_add_f32_e32 v82, 1.0, v82
	v_add_f32_e32 v83, 1.0, v83
	v_add_f32_e32 v84, 1.0, v84
	v_add_f32_e32 v85, 1.0, v85
	v_mul_f32_e32 v0, v54, v70
	v_mul_f32_e32 v1, v55, v71
	v_mul_f32_e32 v2, v56, v72
	v_mul_f32_e32 v3, v57, v73
	v_mul_f32_e32 v4, v58, v74
	v_mul_f32_e32 v5, v59, v75
	v_mul_f32_e32 v6, v60, v76
	v_mul_f32_e32 v7, v61, v77
	v_mul_f32_e32 v8, v62, v78
	v_mul_f32_e32 v9, v63, v79
	v_mul_f32_e32 v10, v64, v80
	v_mul_f32_e32 v11, v65, v81
	v_mul_f32_e32 v12, v66, v82
	v_mul_f32_e32 v13, v67, v83
	v_mul_f32_e32 v14, v68, v84
	v_mul_f32_e32 v15, v69, v85
; DI void row1_phase(const Params& P, int combine_l, int norm_l, int r_begin) {
;     ...
;   auto load_row = [&](int r, float4 (&xv)[4], h4 (&ya)[4], h4 (&yb)[4]) {
;     if (combine_l < 0) {
;       const float* src = r < TC ? P.ctx + (size_t)r * D : P.x + (size_t)(r - TC) * D;
; #pragma unroll
;       for (int i = 0; i < 4; i++) xv[i] = *(const float4*)(src + i * 256 + lane * 4);
;     ...
;       float ss = 0.f;
; #pragma unroll
;       for (int i = 0; i < 4; i++) ss += xv[i].x * xv[i].x + xv[i].y * xv[i].y + xv[i].z * xv[i].z + xv[i].w * xv[i].w;
;       ss = wave_sum(ss);
;       const float rstd = rsqrtf(ss * (1.f / 1024.f) + EPS);
;       const float* g = P.norm1_g + norm_l * 1024;
;       const float* sh = P.mod + (size_t)(norm_l * 9 + n) * 6144; const float* sc = sh + 1024;
; #pragma unroll
;       for (int i = 0; i < 4; i++) {
;         int c = i * 256 + lane * 4;
;         float4 gg = *(const float4*)(g + c), s1 = *(const float4*)(sc + c), s0 = *(const float4*)(sh + c);
;         h4 o;
;         o[0] = (half_t)(xv[i].x * rstd * gg.x * (1.f + s1.x) + s0.x); o[1] = (half_t)(xv[i].y * rstd * gg.y * (1.f + s1.y) + s0.y);
;         o[2] = (half_t)(xv[i].z * rstd * gg.z * (1.f + s1.z) + s0.z); o[3] = (half_t)(xv[i].w * rstd * gg.w * (1.f + s1.w) + s0.w);
;         *(h4*)(P.hx + (size_t)r * D + c) = o;
;       }
.Lr1a_nr2:
	s_waitcnt vmcnt(16)
	v_accvgpr_read_b32 v54, a32
	v_accvgpr_read_b32 v55, a33
	v_accvgpr_read_b32 v56, a34
	v_accvgpr_read_b32 v57, a35
	v_accvgpr_read_b32 v58, a36
	v_accvgpr_read_b32 v59, a37
	v_accvgpr_read_b32 v60, a38
	v_accvgpr_read_b32 v61, a39
	v_accvgpr_read_b32 v62, a40
	v_accvgpr_read_b32 v63, a41
	v_accvgpr_read_b32 v64, a42
	v_accvgpr_read_b32 v65, a43
	v_accvgpr_read_b32 v66, a44
	v_accvgpr_read_b32 v67, a45
	v_accvgpr_read_b32 v68, a46
	v_accvgpr_read_b32 v69, a47
	s_lshl_b32 s10, s5, 12
	s_lshr_b32 s10, s10, 1
	s_add_u32 s36, s54, s10
	s_addc_u32 s37, s55, 0
	s_cmp_lt_u32 s7, 0x800
	s_cselect_b64 s[60:61], s[48:49], s[50:51]
	s_lshl_b32 s10, s7, 12
	s_add_u32 s60, s60, s10
	s_addc_u32 s61, s61, 0
	global_load_dwordx4 a[32:35], v150, s[60:61] offset:0
	global_load_dwordx4 a[36:39], v150, s[60:61] offset:1024
	global_load_dwordx4 a[40:43], v150, s[60:61] offset:2048
	global_load_dwordx4 a[44:47], v150, s[60:61] offset:3072
	s_add_u32 s7, s7, 1
	v_mul_f32_e32 v152, v54, v54
	v_mul_f32_e32 v153, v55, v55
	v_fmac_f32_e32 v152, v56, v56
	v_fmac_f32_e32 v153, v57, v57
	v_fmac_f32_e32 v152, v58, v58
	v_fmac_f32_e32 v153, v59, v59
	v_fmac_f32_e32 v152, v60, v60
	v_fmac_f32_e32 v153, v61, v61
	v_fmac_f32_e32 v152, v62, v62
	v_fmac_f32_e32 v153, v63, v63
	v_fmac_f32_e32 v152, v64, v64
	v_fmac_f32_e32 v153, v65, v65
	v_fmac_f32_e32 v152, v66, v66
	v_fmac_f32_e32 v153, v67, v67
	v_fmac_f32_e32 v152, v68, v68
	v_fmac_f32_e32 v153, v69, v69
	v_add_f32_e32 v152, v152, v153
	v_xor_b32_e32 v158, 128, v159
	ds_bpermute_b32 v153, v158, v152
	s_waitcnt lgkmcnt(0)
	v_add_f32_e32 v152, v152, v153
	v_xor_b32_e32 v158, 64, v159
	ds_bpermute_b32 v153, v158, v152
	s_waitcnt lgkmcnt(0)
	v_add_f32_e32 v152, v152, v153
	v_xor_b32_e32 v158, 32, v159
	ds_bpermute_b32 v153, v158, v152
	s_waitcnt lgkmcnt(0)
	v_add_f32_e32 v152, v152, v153
	v_xor_b32_e32 v158, 16, v159
	ds_bpermute_b32 v153, v158, v152
	s_waitcnt lgkmcnt(0)
	v_add_f32_e32 v152, v152, v153
	v_xor_b32_e32 v158, 8, v159
	ds_bpermute_b32 v153, v158, v152
	s_waitcnt lgkmcnt(0)
	v_add_f32_e32 v152, v152, v153
	v_xor_b32_e32 v158, 4, v159
	ds_bpermute_b32 v153, v158, v152
	s_waitcnt lgkmcnt(0)
	v_add_f32_e32 v152, v152, v153
	v_mov_b32_e32 v153, 0x358637bd
	v_fmamk_f32 v152, v152, 0x3a800000, v153
	v_rsq_f32_e32 v152, v152
	s_nop 1
	v_mul_f32_e32 v54, v54, v152
	v_mul_f32_e32 v55, v55, v152
	v_mul_f32_e32 v56, v56, v152
	v_mul_f32_e32 v57, v57, v152
	v_mul_f32_e32 v58, v58, v152
	v_mul_f32_e32 v59, v59, v152
	v_mul_f32_e32 v60, v60, v152
	v_mul_f32_e32 v61, v61, v152
	v_mul_f32_e32 v62, v62, v152
	v_mul_f32_e32 v63, v63, v152
	v_mul_f32_e32 v64, v64, v152
	v_mul_f32_e32 v65, v65, v152
	v_mul_f32_e32 v66, v66, v152
	v_mul_f32_e32 v67, v67, v152
	v_mul_f32_e32 v68, v68, v152
	v_mul_f32_e32 v69, v69, v152
	v_fma_f32 v54, v54, v0, v16
	v_fma_f32 v55, v55, v1, v17
	v_fma_f32 v56, v56, v2, v18
	v_fma_f32 v57, v57, v3, v19
	v_fma_f32 v58, v58, v4, v20
	v_fma_f32 v59, v59, v5, v21
	v_fma_f32 v60, v60, v6, v22
	v_fma_f32 v61, v61, v7, v23
	v_fma_f32 v62, v62, v8, v24
	v_fma_f32 v63, v63, v9, v25
	v_fma_f32 v64, v64, v10, v26
	v_fma_f32 v65, v65, v11, v27
	v_fma_f32 v66, v66, v12, v28
	v_fma_f32 v67, v67, v13, v29
	v_fma_f32 v68, v68, v14, v30
	v_fma_f32 v69, v69, v15, v31
	v_cvt_pk_f16_f32 v70, v54, v55
	v_cvt_pk_f16_f32 v71, v56, v57
	v_cvt_pk_f16_f32 v72, v58, v59
	v_cvt_pk_f16_f32 v73, v60, v61
	v_cvt_pk_f16_f32 v74, v62, v63
	v_cvt_pk_f16_f32 v75, v64, v65
	v_cvt_pk_f16_f32 v76, v66, v67
	v_cvt_pk_f16_f32 v77, v68, v69
	global_store_dwordx2 v151, v[70:71], s[36:37] offset:0
	global_store_dwordx2 v151, v[72:73], s[36:37] offset:512
	global_store_dwordx2 v151, v[74:75], s[36:37] offset:1024
	global_store_dwordx2 v151, v[76:77], s[36:37] offset:1536
	s_add_u32 s5, s5, 1
	s_sub_u32 s9, s5, 0x800
	s_lshr_b32 s9, s9, 13
	s_cmp_lt_u32 s5, 0x800
	s_cselect_b32 s9, 8, s9
	s_cmp_eq_u32 s9, s8
	s_cbranch_scc1 .Lr1a_nr3
	s_mov_b32 s8, s9
	s_waitcnt vmcnt(0)
	s_add_u32 s10, s9, 0
	s_mul_i32 s10, s10, 0x6000
	s_add_u32 s38, s56, s10
	s_addc_u32 s39, s57, 0
	global_load_dwordx4 v[54:57], v150, s[58:59] offset:0
	global_load_dwordx4 v[58:61], v150, s[58:59] offset:1024
	global_load_dwordx4 v[62:65], v150, s[58:59] offset:2048
	global_load_dwordx4 v[66:69], v150, s[58:59] offset:3072
	s_add_u32 s44, s38, 0x1000
	s_addc_u32 s45, s39, 0
	global_load_dwordx4 v[70:73], v150, s[44:45] offset:0
	global_load_dwordx4 v[74:77], v150, s[44:45] offset:1024
	global_load_dwordx4 v[78:81], v150, s[44:45] offset:2048
	global_load_dwordx4 v[82:85], v150, s[44:45] offset:3072
	global_load_dwordx4 v[16:19], v150, s[38:39] offset:0
	global_load_dwordx4 v[20:23], v150, s[38:39] offset:1024
	global_load_dwordx4 v[24:27], v150, s[38:39] offset:2048
	global_load_dwordx4 v[28:31], v150, s[38:39] offset:3072
	s_waitcnt vmcnt(0)
	v_add_f32_e32 v70, 1.0, v70
	v_add_f32_e32 v71, 1.0, v71
	v_add_f32_e32 v72, 1.0, v72
	v_add_f32_e32 v73, 1.0, v73
	v_add_f32_e32 v74, 1.0, v74
	v_add_f32_e32 v75, 1.0, v75
	v_add_f32_e32 v76, 1.0, v76
	v_add_f32_e32 v77, 1.0, v77
	v_add_f32_e32 v78, 1.0, v78
	v_add_f32_e32 v79, 1.0, v79
	v_add_f32_e32 v80, 1.0, v80
	v_add_f32_e32 v81, 1.0, v81
	v_add_f32_e32 v82, 1.0, v82
	v_add_f32_e32 v83, 1.0, v83
	v_add_f32_e32 v84, 1.0, v84
	v_add_f32_e32 v85, 1.0, v85
	v_mul_f32_e32 v0, v54, v70
	v_mul_f32_e32 v1, v55, v71
	v_mul_f32_e32 v2, v56, v72
	v_mul_f32_e32 v3, v57, v73
	v_mul_f32_e32 v4, v58, v74
	v_mul_f32_e32 v5, v59, v75
	v_mul_f32_e32 v6, v60, v76
	v_mul_f32_e32 v7, v61, v77
	v_mul_f32_e32 v8, v62, v78
	v_mul_f32_e32 v9, v63, v79
	v_mul_f32_e32 v10, v64, v80
	v_mul_f32_e32 v11, v65, v81
	v_mul_f32_e32 v12, v66, v82
	v_mul_f32_e32 v13, v67, v83
	v_mul_f32_e32 v14, v68, v84
	v_mul_f32_e32 v15, v69, v85
; DI void row1_phase(const Params& P, int combine_l, int norm_l, int r_begin) {
;     ...
;   auto load_row = [&](int r, float4 (&xv)[4], h4 (&ya)[4], h4 (&yb)[4]) {
;     if (combine_l < 0) {
;       const float* src = r < TC ? P.ctx + (size_t)r * D : P.x + (size_t)(r - TC) * D;
; #pragma unroll
;       for (int i = 0; i < 4; i++) xv[i] = *(const float4*)(src + i * 256 + lane * 4);
;     ...
;       float ss = 0.f;
; #pragma unroll
;       for (int i = 0; i < 4; i++) ss += xv[i].x * xv[i].x + xv[i].y * xv[i].y + xv[i].z * xv[i].z + xv[i].w * xv[i].w;
;       ss = wave_sum(ss);
;       const float rstd = rsqrtf(ss * (1.f / 1024.f) + EPS);
;       const float* g = P.norm1_g + norm_l * 1024;
;       const float* sh = P.mod + (size_t)(norm_l * 9 + n) * 6144; const float* sc = sh + 1024;
; #pragma unroll
;       for (int i = 0; i < 4; i++) {
;         int c = i * 256 + lane * 4;
;         float4 gg = *(const float4*)(g + c), s1 = *(const float4*)(sc + c), s0 = *(const float4*)(sh + c);
;         h4 o;
;         o[0] = (half_t)(xv[i].x * rstd * gg.x * (1.f + s1.x) + s0.x); o[1] = (half_t)(xv[i].y * rstd * gg.y * (1.f + s1.y) + s0.y);
;         o[2] = (half_t)(xv[i].z * rstd * gg.z * (1.f + s1.z) + s0.z); o[3] = (half_t)(xv[i].w * rstd * gg.w * (1.f + s1.w) + s0.w);
;         *(h4*)(P.hx + (size_t)r * D + c) = o;
;       }
.Lr1a_nr3:
	s_waitcnt vmcnt(16)
	v_accvgpr_read_b32 v54, a64
	v_accvgpr_read_b32 v55, a65
	v_accvgpr_read_b32 v56, a66
	v_accvgpr_read_b32 v57, a67
	v_accvgpr_read_b32 v58, a68
	v_accvgpr_read_b32 v59, a69
	v_accvgpr_read_b32 v60, a70
	v_accvgpr_read_b32 v61, a71
	v_accvgpr_read_b32 v62, a72
	v_accvgpr_read_b32 v63, a73
	v_accvgpr_read_b32 v64, a74
	v_accvgpr_read_b32 v65, a75
	v_accvgpr_read_b32 v66, a76
	v_accvgpr_read_b32 v67, a77
	v_accvgpr_read_b32 v68, a78
	v_accvgpr_read_b32 v69, a79
	s_lshl_b32 s10, s5, 12
	s_lshr_b32 s10, s10, 1
	s_add_u32 s36, s54, s10
	s_addc_u32 s37, s55, 0
	s_cmp_lt_u32 s7, 0x800
	s_cselect_b64 s[60:61], s[48:49], s[50:51]
	s_lshl_b32 s10, s7, 12
	s_add_u32 s60, s60, s10
	s_addc_u32 s61, s61, 0
	global_load_dwordx4 a[64:67], v150, s[60:61] offset:0
	global_load_dwordx4 a[68:71], v150, s[60:61] offset:1024
	global_load_dwordx4 a[72:75], v150, s[60:61] offset:2048
	global_load_dwordx4 a[76:79], v150, s[60:61] offset:3072
	s_add_u32 s7, s7, 1
	v_mul_f32_e32 v152, v54, v54
	v_mul_f32_e32 v153, v55, v55
	v_fmac_f32_e32 v152, v56, v56
	v_fmac_f32_e32 v153, v57, v57
	v_fmac_f32_e32 v152, v58, v58
	v_fmac_f32_e32 v153, v59, v59
	v_fmac_f32_e32 v152, v60, v60
	v_fmac_f32_e32 v153, v61, v61
	v_fmac_f32_e32 v152, v62, v62
	v_fmac_f32_e32 v153, v63, v63
	v_fmac_f32_e32 v152, v64, v64
	v_fmac_f32_e32 v153, v65, v65
	v_fmac_f32_e32 v152, v66, v66
	v_fmac_f32_e32 v153, v67, v67
	v_fmac_f32_e32 v152, v68, v68
	v_fmac_f32_e32 v153, v69, v69
	v_add_f32_e32 v152, v152, v153
	v_xor_b32_e32 v158, 128, v159
	ds_bpermute_b32 v153, v158, v152
	s_waitcnt lgkmcnt(0)
	v_add_f32_e32 v152, v152, v153
	v_xor_b32_e32 v158, 64, v159
	ds_bpermute_b32 v153, v158, v152
	s_waitcnt lgkmcnt(0)
	v_add_f32_e32 v152, v152, v153
	v_xor_b32_e32 v158, 32, v159
	ds_bpermute_b32 v153, v158, v152
	s_waitcnt lgkmcnt(0)
	v_add_f32_e32 v152, v152, v153
	v_xor_b32_e32 v158, 16, v159
	ds_bpermute_b32 v153, v158, v152
	s_waitcnt lgkmcnt(0)
	v_add_f32_e32 v152, v152, v153
	v_xor_b32_e32 v158, 8, v159
	ds_bpermute_b32 v153, v158, v152
	s_waitcnt lgkmcnt(0)
	v_add_f32_e32 v152, v152, v153
	v_xor_b32_e32 v158, 4, v159
	ds_bpermute_b32 v153, v158, v152
	s_waitcnt lgkmcnt(0)
	v_add_f32_e32 v152, v152, v153
	v_mov_b32_e32 v153, 0x358637bd
	v_fmamk_f32 v152, v152, 0x3a800000, v153
	v_rsq_f32_e32 v152, v152
	s_nop 1
	v_mul_f32_e32 v54, v54, v152
	v_mul_f32_e32 v55, v55, v152
	v_mul_f32_e32 v56, v56, v152
	v_mul_f32_e32 v57, v57, v152
	v_mul_f32_e32 v58, v58, v152
	v_mul_f32_e32 v59, v59, v152
	v_mul_f32_e32 v60, v60, v152
	v_mul_f32_e32 v61, v61, v152
	v_mul_f32_e32 v62, v62, v152
	v_mul_f32_e32 v63, v63, v152
	v_mul_f32_e32 v64, v64, v152
	v_mul_f32_e32 v65, v65, v152
	v_mul_f32_e32 v66, v66, v152
	v_mul_f32_e32 v67, v67, v152
	v_mul_f32_e32 v68, v68, v152
	v_mul_f32_e32 v69, v69, v152
	v_fma_f32 v54, v54, v0, v16
	v_fma_f32 v55, v55, v1, v17
	v_fma_f32 v56, v56, v2, v18
	v_fma_f32 v57, v57, v3, v19
	v_fma_f32 v58, v58, v4, v20
	v_fma_f32 v59, v59, v5, v21
	v_fma_f32 v60, v60, v6, v22
	v_fma_f32 v61, v61, v7, v23
	v_fma_f32 v62, v62, v8, v24
	v_fma_f32 v63, v63, v9, v25
	v_fma_f32 v64, v64, v10, v26
	v_fma_f32 v65, v65, v11, v27
	v_fma_f32 v66, v66, v12, v28
	v_fma_f32 v67, v67, v13, v29
	v_fma_f32 v68, v68, v14, v30
	v_fma_f32 v69, v69, v15, v31
	v_cvt_pk_f16_f32 v70, v54, v55
	v_cvt_pk_f16_f32 v71, v56, v57
	v_cvt_pk_f16_f32 v72, v58, v59
	v_cvt_pk_f16_f32 v73, v60, v61
	v_cvt_pk_f16_f32 v74, v62, v63
	v_cvt_pk_f16_f32 v75, v64, v65
	v_cvt_pk_f16_f32 v76, v66, v67
	v_cvt_pk_f16_f32 v77, v68, v69
	global_store_dwordx2 v151, v[70:71], s[36:37] offset:0
	global_store_dwordx2 v151, v[72:73], s[36:37] offset:512
	global_store_dwordx2 v151, v[74:75], s[36:37] offset:1024
	global_store_dwordx2 v151, v[76:77], s[36:37] offset:1536
	s_add_u32 s5, s5, 1
	s_sub_u32 s9, s5, 0x800
	s_lshr_b32 s9, s9, 13
	s_cmp_lt_u32 s5, 0x800
	s_cselect_b32 s9, 8, s9
	s_cmp_eq_u32 s9, s8
	s_cbranch_scc1 .Lr1a_nr4
	s_mov_b32 s8, s9
	s_waitcnt vmcnt(0)
	s_add_u32 s10, s9, 0
	s_mul_i32 s10, s10, 0x6000
	s_add_u32 s38, s56, s10
	s_addc_u32 s39, s57, 0
	global_load_dwordx4 v[54:57], v150, s[58:59] offset:0
	global_load_dwordx4 v[58:61], v150, s[58:59] offset:1024
	global_load_dwordx4 v[62:65], v150, s[58:59] offset:2048
	global_load_dwordx4 v[66:69], v150, s[58:59] offset:3072
	s_add_u32 s44, s38, 0x1000
	s_addc_u32 s45, s39, 0
	global_load_dwordx4 v[70:73], v150, s[44:45] offset:0
	global_load_dwordx4 v[74:77], v150, s[44:45] offset:1024
	global_load_dwordx4 v[78:81], v150, s[44:45] offset:2048
	global_load_dwordx4 v[82:85], v150, s[44:45] offset:3072
	global_load_dwordx4 v[16:19], v150, s[38:39] offset:0
	global_load_dwordx4 v[20:23], v150, s[38:39] offset:1024
	global_load_dwordx4 v[24:27], v150, s[38:39] offset:2048
	global_load_dwordx4 v[28:31], v150, s[38:39] offset:3072
	s_waitcnt vmcnt(0)
	v_add_f32_e32 v70, 1.0, v70
	v_add_f32_e32 v71, 1.0, v71
	v_add_f32_e32 v72, 1.0, v72
	v_add_f32_e32 v73, 1.0, v73
	v_add_f32_e32 v74, 1.0, v74
	v_add_f32_e32 v75, 1.0, v75
	v_add_f32_e32 v76, 1.0, v76
	v_add_f32_e32 v77, 1.0, v77
	v_add_f32_e32 v78, 1.0, v78
	v_add_f32_e32 v79, 1.0, v79
	v_add_f32_e32 v80, 1.0, v80
	v_add_f32_e32 v81, 1.0, v81
	v_add_f32_e32 v82, 1.0, v82
	v_add_f32_e32 v83, 1.0, v83
	v_add_f32_e32 v84, 1.0, v84
	v_add_f32_e32 v85, 1.0, v85
	v_mul_f32_e32 v0, v54, v70
	v_mul_f32_e32 v1, v55, v71
	v_mul_f32_e32 v2, v56, v72
	v_mul_f32_e32 v3, v57, v73
	v_mul_f32_e32 v4, v58, v74
	v_mul_f32_e32 v5, v59, v75
	v_mul_f32_e32 v6, v60, v76
	v_mul_f32_e32 v7, v61, v77
	v_mul_f32_e32 v8, v62, v78
	v_mul_f32_e32 v9, v63, v79
	v_mul_f32_e32 v10, v64, v80
	v_mul_f32_e32 v11, v65, v81
	v_mul_f32_e32 v12, v66, v82
	v_mul_f32_e32 v13, v67, v83
	v_mul_f32_e32 v14, v68, v84
	v_mul_f32_e32 v15, v69, v85
; DI void row1_phase(const Params& P, int combine_l, int norm_l, int r_begin) {
;     ...
;   auto load_row = [&](int r, float4 (&xv)[4], h4 (&ya)[4], h4 (&yb)[4]) {
;     if (combine_l < 0) {
;       const float* src = r < TC ? P.ctx + (size_t)r * D : P.x + (size_t)(r - TC) * D;
; #pragma unroll
;       for (int i = 0; i < 4; i++) xv[i] = *(const float4*)(src + i * 256 + lane * 4);
;     ...
;       float ss = 0.f;
; #pragma unroll
;       for (int i = 0; i < 4; i++) ss += xv[i].x * xv[i].x + xv[i].y * xv[i].y + xv[i].z * xv[i].z + xv[i].w * xv[i].w;
;       ss = wave_sum(ss);
;       const float rstd = rsqrtf(ss * (1.f / 1024.f) + EPS);
;       const float* g = P.norm1_g + norm_l * 1024;
;       const float* sh = P.mod + (size_t)(norm_l * 9 + n) * 6144; const float* sc = sh + 1024;
; #pragma unroll
;       for (int i = 0; i < 4; i++) {
;         int c = i * 256 + lane * 4;
;         float4 gg = *(const float4*)(g + c), s1 = *(const float4*)(sc + c), s0 = *(const float4*)(sh + c);
;         h4 o;
;         o[0] = (half_t)(xv[i].x * rstd * gg.x * (1.f + s1.x) + s0.x); o[1] = (half_t)(xv[i].y * rstd * gg.y * (1.f + s1.y) + s0.y);
;         o[2] = (half_t)(xv[i].z * rstd * gg.z * (1.f + s1.z) + s0.z); o[3] = (half_t)(xv[i].w * rstd * gg.w * (1.f + s1.w) + s0.w);
;         *(h4*)(P.hx + (size_t)r * D + c) = o;
;       }
;     ...
;   for (int r = r_lo; r < r_hi; r += 4) {
.Lr1a_nr4:
	s_waitcnt vmcnt(16)
	v_accvgpr_read_b32 v54, a96
	v_accvgpr_read_b32 v55, a97
	v_accvgpr_read_b32 v56, a98
	v_accvgpr_read_b32 v57, a99
	v_accvgpr_read_b32 v58, a100
	v_accvgpr_read_b32 v59, a101
	v_accvgpr_read_b32 v60, a102
	v_accvgpr_read_b32 v61, a103
	v_accvgpr_read_b32 v62, a104
	v_accvgpr_read_b32 v63, a105
	v_accvgpr_read_b32 v64, a106
	v_accvgpr_read_b32 v65, a107
	v_accvgpr_read_b32 v66, a108
	v_accvgpr_read_b32 v67, a109
	v_accvgpr_read_b32 v68, a110
	v_accvgpr_read_b32 v69, a111
	s_lshl_b32 s10, s5, 12
	s_lshr_b32 s10, s10, 1
	s_add_u32 s36, s54, s10
	s_addc_u32 s37, s55, 0
	s_cmp_lt_u32 s7, 0x800
	s_cselect_b64 s[60:61], s[48:49], s[50:51]
	s_lshl_b32 s10, s7, 12
	s_add_u32 s60, s60, s10
	s_addc_u32 s61, s61, 0
	global_load_dwordx4 a[96:99], v150, s[60:61] offset:0
	global_load_dwordx4 a[100:103], v150, s[60:61] offset:1024
	global_load_dwordx4 a[104:107], v150, s[60:61] offset:2048
	global_load_dwordx4 a[108:111], v150, s[60:61] offset:3072
	s_add_u32 s7, s7, 1
	v_mul_f32_e32 v152, v54, v54
	v_mul_f32_e32 v153, v55, v55
	v_fmac_f32_e32 v152, v56, v56
	v_fmac_f32_e32 v153, v57, v57
	v_fmac_f32_e32 v152, v58, v58
	v_fmac_f32_e32 v153, v59, v59
	v_fmac_f32_e32 v152, v60, v60
	v_fmac_f32_e32 v153, v61, v61
	v_fmac_f32_e32 v152, v62, v62
	v_fmac_f32_e32 v153, v63, v63
	v_fmac_f32_e32 v152, v64, v64
	v_fmac_f32_e32 v153, v65, v65
	v_fmac_f32_e32 v152, v66, v66
	v_fmac_f32_e32 v153, v67, v67
	v_fmac_f32_e32 v152, v68, v68
	v_fmac_f32_e32 v153, v69, v69
	v_add_f32_e32 v152, v152, v153
	v_xor_b32_e32 v158, 128, v159
	ds_bpermute_b32 v153, v158, v152
	s_waitcnt lgkmcnt(0)
	v_add_f32_e32 v152, v152, v153
	v_xor_b32_e32 v158, 64, v159
	ds_bpermute_b32 v153, v158, v152
	s_waitcnt lgkmcnt(0)
	v_add_f32_e32 v152, v152, v153
	v_xor_b32_e32 v158, 32, v159
	ds_bpermute_b32 v153, v158, v152
	s_waitcnt lgkmcnt(0)
	v_add_f32_e32 v152, v152, v153
	v_xor_b32_e32 v158, 16, v159
	ds_bpermute_b32 v153, v158, v152
	s_waitcnt lgkmcnt(0)
	v_add_f32_e32 v152, v152, v153
	v_xor_b32_e32 v158, 8, v159
	ds_bpermute_b32 v153, v158, v152
	s_waitcnt lgkmcnt(0)
	v_add_f32_e32 v152, v152, v153
	v_xor_b32_e32 v158, 4, v159
	ds_bpermute_b32 v153, v158, v152
	s_waitcnt lgkmcnt(0)
	v_add_f32_e32 v152, v152, v153
	v_mov_b32_e32 v153, 0x358637bd
	v_fmamk_f32 v152, v152, 0x3a800000, v153
	v_rsq_f32_e32 v152, v152
	s_nop 1
	v_mul_f32_e32 v54, v54, v152
	v_mul_f32_e32 v55, v55, v152
	v_mul_f32_e32 v56, v56, v152
	v_mul_f32_e32 v57, v57, v152
	v_mul_f32_e32 v58, v58, v152
	v_mul_f32_e32 v59, v59, v152
	v_mul_f32_e32 v60, v60, v152
	v_mul_f32_e32 v61, v61, v152
	v_mul_f32_e32 v62, v62, v152
	v_mul_f32_e32 v63, v63, v152
	v_mul_f32_e32 v64, v64, v152
	v_mul_f32_e32 v65, v65, v152
	v_mul_f32_e32 v66, v66, v152
	v_mul_f32_e32 v67, v67, v152
	v_mul_f32_e32 v68, v68, v152
	v_mul_f32_e32 v69, v69, v152
	v_fma_f32 v54, v54, v0, v16
	v_fma_f32 v55, v55, v1, v17
	v_fma_f32 v56, v56, v2, v18
	v_fma_f32 v57, v57, v3, v19
	v_fma_f32 v58, v58, v4, v20
	v_fma_f32 v59, v59, v5, v21
	v_fma_f32 v60, v60, v6, v22
	v_fma_f32 v61, v61, v7, v23
	v_fma_f32 v62, v62, v8, v24
	v_fma_f32 v63, v63, v9, v25
	v_fma_f32 v64, v64, v10, v26
	v_fma_f32 v65, v65, v11, v27
	v_fma_f32 v66, v66, v12, v28
	v_fma_f32 v67, v67, v13, v29
	v_fma_f32 v68, v68, v14, v30
	v_fma_f32 v69, v69, v15, v31
	v_cvt_pk_f16_f32 v70, v54, v55
	v_cvt_pk_f16_f32 v71, v56, v57
	v_cvt_pk_f16_f32 v72, v58, v59
	v_cvt_pk_f16_f32 v73, v60, v61
	v_cvt_pk_f16_f32 v74, v62, v63
	v_cvt_pk_f16_f32 v75, v64, v65
	v_cvt_pk_f16_f32 v76, v66, v67
	v_cvt_pk_f16_f32 v77, v68, v69
	global_store_dwordx2 v151, v[70:71], s[36:37] offset:0
	global_store_dwordx2 v151, v[72:73], s[36:37] offset:512
	global_store_dwordx2 v151, v[74:75], s[36:37] offset:1024
	global_store_dwordx2 v151, v[76:77], s[36:37] offset:1536
	s_add_u32 s5, s5, 1
	s_sub_u32 s98, s98, 1
	s_cmp_lg_u32 s98, 0
	s_cbranch_scc1 .Lr1a_loop
	s_sub_u32 s9, s5, 0x800
	s_lshr_b32 s9, s9, 13
	s_cmp_lt_u32 s5, 0x800
	s_cselect_b32 s9, 8, s9
	s_cmp_eq_u32 s9, s8
	s_cbranch_scc1 .Lr1a_nr5
	s_mov_b32 s8, s9
	s_waitcnt vmcnt(0)
	s_add_u32 s10, s9, 0
	s_mul_i32 s10, s10, 0x6000
	s_add_u32 s38, s56, s10
	s_addc_u32 s39, s57, 0
	global_load_dwordx4 v[54:57], v150, s[58:59] offset:0
	global_load_dwordx4 v[58:61], v150, s[58:59] offset:1024
	global_load_dwordx4 v[62:65], v150, s[58:59] offset:2048
	global_load_dwordx4 v[66:69], v150, s[58:59] offset:3072
	s_add_u32 s44, s38, 0x1000
	s_addc_u32 s45, s39, 0
	global_load_dwordx4 v[70:73], v150, s[44:45] offset:0
	global_load_dwordx4 v[74:77], v150, s[44:45] offset:1024
	global_load_dwordx4 v[78:81], v150, s[44:45] offset:2048
	global_load_dwordx4 v[82:85], v150, s[44:45] offset:3072
	global_load_dwordx4 v[16:19], v150, s[38:39] offset:0
	global_load_dwordx4 v[20:23], v150, s[38:39] offset:1024
	global_load_dwordx4 v[24:27], v150, s[38:39] offset:2048
	global_load_dwordx4 v[28:31], v150, s[38:39] offset:3072
	s_waitcnt vmcnt(0)
	v_add_f32_e32 v70, 1.0, v70
	v_add_f32_e32 v71, 1.0, v71
	v_add_f32_e32 v72, 1.0, v72
	v_add_f32_e32 v73, 1.0, v73
	v_add_f32_e32 v74, 1.0, v74
	v_add_f32_e32 v75, 1.0, v75
	v_add_f32_e32 v76, 1.0, v76
	v_add_f32_e32 v77, 1.0, v77
	v_add_f32_e32 v78, 1.0, v78
	v_add_f32_e32 v79, 1.0, v79
	v_add_f32_e32 v80, 1.0, v80
	v_add_f32_e32 v81, 1.0, v81
	v_add_f32_e32 v82, 1.0, v82
	v_add_f32_e32 v83, 1.0, v83
	v_add_f32_e32 v84, 1.0, v84
	v_add_f32_e32 v85, 1.0, v85
	v_mul_f32_e32 v0, v54, v70
	v_mul_f32_e32 v1, v55, v71
	v_mul_f32_e32 v2, v56, v72
	v_mul_f32_e32 v3, v57, v73
	v_mul_f32_e32 v4, v58, v74
	v_mul_f32_e32 v5, v59, v75
	v_mul_f32_e32 v6, v60, v76
	v_mul_f32_e32 v7, v61, v77
	v_mul_f32_e32 v8, v62, v78
	v_mul_f32_e32 v9, v63, v79
	v_mul_f32_e32 v10, v64, v80
	v_mul_f32_e32 v11, v65, v81
	v_mul_f32_e32 v12, v66, v82
	v_mul_f32_e32 v13, v67, v83
	v_mul_f32_e32 v14, v68, v84
	v_mul_f32_e32 v15, v69, v85

; DI void row1_phase(const Params& P, int combine_l, int norm_l, int r_begin) {
;     ...
;       float ss = 0.f;
; #pragma unroll
;       for (int i = 0; i < 4; i++) ss += xv[i].x * xv[i].x + xv[i].y * xv[i].y + xv[i].z * xv[i].z + xv[i].w * xv[i].w;
;       ss = wave_sum(ss);
;       const float rstd = rsqrtf(ss * (1.f / 1024.f) + EPS);
;       const float* g = P.norm1_g + norm_l * 1024;
;       const float* sh = P.mod + (size_t)(norm_l * 9 + n) * 6144; const float* sc = sh + 1024;
; #pragma unroll
;       for (int i = 0; i < 4; i++) {
;         int c = i * 256 + lane * 4;
;         float4 gg = *(const float4*)(g + c), s1 = *(const float4*)(sc + c), s0 = *(const float4*)(sh + c);
;         h4 o;
;         o[0] = (half_t)(xv[i].x * rstd * gg.x * (1.f + s1.x) + s0.x); o[1] = (half_t)(xv[i].y * rstd * gg.y * (1.f + s1.y) + s0.y);
;         o[2] = (half_t)(xv[i].z * rstd * gg.z * (1.f + s1.z) + s0.z); o[3] = (half_t)(xv[i].w * rstd * gg.w * (1.f + s1.w) + s0.w);
;         *(h4*)(P.hx + (size_t)r * D + c) = o;
;       }
.Lr1a_nr7:
	s_waitcnt vmcnt(16)
	v_accvgpr_read_b32 v54, a64
	v_accvgpr_read_b32 v55, a65
	v_accvgpr_read_b32 v56, a66
	v_accvgpr_read_b32 v57, a67
	v_accvgpr_read_b32 v58, a68
	v_accvgpr_read_b32 v59, a69
	v_accvgpr_read_b32 v60, a70
	v_accvgpr_read_b32 v61, a71
	v_accvgpr_read_b32 v62, a72
	v_accvgpr_read_b32 v63, a73
	v_accvgpr_read_b32 v64, a74
	v_accvgpr_read_b32 v65, a75
	v_accvgpr_read_b32 v66, a76
	v_accvgpr_read_b32 v67, a77
	v_accvgpr_read_b32 v68, a78
	v_accvgpr_read_b32 v69, a79
	s_lshl_b32 s10, s5, 12
	s_lshr_b32 s10, s10, 1
	s_add_u32 s36, s54, s10
	s_addc_u32 s37, s55, 0
	v_mul_f32_e32 v152, v54, v54
	v_mul_f32_e32 v153, v55, v55
	v_fmac_f32_e32 v152, v56, v56
	v_fmac_f32_e32 v153, v57, v57
	v_fmac_f32_e32 v152, v58, v58
	v_fmac_f32_e32 v153, v59, v59
	v_fmac_f32_e32 v152, v60, v60
	v_fmac_f32_e32 v153, v61, v61
	v_fmac_f32_e32 v152, v62, v62
	v_fmac_f32_e32 v153, v63, v63
	v_fmac_f32_e32 v152, v64, v64
	v_fmac_f32_e32 v153, v65, v65
	v_fmac_f32_e32 v152, v66, v66
	v_fmac_f32_e32 v153, v67, v67
	v_fmac_f32_e32 v152, v68, v68
	v_fmac_f32_e32 v153, v69, v69
	v_add_f32_e32 v152, v152, v153
	v_xor_b32_e32 v158, 128, v159
	ds_bpermute_b32 v153, v158, v152
	s_waitcnt lgkmcnt(0)
	v_add_f32_e32 v152, v152, v153
	v_xor_b32_e32 v158, 64, v159
	ds_bpermute_b32 v153, v158, v152
	s_waitcnt lgkmcnt(0)
	v_add_f32_e32 v152, v152, v153
	v_xor_b32_e32 v158, 32, v159
	ds_bpermute_b32 v153, v158, v152
	s_waitcnt lgkmcnt(0)
	v_add_f32_e32 v152, v152, v153
	v_xor_b32_e32 v158, 16, v159
	ds_bpermute_b32 v153, v158, v152
	s_waitcnt lgkmcnt(0)
	v_add_f32_e32 v152, v152, v153
	v_xor_b32_e32 v158, 8, v159
	ds_bpermute_b32 v153, v158, v152
	s_waitcnt lgkmcnt(0)
	v_add_f32_e32 v152, v152, v153
	v_xor_b32_e32 v158, 4, v159
	ds_bpermute_b32 v153, v158, v152
	s_waitcnt lgkmcnt(0)
	v_add_f32_e32 v152, v152, v153
	v_mov_b32_e32 v153, 0x358637bd
	v_fmamk_f32 v152, v152, 0x3a800000, v153
	v_rsq_f32_e32 v152, v152
	s_nop 1
	v_mul_f32_e32 v54, v54, v152
	v_mul_f32_e32 v55, v55, v152
	v_mul_f32_e32 v56, v56, v152
	v_mul_f32_e32 v57, v57, v152
	v_mul_f32_e32 v58, v58, v152
	v_mul_f32_e32 v59, v59, v152
	v_mul_f32_e32 v60, v60, v152
	v_mul_f32_e32 v61, v61, v152
	v_mul_f32_e32 v62, v62, v152
	v_mul_f32_e32 v63, v63, v152
	v_mul_f32_e32 v64, v64, v152
	v_mul_f32_e32 v65, v65, v152
	v_mul_f32_e32 v66, v66, v152
	v_mul_f32_e32 v67, v67, v152
	v_mul_f32_e32 v68, v68, v152
	v_mul_f32_e32 v69, v69, v152
	v_fma_f32 v54, v54, v0, v16
	v_fma_f32 v55, v55, v1, v17
	v_fma_f32 v56, v56, v2, v18
	v_fma_f32 v57, v57, v3, v19
	v_fma_f32 v58, v58, v4, v20
	v_fma_f32 v59, v59, v5, v21
	v_fma_f32 v60, v60, v6, v22
	v_fma_f32 v61, v61, v7, v23
	v_fma_f32 v62, v62, v8, v24
	v_fma_f32 v63, v63, v9, v25
	v_fma_f32 v64, v64, v10, v26
	v_fma_f32 v65, v65, v11, v27
	v_fma_f32 v66, v66, v12, v28
	v_fma_f32 v67, v67, v13, v29
	v_fma_f32 v68, v68, v14, v30
	v_fma_f32 v69, v69, v15, v31
	v_cvt_pk_f16_f32 v70, v54, v55
	v_cvt_pk_f16_f32 v71, v56, v57
	v_cvt_pk_f16_f32 v72, v58, v59
	v_cvt_pk_f16_f32 v73, v60, v61
	v_cvt_pk_f16_f32 v74, v62, v63
	v_cvt_pk_f16_f32 v75, v64, v65
	v_cvt_pk_f16_f32 v76, v66, v67
	v_cvt_pk_f16_f32 v77, v68, v69
	global_store_dwordx2 v151, v[70:71], s[36:37] offset:0
	global_store_dwordx2 v151, v[72:73], s[36:37] offset:512
	global_store_dwordx2 v151, v[74:75], s[36:37] offset:1024
	global_store_dwordx2 v151, v[76:77], s[36:37] offset:1536
	s_add_u32 s5, s5, 1
	s_sub_u32 s9, s5, 0x800
	s_lshr_b32 s9, s9, 13
	s_cmp_lt_u32 s5, 0x800
	s_cselect_b32 s9, 8, s9
	s_cmp_eq_u32 s9, s8
	s_cbranch_scc1 .Lr1a_nr8
	s_mov_b32 s8, s9
	s_waitcnt vmcnt(0)
	s_add_u32 s10, s9, 0
	s_mul_i32 s10, s10, 0x6000
	s_add_u32 s38, s56, s10
	s_addc_u32 s39, s57, 0
	global_load_dwordx4 v[54:57], v150, s[58:59] offset:0
	global_load_dwordx4 v[58:61], v150, s[58:59] offset:1024
	global_load_dwordx4 v[62:65], v150, s[58:59] offset:2048
	global_load_dwordx4 v[66:69], v150, s[58:59] offset:3072
	s_add_u32 s44, s38, 0x1000
	s_addc_u32 s45, s39, 0
	global_load_dwordx4 v[70:73], v150, s[44:45] offset:0
	global_load_dwordx4 v[74:77], v150, s[44:45] offset:1024
	global_load_dwordx4 v[78:81], v150, s[44:45] offset:2048
	global_load_dwordx4 v[82:85], v150, s[44:45] offset:3072
	global_load_dwordx4 v[16:19], v150, s[38:39] offset:0
	global_load_dwordx4 v[20:23], v150, s[38:39] offset:1024
	global_load_dwordx4 v[24:27], v150, s[38:39] offset:2048
	global_load_dwordx4 v[28:31], v150, s[38:39] offset:3072
	s_waitcnt vmcnt(0)
	v_add_f32_e32 v70, 1.0, v70
	v_add_f32_e32 v71, 1.0, v71
	v_add_f32_e32 v72, 1.0, v72
	v_add_f32_e32 v73, 1.0, v73
	v_add_f32_e32 v74, 1.0, v74
	v_add_f32_e32 v75, 1.0, v75
	v_add_f32_e32 v76, 1.0, v76
	v_add_f32_e32 v77, 1.0, v77
	v_add_f32_e32 v78, 1.0, v78
	v_add_f32_e32 v79, 1.0, v79
	v_add_f32_e32 v80, 1.0, v80
	v_add_f32_e32 v81, 1.0, v81
	v_add_f32_e32 v82, 1.0, v82
	v_add_f32_e32 v83, 1.0, v83
	v_add_f32_e32 v84, 1.0, v84
	v_add_f32_e32 v85, 1.0, v85
	v_mul_f32_e32 v0, v54, v70
	v_mul_f32_e32 v1, v55, v71
	v_mul_f32_e32 v2, v56, v72
	v_mul_f32_e32 v3, v57, v73
	v_mul_f32_e32 v4, v58, v74
	v_mul_f32_e32 v5, v59, v75
	v_mul_f32_e32 v6, v60, v76
	v_mul_f32_e32 v7, v61, v77
	v_mul_f32_e32 v8, v62, v78
	v_mul_f32_e32 v9, v63, v79
	v_mul_f32_e32 v10, v64, v80
	v_mul_f32_e32 v11, v65, v81
	v_mul_f32_e32 v12, v66, v82
	v_mul_f32_e32 v13, v67, v83
	v_mul_f32_e32 v14, v68, v84
	v_mul_f32_e32 v15, v69, v85
; DI void row1_phase(const Params& P, int combine_l, int norm_l, int r_begin) {
;     ...
;       float ss = 0.f;
; #pragma unroll
;       for (int i = 0; i < 4; i++) ss += xv[i].x * xv[i].x + xv[i].y * xv[i].y + xv[i].z * xv[i].z + xv[i].w * xv[i].w;
;       ss = wave_sum(ss);
;       const float rstd = rsqrtf(ss * (1.f / 1024.f) + EPS);
;       const float* g = P.norm1_g + norm_l * 1024;
;       const float* sh = P.mod + (size_t)(norm_l * 9 + n) * 6144; const float* sc = sh + 1024;
; #pragma unroll
;       for (int i = 0; i < 4; i++) {
;         int c = i * 256 + lane * 4;
;         float4 gg = *(const float4*)(g + c), s1 = *(const float4*)(sc + c), s0 = *(const float4*)(sh + c);
;         h4 o;
;         o[0] = (half_t)(xv[i].x * rstd * gg.x * (1.f + s1.x) + s0.x); o[1] = (half_t)(xv[i].y * rstd * gg.y * (1.f + s1.y) + s0.y);
;         o[2] = (half_t)(xv[i].z * rstd * gg.z * (1.f + s1.z) + s0.z); o[3] = (half_t)(xv[i].w * rstd * gg.w * (1.f + s1.w) + s0.w);
;         *(h4*)(P.hx + (size_t)r * D + c) = o;
;       }
.Lr1a_nr8:
	s_waitcnt vmcnt(12)
	v_accvgpr_read_b32 v54, a96
	v_accvgpr_read_b32 v55, a97
	v_accvgpr_read_b32 v56, a98
	v_accvgpr_read_b32 v57, a99
	v_accvgpr_read_b32 v58, a100
	v_accvgpr_read_b32 v59, a101
	v_accvgpr_read_b32 v60, a102
	v_accvgpr_read_b32 v61, a103
	v_accvgpr_read_b32 v62, a104
	v_accvgpr_read_b32 v63, a105
	v_accvgpr_read_b32 v64, a106
	v_accvgpr_read_b32 v65, a107
	v_accvgpr_read_b32 v66, a108
	v_accvgpr_read_b32 v67, a109
	v_accvgpr_read_b32 v68, a110
	v_accvgpr_read_b32 v69, a111
	s_lshl_b32 s10, s5, 12
	s_lshr_b32 s10, s10, 1
	s_add_u32 s36, s54, s10
	s_addc_u32 s37, s55, 0
	v_mul_f32_e32 v152, v54, v54
	v_mul_f32_e32 v153, v55, v55
	v_fmac_f32_e32 v152, v56, v56
	v_fmac_f32_e32 v153, v57, v57
	v_fmac_f32_e32 v152, v58, v58
	v_fmac_f32_e32 v153, v59, v59
	v_fmac_f32_e32 v152, v60, v60
	v_fmac_f32_e32 v153, v61, v61
	v_fmac_f32_e32 v152, v62, v62
	v_fmac_f32_e32 v153, v63, v63
	v_fmac_f32_e32 v152, v64, v64
	v_fmac_f32_e32 v153, v65, v65
	v_fmac_f32_e32 v152, v66, v66
	v_fmac_f32_e32 v153, v67, v67
	v_fmac_f32_e32 v152, v68, v68
	v_fmac_f32_e32 v153, v69, v69
	v_add_f32_e32 v152, v152, v153
	v_xor_b32_e32 v158, 128, v159
	ds_bpermute_b32 v153, v158, v152
	s_waitcnt lgkmcnt(0)
	v_add_f32_e32 v152, v152, v153
	v_xor_b32_e32 v158, 64, v159
	ds_bpermute_b32 v153, v158, v152
	s_waitcnt lgkmcnt(0)
	v_add_f32_e32 v152, v152, v153
	v_xor_b32_e32 v158, 32, v159
	ds_bpermute_b32 v153, v158, v152
	s_waitcnt lgkmcnt(0)
	v_add_f32_e32 v152, v152, v153
	v_xor_b32_e32 v158, 16, v159
	ds_bpermute_b32 v153, v158, v152
	s_waitcnt lgkmcnt(0)
	v_add_f32_e32 v152, v152, v153
	v_xor_b32_e32 v158, 8, v159
	ds_bpermute_b32 v153, v158, v152
	s_waitcnt lgkmcnt(0)
	v_add_f32_e32 v152, v152, v153
	v_xor_b32_e32 v158, 4, v159
	ds_bpermute_b32 v153, v158, v152
	s_waitcnt lgkmcnt(0)
	v_add_f32_e32 v152, v152, v153
	v_mov_b32_e32 v153, 0x358637bd
	v_fmamk_f32 v152, v152, 0x3a800000, v153
	v_rsq_f32_e32 v152, v152
	s_nop 1
	v_mul_f32_e32 v54, v54, v152
	v_mul_f32_e32 v55, v55, v152
	v_mul_f32_e32 v56, v56, v152
	v_mul_f32_e32 v57, v57, v152
	v_mul_f32_e32 v58, v58, v152
	v_mul_f32_e32 v59, v59, v152
	v_mul_f32_e32 v60, v60, v152
	v_mul_f32_e32 v61, v61, v152
	v_mul_f32_e32 v62, v62, v152
	v_mul_f32_e32 v63, v63, v152
	v_mul_f32_e32 v64, v64, v152
	v_mul_f32_e32 v65, v65, v152
	v_mul_f32_e32 v66, v66, v152
	v_mul_f32_e32 v67, v67, v152
	v_mul_f32_e32 v68, v68, v152
	v_mul_f32_e32 v69, v69, v152
	v_fma_f32 v54, v54, v0, v16
	v_fma_f32 v55, v55, v1, v17
	v_fma_f32 v56, v56, v2, v18
	v_fma_f32 v57, v57, v3, v19
	v_fma_f32 v58, v58, v4, v20
	v_fma_f32 v59, v59, v5, v21
	v_fma_f32 v60, v60, v6, v22
	v_fma_f32 v61, v61, v7, v23
	v_fma_f32 v62, v62, v8, v24
	v_fma_f32 v63, v63, v9, v25
	v_fma_f32 v64, v64, v10, v26
	v_fma_f32 v65, v65, v11, v27
	v_fma_f32 v66, v66, v12, v28
	v_fma_f32 v67, v67, v13, v29
	v_fma_f32 v68, v68, v14, v30
	v_fma_f32 v69, v69, v15, v31
	v_cvt_pk_f16_f32 v70, v54, v55
	v_cvt_pk_f16_f32 v71, v56, v57
	v_cvt_pk_f16_f32 v72, v58, v59
	v_cvt_pk_f16_f32 v73, v60, v61
	v_cvt_pk_f16_f32 v74, v62, v63
	v_cvt_pk_f16_f32 v75, v64, v65
	v_cvt_pk_f16_f32 v76, v66, v67
	v_cvt_pk_f16_f32 v77, v68, v69
	global_store_dwordx2 v151, v[70:71], s[36:37] offset:0
	global_store_dwordx2 v151, v[72:73], s[36:37] offset:512
	global_store_dwordx2 v151, v[74:75], s[36:37] offset:1024
	global_store_dwordx2 v151, v[76:77], s[36:37] offset:1536
	s_add_u32 s5, s5, 1
	s_sub_u32 s9, s5, 0x800
	s_lshr_b32 s9, s9, 13
	s_cmp_lt_u32 s5, 0x800
	s_cselect_b32 s9, 8, s9
	s_cmp_eq_u32 s9, s8
	s_cbranch_scc1 .Lr1a_nr9
	s_mov_b32 s8, s9
	s_waitcnt vmcnt(0)
	s_add_u32 s10, s9, 0
	s_mul_i32 s10, s10, 0x6000
	s_add_u32 s38, s56, s10
	s_addc_u32 s39, s57, 0
	global_load_dwordx4 v[54:57], v150, s[58:59] offset:0
	global_load_dwordx4 v[58:61], v150, s[58:59] offset:1024
	global_load_dwordx4 v[62:65], v150, s[58:59] offset:2048
	global_load_dwordx4 v[66:69], v150, s[58:59] offset:3072
	s_add_u32 s44, s38, 0x1000
	s_addc_u32 s45, s39, 0
	global_load_dwordx4 v[70:73], v150, s[44:45] offset:0
	global_load_dwordx4 v[74:77], v150, s[44:45] offset:1024
	global_load_dwordx4 v[78:81], v150, s[44:45] offset:2048
	global_load_dwordx4 v[82:85], v150, s[44:45] offset:3072
	global_load_dwordx4 v[16:19], v150, s[38:39] offset:0
	global_load_dwordx4 v[20:23], v150, s[38:39] offset:1024
	global_load_dwordx4 v[24:27], v150, s[38:39] offset:2048
	global_load_dwordx4 v[28:31], v150, s[38:39] offset:3072
	s_waitcnt vmcnt(0)
	v_add_f32_e32 v70, 1.0, v70
	v_add_f32_e32 v71, 1.0, v71
	v_add_f32_e32 v72, 1.0, v72
	v_add_f32_e32 v73, 1.0, v73
	v_add_f32_e32 v74, 1.0, v74
	v_add_f32_e32 v75, 1.0, v75
	v_add_f32_e32 v76, 1.0, v76
	v_add_f32_e32 v77, 1.0, v77
	v_add_f32_e32 v78, 1.0, v78
	v_add_f32_e32 v79, 1.0, v79
	v_add_f32_e32 v80, 1.0, v80
	v_add_f32_e32 v81, 1.0, v81
	v_add_f32_e32 v82, 1.0, v82
	v_add_f32_e32 v83, 1.0, v83
	v_add_f32_e32 v84, 1.0, v84
	v_add_f32_e32 v85, 1.0, v85
	v_mul_f32_e32 v0, v54, v70
	v_mul_f32_e32 v1, v55, v71
	v_mul_f32_e32 v2, v56, v72
	v_mul_f32_e32 v3, v57, v73
	v_mul_f32_e32 v4, v58, v74
	v_mul_f32_e32 v5, v59, v75
	v_mul_f32_e32 v6, v60, v76
	v_mul_f32_e32 v7, v61, v77
	v_mul_f32_e32 v8, v62, v78
	v_mul_f32_e32 v9, v63, v79
	v_mul_f32_e32 v10, v64, v80
	v_mul_f32_e32 v11, v65, v81
	v_mul_f32_e32 v12, v66, v82
	v_mul_f32_e32 v13, v67, v83
	v_mul_f32_e32 v14, v68, v84
	v_mul_f32_e32 v15, v69, v85
; DI void row1_phase(const Params& P, int combine_l, int norm_l, int r_begin) {
;     ...
;       float ss = 0.f;
; #pragma unroll
;       for (int i = 0; i < 4; i++) ss += xv[i].x * xv[i].x + xv[i].y * xv[i].y + xv[i].z * xv[i].z + xv[i].w * xv[i].w;
;       ss = wave_sum(ss);
;       const float rstd = rsqrtf(ss * (1.f / 1024.f) + EPS);
;       const float* g = P.norm1_g + norm_l * 1024;
;       const float* sh = P.mod + (size_t)(norm_l * 9 + n) * 6144; const float* sc = sh + 1024;
; #pragma unroll
;       for (int i = 0; i < 4; i++) {
;         int c = i * 256 + lane * 4;
;         float4 gg = *(const float4*)(g + c), s1 = *(const float4*)(sc + c), s0 = *(const float4*)(sh + c);
;         h4 o;
;         o[0] = (half_t)(xv[i].x * rstd * gg.x * (1.f + s1.x) + s0.x); o[1] = (half_t)(xv[i].y * rstd * gg.y * (1.f + s1.y) + s0.y);
;         o[2] = (half_t)(xv[i].z * rstd * gg.z * (1.f + s1.z) + s0.z); o[3] = (half_t)(xv[i].w * rstd * gg.w * (1.f + s1.w) + s0.w);
;         *(h4*)(P.hx + (size_t)r * D + c) = o;
;       }
.Lr1a_nr9:
	s_waitcnt vmcnt(8)
	v_accvgpr_read_b32 v54, a0
	v_accvgpr_read_b32 v55, a1
	v_accvgpr_read_b32 v56, a2
	v_accvgpr_read_b32 v57, a3
	v_accvgpr_read_b32 v58, a4
	v_accvgpr_read_b32 v59, a5
	v_accvgpr_read_b32 v60, a6
	v_accvgpr_read_b32 v61, a7
	v_accvgpr_read_b32 v62, a8
	v_accvgpr_read_b32 v63, a9
	v_accvgpr_read_b32 v64, a10
	v_accvgpr_read_b32 v65, a11
	v_accvgpr_read_b32 v66, a12
	v_accvgpr_read_b32 v67, a13
	v_accvgpr_read_b32 v68, a14
	v_accvgpr_read_b32 v69, a15
	s_lshl_b32 s10, s5, 12
	s_lshr_b32 s10, s10, 1
	s_add_u32 s36, s54, s10
	s_addc_u32 s37, s55, 0
	v_mul_f32_e32 v152, v54, v54
	v_mul_f32_e32 v153, v55, v55
	v_fmac_f32_e32 v152, v56, v56
	v_fmac_f32_e32 v153, v57, v57
	v_fmac_f32_e32 v152, v58, v58
	v_fmac_f32_e32 v153, v59, v59
	v_fmac_f32_e32 v152, v60, v60
	v_fmac_f32_e32 v153, v61, v61
	v_fmac_f32_e32 v152, v62, v62
	v_fmac_f32_e32 v153, v63, v63
	v_fmac_f32_e32 v152, v64, v64
	v_fmac_f32_e32 v153, v65, v65
	v_fmac_f32_e32 v152, v66, v66
	v_fmac_f32_e32 v153, v67, v67
	v_fmac_f32_e32 v152, v68, v68
	v_fmac_f32_e32 v153, v69, v69
	v_add_f32_e32 v152, v152, v153
	v_xor_b32_e32 v158, 128, v159
	ds_bpermute_b32 v153, v158, v152
	s_waitcnt lgkmcnt(0)
	v_add_f32_e32 v152, v152, v153
	v_xor_b32_e32 v158, 64, v159
	ds_bpermute_b32 v153, v158, v152
	s_waitcnt lgkmcnt(0)
	v_add_f32_e32 v152, v152, v153
	v_xor_b32_e32 v158, 32, v159
	ds_bpermute_b32 v153, v158, v152
	s_waitcnt lgkmcnt(0)
	v_add_f32_e32 v152, v152, v153
	v_xor_b32_e32 v158, 16, v159
	ds_bpermute_b32 v153, v158, v152
	s_waitcnt lgkmcnt(0)
	v_add_f32_e32 v152, v152, v153
	v_xor_b32_e32 v158, 8, v159
	ds_bpermute_b32 v153, v158, v152
	s_waitcnt lgkmcnt(0)
	v_add_f32_e32 v152, v152, v153
	v_xor_b32_e32 v158, 4, v159
	ds_bpermute_b32 v153, v158, v152
	s_waitcnt lgkmcnt(0)
	v_add_f32_e32 v152, v152, v153
	v_mov_b32_e32 v153, 0x358637bd
	v_fmamk_f32 v152, v152, 0x3a800000, v153
	v_rsq_f32_e32 v152, v152
	s_nop 1
	v_mul_f32_e32 v54, v54, v152
	v_mul_f32_e32 v55, v55, v152
	v_mul_f32_e32 v56, v56, v152
	v_mul_f32_e32 v57, v57, v152
	v_mul_f32_e32 v58, v58, v152
	v_mul_f32_e32 v59, v59, v152
	v_mul_f32_e32 v60, v60, v152
	v_mul_f32_e32 v61, v61, v152
	v_mul_f32_e32 v62, v62, v152
	v_mul_f32_e32 v63, v63, v152
	v_mul_f32_e32 v64, v64, v152
	v_mul_f32_e32 v65, v65, v152
	v_mul_f32_e32 v66, v66, v152
	v_mul_f32_e32 v67, v67, v152
	v_mul_f32_e32 v68, v68, v152
	v_mul_f32_e32 v69, v69, v152
	v_fma_f32 v54, v54, v0, v16
	v_fma_f32 v55, v55, v1, v17
	v_fma_f32 v56, v56, v2, v18
	v_fma_f32 v57, v57, v3, v19
	v_fma_f32 v58, v58, v4, v20
	v_fma_f32 v59, v59, v5, v21
	v_fma_f32 v60, v60, v6, v22
	v_fma_f32 v61, v61, v7, v23
	v_fma_f32 v62, v62, v8, v24
	v_fma_f32 v63, v63, v9, v25
	v_fma_f32 v64, v64, v10, v26
	v_fma_f32 v65, v65, v11, v27
	v_fma_f32 v66, v66, v12, v28
	v_fma_f32 v67, v67, v13, v29
	v_fma_f32 v68, v68, v14, v30
	v_fma_f32 v69, v69, v15, v31
	v_cvt_pk_f16_f32 v70, v54, v55
	v_cvt_pk_f16_f32 v71, v56, v57
	v_cvt_pk_f16_f32 v72, v58, v59
	v_cvt_pk_f16_f32 v73, v60, v61
	v_cvt_pk_f16_f32 v74, v62, v63
	v_cvt_pk_f16_f32 v75, v64, v65
	v_cvt_pk_f16_f32 v76, v66, v67
	v_cvt_pk_f16_f32 v77, v68, v69
	global_store_dwordx2 v151, v[70:71], s[36:37] offset:0
	global_store_dwordx2 v151, v[72:73], s[36:37] offset:512
	global_store_dwordx2 v151, v[74:75], s[36:37] offset:1024
	global_store_dwordx2 v151, v[76:77], s[36:37] offset:1536
	s_add_u32 s5, s5, 1
	s_sub_u32 s9, s5, 0x800
	s_lshr_b32 s9, s9, 13
	s_cmp_lt_u32 s5, 0x800
	s_cselect_b32 s9, 8, s9
	s_cmp_eq_u32 s9, s8
	s_cbranch_scc1 .Lr1a_nr10
	s_mov_b32 s8, s9
	s_waitcnt vmcnt(0)
	s_add_u32 s10, s9, 0
	s_mul_i32 s10, s10, 0x6000
	s_add_u32 s38, s56, s10
	s_addc_u32 s39, s57, 0
	global_load_dwordx4 v[54:57], v150, s[58:59] offset:0
	global_load_dwordx4 v[58:61], v150, s[58:59] offset:1024
	global_load_dwordx4 v[62:65], v150, s[58:59] offset:2048
	global_load_dwordx4 v[66:69], v150, s[58:59] offset:3072
	s_add_u32 s44, s38, 0x1000
	s_addc_u32 s45, s39, 0
	global_load_dwordx4 v[70:73], v150, s[44:45] offset:0
	global_load_dwordx4 v[74:77], v150, s[44:45] offset:1024
	global_load_dwordx4 v[78:81], v150, s[44:45] offset:2048
	global_load_dwordx4 v[82:85], v150, s[44:45] offset:3072
	global_load_dwordx4 v[16:19], v150, s[38:39] offset:0
	global_load_dwordx4 v[20:23], v150, s[38:39] offset:1024
	global_load_dwordx4 v[24:27], v150, s[38:39] offset:2048
	global_load_dwordx4 v[28:31], v150, s[38:39] offset:3072
	s_waitcnt vmcnt(0)
	v_add_f32_e32 v70, 1.0, v70
	v_add_f32_e32 v71, 1.0, v71
	v_add_f32_e32 v72, 1.0, v72
	v_add_f32_e32 v73, 1.0, v73
	v_add_f32_e32 v74, 1.0, v74
	v_add_f32_e32 v75, 1.0, v75
	v_add_f32_e32 v76, 1.0, v76
	v_add_f32_e32 v77, 1.0, v77
	v_add_f32_e32 v78, 1.0, v78
	v_add_f32_e32 v79, 1.0, v79
	v_add_f32_e32 v80, 1.0, v80
	v_add_f32_e32 v81, 1.0, v81
	v_add_f32_e32 v82, 1.0, v82
	v_add_f32_e32 v83, 1.0, v83
	v_add_f32_e32 v84, 1.0, v84
	v_add_f32_e32 v85, 1.0, v85
	v_mul_f32_e32 v0, v54, v70
	v_mul_f32_e32 v1, v55, v71
	v_mul_f32_e32 v2, v56, v72
	v_mul_f32_e32 v3, v57, v73
	v_mul_f32_e32 v4, v58, v74
	v_mul_f32_e32 v5, v59, v75
	v_mul_f32_e32 v6, v60, v76
	v_mul_f32_e32 v7, v61, v77
	v_mul_f32_e32 v8, v62, v78
	v_mul_f32_e32 v9, v63, v79
	v_mul_f32_e32 v10, v64, v80
	v_mul_f32_e32 v11, v65, v81
	v_mul_f32_e32 v12, v66, v82
	v_mul_f32_e32 v13, v67, v83
	v_mul_f32_e32 v14, v68, v84
	v_mul_f32_e32 v15, v69, v85
; DI void row1_phase(const Params& P, int combine_l, int norm_l, int r_begin) {
;     ...
;       float ss = 0.f;
; #pragma unroll
;       for (int i = 0; i < 4; i++) ss += xv[i].x * xv[i].x + xv[i].y * xv[i].y + xv[i].z * xv[i].z + xv[i].w * xv[i].w;
;       ss = wave_sum(ss);
;       const float rstd = rsqrtf(ss * (1.f / 1024.f) + EPS);
;       const float* g = P.norm1_g + norm_l * 1024;
;       const float* sh = P.mod + (size_t)(norm_l * 9 + n) * 6144; const float* sc = sh + 1024;
; #pragma unroll
;       for (int i = 0; i < 4; i++) {
;         int c = i * 256 + lane * 4;
;         float4 gg = *(const float4*)(g + c), s1 = *(const float4*)(sc + c), s0 = *(const float4*)(sh + c);
;         h4 o;
;         o[0] = (half_t)(xv[i].x * rstd * gg.x * (1.f + s1.x) + s0.x); o[1] = (half_t)(xv[i].y * rstd * gg.y * (1.f + s1.y) + s0.y);
;         o[2] = (half_t)(xv[i].z * rstd * gg.z * (1.f + s1.z) + s0.z); o[3] = (half_t)(xv[i].w * rstd * gg.w * (1.f + s1.w) + s0.w);
;         *(h4*)(P.hx + (size_t)r * D + c) = o;
;       }
.Lr1a_nr10:
	s_waitcnt vmcnt(4)
	v_accvgpr_read_b32 v54, a32
	v_accvgpr_read_b32 v55, a33
	v_accvgpr_read_b32 v56, a34
	v_accvgpr_read_b32 v57, a35
	v_accvgpr_read_b32 v58, a36
	v_accvgpr_read_b32 v59, a37
	v_accvgpr_read_b32 v60, a38
	v_accvgpr_read_b32 v61, a39
	v_accvgpr_read_b32 v62, a40
	v_accvgpr_read_b32 v63, a41
	v_accvgpr_read_b32 v64, a42
	v_accvgpr_read_b32 v65, a43
	v_accvgpr_read_b32 v66, a44
	v_accvgpr_read_b32 v67, a45
	v_accvgpr_read_b32 v68, a46
	v_accvgpr_read_b32 v69, a47
	s_lshl_b32 s10, s5, 12
	s_lshr_b32 s10, s10, 1
	s_add_u32 s36, s54, s10
	s_addc_u32 s37, s55, 0
	v_mul_f32_e32 v152, v54, v54
	v_mul_f32_e32 v153, v55, v55
	v_fmac_f32_e32 v152, v56, v56
	v_fmac_f32_e32 v153, v57, v57
	v_fmac_f32_e32 v152, v58, v58
	v_fmac_f32_e32 v153, v59, v59
	v_fmac_f32_e32 v152, v60, v60
	v_fmac_f32_e32 v153, v61, v61
	v_fmac_f32_e32 v152, v62, v62
	v_fmac_f32_e32 v153, v63, v63
	v_fmac_f32_e32 v152, v64, v64
	v_fmac_f32_e32 v153, v65, v65
	v_fmac_f32_e32 v152, v66, v66
	v_fmac_f32_e32 v153, v67, v67
	v_fmac_f32_e32 v152, v68, v68
	v_fmac_f32_e32 v153, v69, v69
	v_add_f32_e32 v152, v152, v153
	v_xor_b32_e32 v158, 128, v159
	ds_bpermute_b32 v153, v158, v152
	s_waitcnt lgkmcnt(0)
	v_add_f32_e32 v152, v152, v153
	v_xor_b32_e32 v158, 64, v159
	ds_bpermute_b32 v153, v158, v152
	s_waitcnt lgkmcnt(0)
	v_add_f32_e32 v152, v152, v153
	v_xor_b32_e32 v158, 32, v159
	ds_bpermute_b32 v153, v158, v152
	s_waitcnt lgkmcnt(0)
	v_add_f32_e32 v152, v152, v153
	v_xor_b32_e32 v158, 16, v159
	ds_bpermute_b32 v153, v158, v152
	s_waitcnt lgkmcnt(0)
	v_add_f32_e32 v152, v152, v153
	v_xor_b32_e32 v158, 8, v159
	ds_bpermute_b32 v153, v158, v152
	s_waitcnt lgkmcnt(0)
	v_add_f32_e32 v152, v152, v153
	v_xor_b32_e32 v158, 4, v159
	ds_bpermute_b32 v153, v158, v152
	s_waitcnt lgkmcnt(0)
	v_add_f32_e32 v152, v152, v153
	v_mov_b32_e32 v153, 0x358637bd
	v_fmamk_f32 v152, v152, 0x3a800000, v153
	v_rsq_f32_e32 v152, v152
	s_nop 1
	v_mul_f32_e32 v54, v54, v152
	v_mul_f32_e32 v55, v55, v152
	v_mul_f32_e32 v56, v56, v152
	v_mul_f32_e32 v57, v57, v152
	v_mul_f32_e32 v58, v58, v152
	v_mul_f32_e32 v59, v59, v152
	v_mul_f32_e32 v60, v60, v152
	v_mul_f32_e32 v61, v61, v152
	v_mul_f32_e32 v62, v62, v152
	v_mul_f32_e32 v63, v63, v152
	v_mul_f32_e32 v64, v64, v152
	v_mul_f32_e32 v65, v65, v152
	v_mul_f32_e32 v66, v66, v152
	v_mul_f32_e32 v67, v67, v152
	v_mul_f32_e32 v68, v68, v152
	v_mul_f32_e32 v69, v69, v152
	v_fma_f32 v54, v54, v0, v16
	v_fma_f32 v55, v55, v1, v17
	v_fma_f32 v56, v56, v2, v18
	v_fma_f32 v57, v57, v3, v19
	v_fma_f32 v58, v58, v4, v20
	v_fma_f32 v59, v59, v5, v21
	v_fma_f32 v60, v60, v6, v22
	v_fma_f32 v61, v61, v7, v23
	v_fma_f32 v62, v62, v8, v24
	v_fma_f32 v63, v63, v9, v25
	v_fma_f32 v64, v64, v10, v26
	v_fma_f32 v65, v65, v11, v27
	v_fma_f32 v66, v66, v12, v28
	v_fma_f32 v67, v67, v13, v29
	v_fma_f32 v68, v68, v14, v30
	v_fma_f32 v69, v69, v15, v31
	v_cvt_pk_f16_f32 v70, v54, v55
	v_cvt_pk_f16_f32 v71, v56, v57
	v_cvt_pk_f16_f32 v72, v58, v59
	v_cvt_pk_f16_f32 v73, v60, v61
	v_cvt_pk_f16_f32 v74, v62, v63
	v_cvt_pk_f16_f32 v75, v64, v65
	v_cvt_pk_f16_f32 v76, v66, v67
	v_cvt_pk_f16_f32 v77, v68, v69
	global_store_dwordx2 v151, v[70:71], s[36:37] offset:0
	global_store_dwordx2 v151, v[72:73], s[36:37] offset:512
	global_store_dwordx2 v151, v[74:75], s[36:37] offset:1024
	global_store_dwordx2 v151, v[76:77], s[36:37] offset:1536
	s_add_u32 s5, s5, 1
	s_waitcnt vmcnt(0)
; DI void row1_phase(const Params& P, int combine_l, int norm_l, int r_begin) {
;     ...
;   const int nrows = TA - r_begin;
;   const int r_lo = r_begin + (int)(((long long)gw * nrows) / nw), r_hi = r_begin + (int)(((long long)(gw + 1) * nrows) / nw);
; #pragma unroll 1
;   for (int r = r_lo; r < r_hi; r += 4) {
.Lr1_done:
	v_mov_b32_e32 v2, v172
	v_mov_b32_e32 v0, v172
	v_readlane_b32 s0, v254, 20
	v_ashrrev_i32_e32 v0, 6, v0
	v_writelane_b32 v255, s2, 26
	v_add_u32_e32 v3, s0, v0
	s_mov_b32 s0, 0
	v_mad_i64_i32 v[0:1], s[0:1], v3, s0, 0
	v_or_b32_e32 v5, s20, v1
	v_mov_b32_e32 v4, v149
	v_writelane_b32 v255, s3, 27
	v_cmp_ne_u64_e32 vcc, 0, v[4:5]
	s_and_saveexec_b64 s[0:1], vcc
	s_xor_b64 s[2:3], exec, s[0:1]
	s_cbranch_execz .LBB0_153
	s_ashr_i32 s4, s20, 31
	v_readlane_b32 s0, v254, 34
	s_add_u32 s0, s0, s4
	s_mov_b32 s5, s4
	s_addc_u32 s1, s20, s4
	s_xor_b64 s[6:7], s[0:1], s[4:5]
	v_cvt_f32_u32_e32 v4, s6
	v_cvt_f32_u32_e32 v5, s7
	s_sub_u32 s5, 0, s6
	s_subb_u32 s8, 0, s7
	v_fmac_f32_e32 v4, 0x4f800000, v5
	v_rcp_f32_e32 v4, v4
	s_nop 0
	v_mul_f32_e32 v4, 0x5f7ffffc, v4
	v_mul_f32_e32 v5, 0x2f800000, v4
	v_trunc_f32_e32 v5, v5
	v_fmac_f32_e32 v4, 0xcf800000, v5
	v_cvt_u32_f32_e32 v5, v5
	v_cvt_u32_f32_e32 v4, v4
	v_readfirstlane_b32 s9, v5
	v_readfirstlane_b32 s0, v4
	s_mul_i32 s1, s5, s9
	s_mul_hi_u32 s11, s5, s0
	s_mul_i32 s10, s8, s0
	s_add_i32 s1, s11, s1
	s_add_i32 s1, s1, s10
	s_mul_i32 s20, s5, s0
	s_mul_i32 s11, s0, s1
	s_mul_hi_u32 s21, s0, s20
	s_mul_hi_u32 s10, s0, s1
	s_add_u32 s11, s21, s11
	s_addc_u32 s10, 0, s10
	s_mul_hi_u32 s22, s9, s20
	s_mul_i32 s20, s9, s20
	s_add_u32 s11, s11, s20
	s_mul_hi_u32 s21, s9, s1
	s_addc_u32 s10, s10, s22
	s_addc_u32 s11, s21, 0
	s_mul_i32 s1, s9, s1
	s_add_u32 s1, s10, s1
	s_addc_u32 s10, 0, s11
	s_add_u32 s11, s0, s1
	s_cselect_b64 s[0:1], -1, 0
	s_cmp_lg_u64 s[0:1], 0
	s_addc_u32 s9, s9, s10
	s_mul_i32 s0, s5, s9
	s_mul_hi_u32 s1, s5, s11
	s_add_i32 s0, s1, s0
	s_mul_i32 s8, s8, s11
	s_add_i32 s0, s0, s8
	s_mul_i32 s5, s5, s11
	s_mul_hi_u32 s8, s9, s5
	s_mul_i32 s10, s9, s5
	s_mul_i32 s21, s11, s0
	s_mul_hi_u32 s5, s11, s5
	s_mul_hi_u32 s20, s11, s0
	s_add_u32 s5, s5, s21
	s_addc_u32 s20, 0, s20
	s_add_u32 s5, s5, s10
	s_mul_hi_u32 s1, s9, s0
	s_addc_u32 s5, s20, s8
	s_addc_u32 s1, s1, 0
	s_mul_i32 s0, s9, s0
	s_add_u32 s0, s5, s0
	s_addc_u32 s5, 0, s1
	s_add_u32 s8, s11, s0
	v_ashrrev_i32_e32 v4, 31, v1
	s_cselect_b64 s[0:1], -1, 0
	v_mov_b32_e32 v5, v4
	s_cmp_lg_u64 s[0:1], 0
	v_lshl_add_u64 v[0:1], v[0:1], 0, v[4:5]
	s_addc_u32 s5, s9, s5
	v_xor_b32_e32 v10, v0, v4
	v_xor_b32_e32 v5, v1, v4
	v_mad_u64_u32 v[0:1], s[0:1], v10, s5, 0
	v_mul_hi_u32 v148, v10, s8
	v_lshl_add_u64 v[0:1], v[148:149], 0, v[0:1]
	v_mad_u64_u32 v[8:9], s[0:1], v5, s8, 0
	v_add_co_u32_e32 v0, vcc, v0, v8
	v_mad_u64_u32 v[6:7], s[0:1], v5, s5, 0
	s_nop 0
	v_addc_co_u32_e32 v148, vcc, v1, v9, vcc
	v_xor_b32_e32 v4, s4, v4
	s_nop 0
	v_addc_co_u32_e32 v7, vcc, 0, v7, vcc
	v_lshl_add_u64 v[0:1], v[148:149], 0, v[6:7]
	v_mul_lo_u32 v8, s7, v0
	v_mul_lo_u32 v9, s6, v1
	v_mad_u64_u32 v[6:7], s[0:1], s6, v0, 0
	v_add3_u32 v11, v7, v9, v8
	v_sub_u32_e32 v7, v5, v11
	v_mov_b32_e32 v8, s7
	v_sub_co_u32_e32 v10, vcc, v10, v6
	v_readlane_b32 s20, v254, 36
	s_nop 0
	v_subb_co_u32_e64 v6, s[0:1], v7, v8, vcc
	v_subrev_co_u32_e64 v7, s[0:1], s6, v10
	v_subb_co_u32_e32 v5, vcc, v5, v11, vcc
	s_nop 0
	v_subbrev_co_u32_e64 v6, s[0:1], 0, v6, s[0:1]
	v_cmp_le_u32_e64 s[0:1], s7, v6
	v_cmp_le_u32_e32 vcc, s7, v5
	s_nop 0
	v_cndmask_b32_e64 v8, 0, -1, s[0:1]
	v_cmp_le_u32_e64 s[0:1], s6, v7
	s_nop 1
	v_cndmask_b32_e64 v7, 0, -1, s[0:1]
	v_cmp_eq_u32_e64 s[0:1], s7, v6
	s_nop 1
	v_cndmask_b32_e64 v12, v8, v7, s[0:1]
	v_lshl_add_u64 v[6:7], v[0:1], 0, 2
	v_lshl_add_u64 v[8:9], v[0:1], 0, 1
	v_cmp_ne_u32_e64 s[0:1], 0, v12
	s_nop 1
	v_cndmask_b32_e64 v7, v9, v7, s[0:1]
	v_cndmask_b32_e64 v9, 0, -1, vcc
	v_cmp_le_u32_e32 vcc, s6, v10
	s_nop 1
	v_cndmask_b32_e64 v10, 0, -1, vcc
	v_cmp_eq_u32_e32 vcc, s7, v5
	s_nop 1
	v_cndmask_b32_e32 v5, v9, v10, vcc
	v_cmp_ne_u32_e32 vcc, 0, v5
	v_cndmask_b32_e64 v5, v8, v6, s[0:1]
	s_nop 0
	v_cndmask_b32_e32 v0, v0, v5, vcc
	v_cndmask_b32_e32 v1, v1, v7, vcc
	v_xor_b32_e32 v0, v0, v4
	v_xor_b32_e32 v1, v1, v4
	v_sub_co_u32_e32 v64, vcc, v0, v4
	s_nop 1
	v_subb_co_u32_e32 v65, vcc, v1, v4, vcc

; DI void row1_phase(const Params& P, int combine_l, int norm_l, int r_begin) {
;     ...
;   const int nrows = TA - r_begin;
;   const int r_lo = r_begin + (int)(((long long)gw * nrows) / nw), r_hi = r_begin + (int)(((long long)(gw + 1) * nrows) / nw);
; #pragma unroll 1
;   for (int r = r_lo; r < r_hi; r += 4) {
.LBB0_155:
	s_or_b64 exec, exec, s[0:1]
	v_add_u32_e32 v0, 1, v3
	s_mov_b32 s0, 0
	v_mad_i64_i32 v[0:1], s[0:1], v0, s0, 0
	v_or_b32_e32 v5, s20, v1
	v_mov_b32_e32 v4, v149
	v_cmp_ne_u64_e32 vcc, 0, v[4:5]
	s_and_saveexec_b64 s[0:1], vcc
	s_xor_b64 s[2:3], exec, s[0:1]
	s_cbranch_execz .LBB0_157
	s_ashr_i32 s4, s20, 31
	v_readlane_b32 s0, v254, 34
	s_add_u32 s0, s0, s4
	s_mov_b32 s5, s4
	s_addc_u32 s1, s20, s4
	s_xor_b64 s[6:7], s[0:1], s[4:5]
	v_cvt_f32_u32_e32 v3, s6
	v_cvt_f32_u32_e32 v4, s7
	s_sub_u32 s5, 0, s6
	s_subb_u32 s8, 0, s7
	v_fmac_f32_e32 v3, 0x4f800000, v4
	v_rcp_f32_e32 v3, v3
	s_nop 0
	v_mul_f32_e32 v3, 0x5f7ffffc, v3
	v_mul_f32_e32 v4, 0x2f800000, v3
	v_trunc_f32_e32 v4, v4
	v_fmac_f32_e32 v3, 0xcf800000, v4
	v_cvt_u32_f32_e32 v4, v4
	v_cvt_u32_f32_e32 v3, v3
	v_readfirstlane_b32 s9, v4
	v_readfirstlane_b32 s0, v3
	s_mul_i32 s1, s5, s9
	s_mul_hi_u32 s11, s5, s0
	s_mul_i32 s10, s8, s0
	s_add_i32 s1, s11, s1
	s_add_i32 s1, s1, s10
	s_mul_i32 s20, s5, s0
	s_mul_i32 s11, s0, s1
	s_mul_hi_u32 s21, s0, s20
	s_mul_hi_u32 s10, s0, s1
	s_add_u32 s11, s21, s11
	s_addc_u32 s10, 0, s10
	s_mul_hi_u32 s22, s9, s20
	s_mul_i32 s20, s9, s20
	s_add_u32 s11, s11, s20
	s_mul_hi_u32 s21, s9, s1
	s_addc_u32 s10, s10, s22
	s_addc_u32 s11, s21, 0
	s_mul_i32 s1, s9, s1
	s_add_u32 s1, s10, s1
	s_addc_u32 s10, 0, s11
	s_add_u32 s11, s0, s1
	s_cselect_b64 s[0:1], -1, 0
	s_cmp_lg_u64 s[0:1], 0
	s_addc_u32 s9, s9, s10
	s_mul_i32 s0, s5, s9
	s_mul_hi_u32 s1, s5, s11
	s_add_i32 s0, s1, s0
	s_mul_i32 s8, s8, s11
	s_add_i32 s0, s0, s8
	s_mul_i32 s5, s5, s11
	s_mul_hi_u32 s8, s9, s5
	s_mul_i32 s10, s9, s5
	s_mul_i32 s21, s11, s0
	s_mul_hi_u32 s5, s11, s5
	s_mul_hi_u32 s20, s11, s0
	s_add_u32 s5, s5, s21
	s_addc_u32 s20, 0, s20
	s_add_u32 s5, s5, s10
	s_mul_hi_u32 s1, s9, s0
	s_addc_u32 s5, s20, s8
	s_addc_u32 s1, s1, 0
	s_mul_i32 s0, s9, s0
	s_add_u32 s0, s5, s0
	s_addc_u32 s5, 0, s1
	s_add_u32 s8, s11, s0
	v_ashrrev_i32_e32 v4, 31, v1
	s_cselect_b64 s[0:1], -1, 0
	v_mov_b32_e32 v5, v4
	s_cmp_lg_u64 s[0:1], 0
	v_lshl_add_u64 v[0:1], v[0:1], 0, v[4:5]
	s_addc_u32 s5, s9, s5
	v_xor_b32_e32 v5, v0, v4
	v_xor_b32_e32 v3, v1, v4
	v_mad_u64_u32 v[0:1], s[0:1], v5, s5, 0
	v_mul_hi_u32 v148, v5, s8
	v_lshl_add_u64 v[0:1], v[148:149], 0, v[0:1]
	v_mad_u64_u32 v[8:9], s[0:1], v3, s8, 0
	v_add_co_u32_e32 v0, vcc, v0, v8
	v_mad_u64_u32 v[6:7], s[0:1], v3, s5, 0
	s_nop 0
	v_addc_co_u32_e32 v148, vcc, v1, v9, vcc
	s_nop 1
	v_addc_co_u32_e32 v7, vcc, 0, v7, vcc
	v_lshl_add_u64 v[0:1], v[148:149], 0, v[6:7]
	v_mul_lo_u32 v8, s7, v0
	v_mul_lo_u32 v9, s6, v1
	v_mad_u64_u32 v[6:7], s[0:1], s6, v0, 0
	v_add3_u32 v10, v7, v9, v8
	v_sub_u32_e32 v7, v3, v10
	v_mov_b32_e32 v8, s7
	v_sub_co_u32_e32 v5, vcc, v5, v6
	s_nop 1
	v_subb_co_u32_e64 v6, s[0:1], v7, v8, vcc
	v_subrev_co_u32_e64 v7, s[0:1], s6, v5
	s_nop 1
	v_subbrev_co_u32_e64 v6, s[0:1], 0, v6, s[0:1]
	v_cmp_le_u32_e64 s[0:1], s7, v6
	s_nop 1
	v_cndmask_b32_e64 v8, 0, -1, s[0:1]
	v_cmp_le_u32_e64 s[0:1], s6, v7
	s_nop 1
	v_cndmask_b32_e64 v7, 0, -1, s[0:1]
	v_cmp_eq_u32_e64 s[0:1], s7, v6
	s_nop 1
	v_cndmask_b32_e64 v11, v8, v7, s[0:1]
	v_lshl_add_u64 v[6:7], v[0:1], 0, 2
	v_lshl_add_u64 v[8:9], v[0:1], 0, 1
	v_subb_co_u32_e32 v1, vcc, v3, v10, vcc
	v_cmp_le_u32_e32 vcc, s7, v1
	s_nop 1
	v_cndmask_b32_e64 v3, 0, -1, vcc
	v_cmp_le_u32_e32 vcc, s6, v5
	s_nop 1
	v_cndmask_b32_e64 v5, 0, -1, vcc
	v_cmp_eq_u32_e32 vcc, s7, v1
	s_nop 1
	v_cndmask_b32_e32 v1, v3, v5, vcc
	v_cmp_ne_u32_e32 vcc, 0, v11
	s_nop 1
	v_cndmask_b32_e32 v3, v8, v6, vcc
	v_cmp_ne_u32_e32 vcc, 0, v1
	v_xor_b32_e32 v1, s4, v4
	s_nop 0
	v_cndmask_b32_e32 v0, v0, v3, vcc
	v_xor_b32_e32 v0, v0, v1
	v_sub_co_u32_e32 v66, vcc, v0, v1

; DI void row1_phase(const Params& P, int combine_l, int norm_l, int r_begin) {
;     ...
;       const float* xm = r < TC ? P.xcbuf + (size_t)r * D : P.out + (size_t)(r - TC) * D;
;       const half_t* y0 = P.yA + (size_t)(2 * r) * D; const half_t* y1 = y0 + D;
; #pragma unroll
;       for (int i = 0; i < 4; i++) { int c = i * 256 + lane * 4; xv[i] = *(const float4*)(xm + c); ya[i] = *(const h4*)(y0 + c); yb[i] = *(const h4*)(y1 + c); }
;     ...
;   const int nrows = TA - r_begin;
;   const int r_lo = r_begin + (int)(((long long)gw * nrows) / nw), r_hi = r_begin + (int)(((long long)(gw + 1) * nrows) / nw);
; #pragma unroll 1
;   for (int r = r_lo; r < r_hi; r += 4) {
;     float4 x0[4], x1[4], x2[4], x3[4]; h4 a0[4], b0[4], a1[4], b1[4], a2[4], b2[4], a3[4], b3[4];
;     const int r1 = r + 1, r2 = r + 2, r3 = r + 3;
;     load_row(r, x0, a0, b0);
;     if (r1 < r_hi) load_row(r1, x1, a1, b1);
;     if (r2 < r_hi) load_row(r2, x2, a2, b2);
;     if (r3 < r_hi) load_row(r3, x3, a3, b3);
;     process(r, x0, a0, b0);
;     if (r1 < r_hi) process(r1, x1, a1, b1);
;     if (r2 < r_hi) process(r2, x2, a2, b2);
;     if (r3 < r_hi) process(r3, x3, a3, b3);
;   }
.LBB0_671:
	v_lshrrev_b32_e32 v152, 6, v172
	v_and_b32_e32 v153, 63, v172
	v_readfirstlane_b32 s5, v152
	v_readlane_b32 s4, v253, 0
	v_lshlrev_b32_e32 v150, 4, v153
	v_lshlrev_b32_e32 v151, 3, v153
	v_lshlrev_b32_e32 v159, 2, v153
	s_nop 2
	s_lshl_b32 s4, s4, 2
	s_add_u32 s4, s4, s5
	s_lshl_b32 s5, s4, 6
	s_add_u32 s5, s5, 0x800
	s_add_u32 s6, s5, 64
	s_add_u32 s52, s90, 0x28cbc700
	s_addc_u32 s53, s91, 0
	s_add_u32 s54, s90, 0xf8bc700
	s_addc_u32 s55, s91, 0
	s_add_u32 s56, s90, 0xce00000
	s_addc_u32 s57, s91, 0
	s_add_u32 s48, s90, 0xf05c700
	s_addc_u32 s49, s91, 0
	v_readlane_b32 s50, v253, 49
	v_readlane_b32 s51, v253, 50
	v_readlane_b32 s58, v255, 15
	v_readlane_b32 s59, v255, 16
	s_nop 3
	s_sub_u32 s50, s50, 0x800000
	s_subb_u32 s51, s51, 0
	s_mov_b32 s8, -1
	s_mov_b32 s7, s5
	s_cmp_lt_u32 s7, 0x800
	s_cselect_b64 s[60:61], s[48:49], s[50:51]
	s_lshl_b32 s10, s7, 12
	s_add_u32 s60, s60, s10
	s_addc_u32 s61, s61, 0
	global_load_dwordx4 a[0:3], v150, s[60:61] offset:0
	global_load_dwordx4 a[4:7], v150, s[60:61] offset:1024
	global_load_dwordx4 a[8:11], v150, s[60:61] offset:2048
	global_load_dwordx4 a[12:15], v150, s[60:61] offset:3072
	s_add_u32 s62, s52, s10
	s_addc_u32 s63, s53, 0
	global_load_dwordx2 a[16:17], v151, s[62:63] offset:0
	global_load_dwordx2 a[18:19], v151, s[62:63] offset:512
	global_load_dwordx2 a[20:21], v151, s[62:63] offset:1024
	global_load_dwordx2 a[22:23], v151, s[62:63] offset:1536
	global_load_dwordx2 a[24:25], v151, s[62:63] offset:2048
	global_load_dwordx2 a[26:27], v151, s[62:63] offset:2560
	global_load_dwordx2 a[28:29], v151, s[62:63] offset:3072
	global_load_dwordx2 a[30:31], v151, s[62:63] offset:3584
	s_add_u32 s7, s7, 1
	s_cmp_lt_u32 s7, 0x800
	s_cselect_b64 s[60:61], s[48:49], s[50:51]
	s_lshl_b32 s10, s7, 12
	s_add_u32 s60, s60, s10
	s_addc_u32 s61, s61, 0
	global_load_dwordx4 a[32:35], v150, s[60:61] offset:0
	global_load_dwordx4 a[36:39], v150, s[60:61] offset:1024
	global_load_dwordx4 a[40:43], v150, s[60:61] offset:2048
	global_load_dwordx4 a[44:47], v150, s[60:61] offset:3072
	s_add_u32 s62, s52, s10
	s_addc_u32 s63, s53, 0
	global_load_dwordx2 a[48:49], v151, s[62:63] offset:0
	global_load_dwordx2 a[50:51], v151, s[62:63] offset:512
	global_load_dwordx2 a[52:53], v151, s[62:63] offset:1024
	global_load_dwordx2 a[54:55], v151, s[62:63] offset:1536
	global_load_dwordx2 a[56:57], v151, s[62:63] offset:2048
	global_load_dwordx2 a[58:59], v151, s[62:63] offset:2560
	global_load_dwordx2 a[60:61], v151, s[62:63] offset:3072
	global_load_dwordx2 a[62:63], v151, s[62:63] offset:3584
	s_add_u32 s7, s7, 1
	s_cmp_lt_u32 s7, 0x800
	s_cselect_b64 s[60:61], s[48:49], s[50:51]
	s_lshl_b32 s10, s7, 12
	s_add_u32 s60, s60, s10
	s_addc_u32 s61, s61, 0
	global_load_dwordx4 a[64:67], v150, s[60:61] offset:0
	global_load_dwordx4 a[68:71], v150, s[60:61] offset:1024
	global_load_dwordx4 a[72:75], v150, s[60:61] offset:2048
	global_load_dwordx4 a[76:79], v150, s[60:61] offset:3072
	s_add_u32 s62, s52, s10
	s_addc_u32 s63, s53, 0
	global_load_dwordx2 a[80:81], v151, s[62:63] offset:0
	global_load_dwordx2 a[82:83], v151, s[62:63] offset:512
	global_load_dwordx2 a[84:85], v151, s[62:63] offset:1024
	global_load_dwordx2 a[86:87], v151, s[62:63] offset:1536
	global_load_dwordx2 a[88:89], v151, s[62:63] offset:2048
	global_load_dwordx2 a[90:91], v151, s[62:63] offset:2560
	global_load_dwordx2 a[92:93], v151, s[62:63] offset:3072
	global_load_dwordx2 a[94:95], v151, s[62:63] offset:3584
	s_add_u32 s7, s7, 1
	s_cmp_lt_u32 s7, 0x800
	s_cselect_b64 s[60:61], s[48:49], s[50:51]
	s_lshl_b32 s10, s7, 12
	s_add_u32 s60, s60, s10
	s_addc_u32 s61, s61, 0
	global_load_dwordx4 a[96:99], v150, s[60:61] offset:0
	global_load_dwordx4 a[100:103], v150, s[60:61] offset:1024
	global_load_dwordx4 a[104:107], v150, s[60:61] offset:2048
	global_load_dwordx4 a[108:111], v150, s[60:61] offset:3072
	s_add_u32 s62, s52, s10
	s_addc_u32 s63, s53, 0
	global_load_dwordx2 a[112:113], v151, s[62:63] offset:0
	global_load_dwordx2 a[114:115], v151, s[62:63] offset:512
	global_load_dwordx2 a[116:117], v151, s[62:63] offset:1024
	global_load_dwordx2 a[118:119], v151, s[62:63] offset:1536
	global_load_dwordx2 a[120:121], v151, s[62:63] offset:2048
	global_load_dwordx2 a[122:123], v151, s[62:63] offset:2560
	global_load_dwordx2 a[124:125], v151, s[62:63] offset:3072
	global_load_dwordx2 a[126:127], v151, s[62:63] offset:3584
	s_add_u32 s7, s7, 1
	s_mov_b32 s98, 15
.Lr1c_loop:
	s_sub_u32 s9, s5, 0x800
	s_lshr_b32 s9, s9, 13
	s_cmp_eq_u32 s9, s8
	s_cbranch_scc1 .Lr1c_nr1
	s_mov_b32 s8, s9
	s_waitcnt vmcnt(0)
	s_add_u32 s10, s9, 9
	s_mul_i32 s10, s10, 0x6000
	s_add_u32 s10, s10, 0x5000
	s_add_u32 s38, s56, s10
	s_addc_u32 s39, s57, 0
	global_load_dwordx4 v[32:35], v150, s[38:39] offset:0
	global_load_dwordx4 v[36:39], v150, s[38:39] offset:1024
	global_load_dwordx4 v[40:43], v150, s[38:39] offset:2048
	global_load_dwordx4 v[44:47], v150, s[38:39] offset:3072
	s_waitcnt vmcnt(0)
; DI void row1_phase(const Params& P, int combine_l, int norm_l, int r_begin) {
;     ...
;       const float* xm = r < TC ? P.xcbuf + (size_t)r * D : P.out + (size_t)(r - TC) * D;
;       const half_t* y0 = P.yA + (size_t)(2 * r) * D; const half_t* y1 = y0 + D;
; #pragma unroll
;       for (int i = 0; i < 4; i++) { int c = i * 256 + lane * 4; xv[i] = *(const float4*)(xm + c); ya[i] = *(const h4*)(y0 + c); yb[i] = *(const h4*)(y1 + c); }
;     ...
;       float* xm = r < TC ? P.xcbuf + (size_t)r * D : P.out + (size_t)(r - TC) * D;
;       const float* g2 = P.mod + (size_t)(combine_l * 9 + n) * 6144 + 5 * 1024;
; #pragma unroll
;       for (int i = 0; i < 4; i++) {
;         int c = i * 256 + lane * 4;
;         float4 g = *(const float4*)(g2 + c); float4 t = xv[i];
;         t.x += g.x * ((float)ya[i][0] + (float)yb[i][0]); t.y += g.y * ((float)ya[i][1] + (float)yb[i][1]);
;         t.z += g.z * ((float)ya[i][2] + (float)yb[i][2]); t.w += g.w * ((float)ya[i][3] + (float)yb[i][3]);
;         *(float4*)(xm + c) = t; xv[i] = t;
;       }
.Lr1c_nr1:
	s_waitcnt vmcnt(40)
	v_accvgpr_read_b32 v54, a0
	v_accvgpr_read_b32 v55, a1
	v_accvgpr_read_b32 v56, a2
	v_accvgpr_read_b32 v57, a3
	v_accvgpr_read_b32 v58, a4
	v_accvgpr_read_b32 v59, a5
	v_accvgpr_read_b32 v60, a6
	v_accvgpr_read_b32 v61, a7
	v_accvgpr_read_b32 v62, a8
	v_accvgpr_read_b32 v63, a9
	v_accvgpr_read_b32 v64, a10
	v_accvgpr_read_b32 v65, a11
	v_accvgpr_read_b32 v66, a12
	v_accvgpr_read_b32 v67, a13
	v_accvgpr_read_b32 v68, a14
	v_accvgpr_read_b32 v69, a15
	v_accvgpr_read_b32 v70, a16
	v_accvgpr_read_b32 v71, a17
	v_accvgpr_read_b32 v72, a18
	v_accvgpr_read_b32 v73, a19
	v_accvgpr_read_b32 v74, a20
	v_accvgpr_read_b32 v75, a21
	v_accvgpr_read_b32 v76, a22
	v_accvgpr_read_b32 v77, a23
	v_accvgpr_read_b32 v78, a24
	v_accvgpr_read_b32 v79, a25
	v_accvgpr_read_b32 v80, a26
	v_accvgpr_read_b32 v81, a27
	v_accvgpr_read_b32 v82, a28
	v_accvgpr_read_b32 v83, a29
	v_accvgpr_read_b32 v84, a30
	v_accvgpr_read_b32 v85, a31
	s_lshl_b32 s10, s5, 12
	s_cmp_lt_u32 s5, 0x800
	s_cselect_b64 s[34:35], s[48:49], s[50:51]
	s_add_u32 s34, s34, s10
	s_addc_u32 s35, s35, 0
	s_cmp_lt_u32 s7, 0x800
	s_cselect_b64 s[60:61], s[48:49], s[50:51]
	s_lshl_b32 s10, s7, 12
	s_add_u32 s60, s60, s10
	s_addc_u32 s61, s61, 0
	global_load_dwordx4 a[0:3], v150, s[60:61] offset:0
	global_load_dwordx4 a[4:7], v150, s[60:61] offset:1024
	global_load_dwordx4 a[8:11], v150, s[60:61] offset:2048
	global_load_dwordx4 a[12:15], v150, s[60:61] offset:3072
	s_add_u32 s62, s52, s10
	s_addc_u32 s63, s53, 0
	global_load_dwordx2 a[16:17], v151, s[62:63] offset:0
	global_load_dwordx2 a[18:19], v151, s[62:63] offset:512
	global_load_dwordx2 a[20:21], v151, s[62:63] offset:1024
	global_load_dwordx2 a[22:23], v151, s[62:63] offset:1536
	global_load_dwordx2 a[24:25], v151, s[62:63] offset:2048
	global_load_dwordx2 a[26:27], v151, s[62:63] offset:2560
	global_load_dwordx2 a[28:29], v151, s[62:63] offset:3072
	global_load_dwordx2 a[30:31], v151, s[62:63] offset:3584
	s_add_u32 s7, s7, 1
	v_cvt_f32_f16_e32 v154, v70
	v_cvt_f32_f16_e32 v155, v78
	v_add_f32_e32 v154, v154, v155
	v_fmac_f32_e32 v54, v32, v154
	v_cvt_f32_f16_sdwa v156, v70 dst_sel:DWORD dst_unused:UNUSED_PAD src0_sel:WORD_1
	v_cvt_f32_f16_sdwa v157, v78 dst_sel:DWORD dst_unused:UNUSED_PAD src0_sel:WORD_1
	v_add_f32_e32 v156, v156, v157
	v_fmac_f32_e32 v55, v33, v156
	v_cvt_f32_f16_e32 v154, v71
	v_cvt_f32_f16_e32 v155, v79
	v_add_f32_e32 v154, v154, v155
	v_fmac_f32_e32 v56, v34, v154
	v_cvt_f32_f16_sdwa v156, v71 dst_sel:DWORD dst_unused:UNUSED_PAD src0_sel:WORD_1
	v_cvt_f32_f16_sdwa v157, v79 dst_sel:DWORD dst_unused:UNUSED_PAD src0_sel:WORD_1
	v_add_f32_e32 v156, v156, v157
	v_fmac_f32_e32 v57, v35, v156
	v_cvt_f32_f16_e32 v154, v72
	v_cvt_f32_f16_e32 v155, v80
	v_add_f32_e32 v154, v154, v155
	v_fmac_f32_e32 v58, v36, v154
	v_cvt_f32_f16_sdwa v156, v72 dst_sel:DWORD dst_unused:UNUSED_PAD src0_sel:WORD_1
	v_cvt_f32_f16_sdwa v157, v80 dst_sel:DWORD dst_unused:UNUSED_PAD src0_sel:WORD_1
	v_add_f32_e32 v156, v156, v157
	v_fmac_f32_e32 v59, v37, v156
	v_cvt_f32_f16_e32 v154, v73
	v_cvt_f32_f16_e32 v155, v81
	v_add_f32_e32 v154, v154, v155
	v_fmac_f32_e32 v60, v38, v154
	v_cvt_f32_f16_sdwa v156, v73 dst_sel:DWORD dst_unused:UNUSED_PAD src0_sel:WORD_1
	v_cvt_f32_f16_sdwa v157, v81 dst_sel:DWORD dst_unused:UNUSED_PAD src0_sel:WORD_1
	v_add_f32_e32 v156, v156, v157
	v_fmac_f32_e32 v61, v39, v156
	v_cvt_f32_f16_e32 v154, v74
	v_cvt_f32_f16_e32 v155, v82
	v_add_f32_e32 v154, v154, v155
	v_fmac_f32_e32 v62, v40, v154
	v_cvt_f32_f16_sdwa v156, v74 dst_sel:DWORD dst_unused:UNUSED_PAD src0_sel:WORD_1
	v_cvt_f32_f16_sdwa v157, v82 dst_sel:DWORD dst_unused:UNUSED_PAD src0_sel:WORD_1
	v_add_f32_e32 v156, v156, v157
	v_fmac_f32_e32 v63, v41, v156
	v_cvt_f32_f16_e32 v154, v75
	v_cvt_f32_f16_e32 v155, v83
	v_add_f32_e32 v154, v154, v155
	v_fmac_f32_e32 v64, v42, v154
	v_cvt_f32_f16_sdwa v156, v75 dst_sel:DWORD dst_unused:UNUSED_PAD src0_sel:WORD_1
	v_cvt_f32_f16_sdwa v157, v83 dst_sel:DWORD dst_unused:UNUSED_PAD src0_sel:WORD_1
	v_add_f32_e32 v156, v156, v157
	v_fmac_f32_e32 v65, v43, v156
	v_cvt_f32_f16_e32 v154, v76
	v_cvt_f32_f16_e32 v155, v84
	v_add_f32_e32 v154, v154, v155
	v_fmac_f32_e32 v66, v44, v154
	v_cvt_f32_f16_sdwa v156, v76 dst_sel:DWORD dst_unused:UNUSED_PAD src0_sel:WORD_1
	v_cvt_f32_f16_sdwa v157, v84 dst_sel:DWORD dst_unused:UNUSED_PAD src0_sel:WORD_1
	v_add_f32_e32 v156, v156, v157
	v_fmac_f32_e32 v67, v45, v156
	v_cvt_f32_f16_e32 v154, v77
	v_cvt_f32_f16_e32 v155, v85
	v_add_f32_e32 v154, v154, v155
	v_fmac_f32_e32 v68, v46, v154
	v_cvt_f32_f16_sdwa v156, v77 dst_sel:DWORD dst_unused:UNUSED_PAD src0_sel:WORD_1
	v_cvt_f32_f16_sdwa v157, v85 dst_sel:DWORD dst_unused:UNUSED_PAD src0_sel:WORD_1
	v_add_f32_e32 v156, v156, v157
	v_fmac_f32_e32 v69, v47, v156
	global_store_dwordx4 v150, v[54:57], s[34:35] offset:0
	global_store_dwordx4 v150, v[58:61], s[34:35] offset:1024
	global_store_dwordx4 v150, v[62:65], s[34:35] offset:2048
	global_store_dwordx4 v150, v[66:69], s[34:35] offset:3072
	s_add_u32 s5, s5, 1
	s_sub_u32 s9, s5, 0x800
	s_lshr_b32 s9, s9, 13
	s_cmp_eq_u32 s9, s8
	s_cbranch_scc1 .Lr1c_nr2
	s_mov_b32 s8, s9
	s_waitcnt vmcnt(0)
	s_add_u32 s10, s9, 9
	s_mul_i32 s10, s10, 0x6000
	s_add_u32 s10, s10, 0x5000
	s_add_u32 s38, s56, s10
	s_addc_u32 s39, s57, 0
	global_load_dwordx4 v[32:35], v150, s[38:39] offset:0
	global_load_dwordx4 v[36:39], v150, s[38:39] offset:1024
	global_load_dwordx4 v[40:43], v150, s[38:39] offset:2048
	global_load_dwordx4 v[44:47], v150, s[38:39] offset:3072
	s_waitcnt vmcnt(0)
; DI void row1_phase(const Params& P, int combine_l, int norm_l, int r_begin) {
;     ...
;       const float* xm = r < TC ? P.xcbuf + (size_t)r * D : P.out + (size_t)(r - TC) * D;
;       const half_t* y0 = P.yA + (size_t)(2 * r) * D; const half_t* y1 = y0 + D;
; #pragma unroll
;       for (int i = 0; i < 4; i++) { int c = i * 256 + lane * 4; xv[i] = *(const float4*)(xm + c); ya[i] = *(const h4*)(y0 + c); yb[i] = *(const h4*)(y1 + c); }
;     ...
;       float* xm = r < TC ? P.xcbuf + (size_t)r * D : P.out + (size_t)(r - TC) * D;
;       const float* g2 = P.mod + (size_t)(combine_l * 9 + n) * 6144 + 5 * 1024;
; #pragma unroll
;       for (int i = 0; i < 4; i++) {
;         int c = i * 256 + lane * 4;
;         float4 g = *(const float4*)(g2 + c); float4 t = xv[i];
;         t.x += g.x * ((float)ya[i][0] + (float)yb[i][0]); t.y += g.y * ((float)ya[i][1] + (float)yb[i][1]);
;         t.z += g.z * ((float)ya[i][2] + (float)yb[i][2]); t.w += g.w * ((float)ya[i][3] + (float)yb[i][3]);
;         *(float4*)(xm + c) = t; xv[i] = t;
;       }
.Lr1c_nr2:
	s_waitcnt vmcnt(40)
	v_accvgpr_read_b32 v54, a32
	v_accvgpr_read_b32 v55, a33
	v_accvgpr_read_b32 v56, a34
	v_accvgpr_read_b32 v57, a35
	v_accvgpr_read_b32 v58, a36
	v_accvgpr_read_b32 v59, a37
	v_accvgpr_read_b32 v60, a38
	v_accvgpr_read_b32 v61, a39
	v_accvgpr_read_b32 v62, a40
	v_accvgpr_read_b32 v63, a41
	v_accvgpr_read_b32 v64, a42
	v_accvgpr_read_b32 v65, a43
	v_accvgpr_read_b32 v66, a44
	v_accvgpr_read_b32 v67, a45
	v_accvgpr_read_b32 v68, a46
	v_accvgpr_read_b32 v69, a47
	v_accvgpr_read_b32 v70, a48
	v_accvgpr_read_b32 v71, a49
	v_accvgpr_read_b32 v72, a50
	v_accvgpr_read_b32 v73, a51
	v_accvgpr_read_b32 v74, a52
	v_accvgpr_read_b32 v75, a53
	v_accvgpr_read_b32 v76, a54
	v_accvgpr_read_b32 v77, a55
	v_accvgpr_read_b32 v78, a56
	v_accvgpr_read_b32 v79, a57
	v_accvgpr_read_b32 v80, a58
	v_accvgpr_read_b32 v81, a59
	v_accvgpr_read_b32 v82, a60
	v_accvgpr_read_b32 v83, a61
	v_accvgpr_read_b32 v84, a62
	v_accvgpr_read_b32 v85, a63
	s_lshl_b32 s10, s5, 12
	s_cmp_lt_u32 s5, 0x800
	s_cselect_b64 s[34:35], s[48:49], s[50:51]
	s_add_u32 s34, s34, s10
	s_addc_u32 s35, s35, 0
	s_cmp_lt_u32 s7, 0x800
	s_cselect_b64 s[60:61], s[48:49], s[50:51]
	s_lshl_b32 s10, s7, 12
	s_add_u32 s60, s60, s10
	s_addc_u32 s61, s61, 0
	global_load_dwordx4 a[32:35], v150, s[60:61] offset:0
	global_load_dwordx4 a[36:39], v150, s[60:61] offset:1024
	global_load_dwordx4 a[40:43], v150, s[60:61] offset:2048
	global_load_dwordx4 a[44:47], v150, s[60:61] offset:3072
	s_add_u32 s62, s52, s10
	s_addc_u32 s63, s53, 0
	global_load_dwordx2 a[48:49], v151, s[62:63] offset:0
	global_load_dwordx2 a[50:51], v151, s[62:63] offset:512
	global_load_dwordx2 a[52:53], v151, s[62:63] offset:1024
	global_load_dwordx2 a[54:55], v151, s[62:63] offset:1536
	global_load_dwordx2 a[56:57], v151, s[62:63] offset:2048
	global_load_dwordx2 a[58:59], v151, s[62:63] offset:2560
	global_load_dwordx2 a[60:61], v151, s[62:63] offset:3072
	global_load_dwordx2 a[62:63], v151, s[62:63] offset:3584
	s_add_u32 s7, s7, 1
	v_cvt_f32_f16_e32 v154, v70
	v_cvt_f32_f16_e32 v155, v78
	v_add_f32_e32 v154, v154, v155
	v_fmac_f32_e32 v54, v32, v154
	v_cvt_f32_f16_sdwa v156, v70 dst_sel:DWORD dst_unused:UNUSED_PAD src0_sel:WORD_1
	v_cvt_f32_f16_sdwa v157, v78 dst_sel:DWORD dst_unused:UNUSED_PAD src0_sel:WORD_1
	v_add_f32_e32 v156, v156, v157
	v_fmac_f32_e32 v55, v33, v156
	v_cvt_f32_f16_e32 v154, v71
	v_cvt_f32_f16_e32 v155, v79
	v_add_f32_e32 v154, v154, v155
	v_fmac_f32_e32 v56, v34, v154
	v_cvt_f32_f16_sdwa v156, v71 dst_sel:DWORD dst_unused:UNUSED_PAD src0_sel:WORD_1
	v_cvt_f32_f16_sdwa v157, v79 dst_sel:DWORD dst_unused:UNUSED_PAD src0_sel:WORD_1
	v_add_f32_e32 v156, v156, v157
	v_fmac_f32_e32 v57, v35, v156
	v_cvt_f32_f16_e32 v154, v72
	v_cvt_f32_f16_e32 v155, v80
	v_add_f32_e32 v154, v154, v155
	v_fmac_f32_e32 v58, v36, v154
	v_cvt_f32_f16_sdwa v156, v72 dst_sel:DWORD dst_unused:UNUSED_PAD src0_sel:WORD_1
	v_cvt_f32_f16_sdwa v157, v80 dst_sel:DWORD dst_unused:UNUSED_PAD src0_sel:WORD_1
	v_add_f32_e32 v156, v156, v157
	v_fmac_f32_e32 v59, v37, v156
	v_cvt_f32_f16_e32 v154, v73
	v_cvt_f32_f16_e32 v155, v81
	v_add_f32_e32 v154, v154, v155
	v_fmac_f32_e32 v60, v38, v154
	v_cvt_f32_f16_sdwa v156, v73 dst_sel:DWORD dst_unused:UNUSED_PAD src0_sel:WORD_1
	v_cvt_f32_f16_sdwa v157, v81 dst_sel:DWORD dst_unused:UNUSED_PAD src0_sel:WORD_1
	v_add_f32_e32 v156, v156, v157
	v_fmac_f32_e32 v61, v39, v156
	v_cvt_f32_f16_e32 v154, v74
	v_cvt_f32_f16_e32 v155, v82
	v_add_f32_e32 v154, v154, v155
	v_fmac_f32_e32 v62, v40, v154
	v_cvt_f32_f16_sdwa v156, v74 dst_sel:DWORD dst_unused:UNUSED_PAD src0_sel:WORD_1
	v_cvt_f32_f16_sdwa v157, v82 dst_sel:DWORD dst_unused:UNUSED_PAD src0_sel:WORD_1
	v_add_f32_e32 v156, v156, v157
	v_fmac_f32_e32 v63, v41, v156
	v_cvt_f32_f16_e32 v154, v75
	v_cvt_f32_f16_e32 v155, v83
	v_add_f32_e32 v154, v154, v155
	v_fmac_f32_e32 v64, v42, v154
	v_cvt_f32_f16_sdwa v156, v75 dst_sel:DWORD dst_unused:UNUSED_PAD src0_sel:WORD_1
	v_cvt_f32_f16_sdwa v157, v83 dst_sel:DWORD dst_unused:UNUSED_PAD src0_sel:WORD_1
	v_add_f32_e32 v156, v156, v157
	v_fmac_f32_e32 v65, v43, v156
	v_cvt_f32_f16_e32 v154, v76
	v_cvt_f32_f16_e32 v155, v84
	v_add_f32_e32 v154, v154, v155
	v_fmac_f32_e32 v66, v44, v154
	v_cvt_f32_f16_sdwa v156, v76 dst_sel:DWORD dst_unused:UNUSED_PAD src0_sel:WORD_1
	v_cvt_f32_f16_sdwa v157, v84 dst_sel:DWORD dst_unused:UNUSED_PAD src0_sel:WORD_1
	v_add_f32_e32 v156, v156, v157
	v_fmac_f32_e32 v67, v45, v156
	v_cvt_f32_f16_e32 v154, v77
	v_cvt_f32_f16_e32 v155, v85
	v_add_f32_e32 v154, v154, v155
	v_fmac_f32_e32 v68, v46, v154
	v_cvt_f32_f16_sdwa v156, v77 dst_sel:DWORD dst_unused:UNUSED_PAD src0_sel:WORD_1
	v_cvt_f32_f16_sdwa v157, v85 dst_sel:DWORD dst_unused:UNUSED_PAD src0_sel:WORD_1
	v_add_f32_e32 v156, v156, v157
	v_fmac_f32_e32 v69, v47, v156
	global_store_dwordx4 v150, v[54:57], s[34:35] offset:0
	global_store_dwordx4 v150, v[58:61], s[34:35] offset:1024
	global_store_dwordx4 v150, v[62:65], s[34:35] offset:2048
	global_store_dwordx4 v150, v[66:69], s[34:35] offset:3072
	s_add_u32 s5, s5, 1
	s_sub_u32 s9, s5, 0x800
	s_lshr_b32 s9, s9, 13
	s_cmp_eq_u32 s9, s8
	s_cbranch_scc1 .Lr1c_nr3
	s_mov_b32 s8, s9
	s_waitcnt vmcnt(0)
	s_add_u32 s10, s9, 9
	s_mul_i32 s10, s10, 0x6000
	s_add_u32 s10, s10, 0x5000
	s_add_u32 s38, s56, s10
	s_addc_u32 s39, s57, 0
	global_load_dwordx4 v[32:35], v150, s[38:39] offset:0
	global_load_dwordx4 v[36:39], v150, s[38:39] offset:1024
	global_load_dwordx4 v[40:43], v150, s[38:39] offset:2048
	global_load_dwordx4 v[44:47], v150, s[38:39] offset:3072
	s_waitcnt vmcnt(0)
; DI void row1_phase(const Params& P, int combine_l, int norm_l, int r_begin) {
;     ...
;       const float* xm = r < TC ? P.xcbuf + (size_t)r * D : P.out + (size_t)(r - TC) * D;
;       const half_t* y0 = P.yA + (size_t)(2 * r) * D; const half_t* y1 = y0 + D;
; #pragma unroll
;       for (int i = 0; i < 4; i++) { int c = i * 256 + lane * 4; xv[i] = *(const float4*)(xm + c); ya[i] = *(const h4*)(y0 + c); yb[i] = *(const h4*)(y1 + c); }
;     ...
;       float* xm = r < TC ? P.xcbuf + (size_t)r * D : P.out + (size_t)(r - TC) * D;
;       const float* g2 = P.mod + (size_t)(combine_l * 9 + n) * 6144 + 5 * 1024;
; #pragma unroll
;       for (int i = 0; i < 4; i++) {
;         int c = i * 256 + lane * 4;
;         float4 g = *(const float4*)(g2 + c); float4 t = xv[i];
;         t.x += g.x * ((float)ya[i][0] + (float)yb[i][0]); t.y += g.y * ((float)ya[i][1] + (float)yb[i][1]);
;         t.z += g.z * ((float)ya[i][2] + (float)yb[i][2]); t.w += g.w * ((float)ya[i][3] + (float)yb[i][3]);
;         *(float4*)(xm + c) = t; xv[i] = t;
;       }
.Lr1c_nr3:
	s_waitcnt vmcnt(40)
	v_accvgpr_read_b32 v54, a64
	v_accvgpr_read_b32 v55, a65
	v_accvgpr_read_b32 v56, a66
	v_accvgpr_read_b32 v57, a67
	v_accvgpr_read_b32 v58, a68
	v_accvgpr_read_b32 v59, a69
	v_accvgpr_read_b32 v60, a70
	v_accvgpr_read_b32 v61, a71
	v_accvgpr_read_b32 v62, a72
	v_accvgpr_read_b32 v63, a73
	v_accvgpr_read_b32 v64, a74
	v_accvgpr_read_b32 v65, a75
	v_accvgpr_read_b32 v66, a76
	v_accvgpr_read_b32 v67, a77
	v_accvgpr_read_b32 v68, a78
	v_accvgpr_read_b32 v69, a79
	v_accvgpr_read_b32 v70, a80
	v_accvgpr_read_b32 v71, a81
	v_accvgpr_read_b32 v72, a82
	v_accvgpr_read_b32 v73, a83
	v_accvgpr_read_b32 v74, a84
	v_accvgpr_read_b32 v75, a85
	v_accvgpr_read_b32 v76, a86
	v_accvgpr_read_b32 v77, a87
	v_accvgpr_read_b32 v78, a88
	v_accvgpr_read_b32 v79, a89
	v_accvgpr_read_b32 v80, a90
	v_accvgpr_read_b32 v81, a91
	v_accvgpr_read_b32 v82, a92
	v_accvgpr_read_b32 v83, a93
	v_accvgpr_read_b32 v84, a94
	v_accvgpr_read_b32 v85, a95
	s_lshl_b32 s10, s5, 12
	s_cmp_lt_u32 s5, 0x800
	s_cselect_b64 s[34:35], s[48:49], s[50:51]
	s_add_u32 s34, s34, s10
	s_addc_u32 s35, s35, 0
	s_cmp_lt_u32 s7, 0x800
	s_cselect_b64 s[60:61], s[48:49], s[50:51]
	s_lshl_b32 s10, s7, 12
	s_add_u32 s60, s60, s10
	s_addc_u32 s61, s61, 0
	global_load_dwordx4 a[64:67], v150, s[60:61] offset:0
	global_load_dwordx4 a[68:71], v150, s[60:61] offset:1024
	global_load_dwordx4 a[72:75], v150, s[60:61] offset:2048
	global_load_dwordx4 a[76:79], v150, s[60:61] offset:3072
	s_add_u32 s62, s52, s10
	s_addc_u32 s63, s53, 0
	global_load_dwordx2 a[80:81], v151, s[62:63] offset:0
	global_load_dwordx2 a[82:83], v151, s[62:63] offset:512
	global_load_dwordx2 a[84:85], v151, s[62:63] offset:1024
	global_load_dwordx2 a[86:87], v151, s[62:63] offset:1536
	global_load_dwordx2 a[88:89], v151, s[62:63] offset:2048
	global_load_dwordx2 a[90:91], v151, s[62:63] offset:2560
	global_load_dwordx2 a[92:93], v151, s[62:63] offset:3072
	global_load_dwordx2 a[94:95], v151, s[62:63] offset:3584
	s_add_u32 s7, s7, 1
	v_cvt_f32_f16_e32 v154, v70
	v_cvt_f32_f16_e32 v155, v78
	v_add_f32_e32 v154, v154, v155
	v_fmac_f32_e32 v54, v32, v154
	v_cvt_f32_f16_sdwa v156, v70 dst_sel:DWORD dst_unused:UNUSED_PAD src0_sel:WORD_1
	v_cvt_f32_f16_sdwa v157, v78 dst_sel:DWORD dst_unused:UNUSED_PAD src0_sel:WORD_1
	v_add_f32_e32 v156, v156, v157
	v_fmac_f32_e32 v55, v33, v156
	v_cvt_f32_f16_e32 v154, v71
	v_cvt_f32_f16_e32 v155, v79
	v_add_f32_e32 v154, v154, v155
	v_fmac_f32_e32 v56, v34, v154
	v_cvt_f32_f16_sdwa v156, v71 dst_sel:DWORD dst_unused:UNUSED_PAD src0_sel:WORD_1
	v_cvt_f32_f16_sdwa v157, v79 dst_sel:DWORD dst_unused:UNUSED_PAD src0_sel:WORD_1
	v_add_f32_e32 v156, v156, v157
	v_fmac_f32_e32 v57, v35, v156
	v_cvt_f32_f16_e32 v154, v72
	v_cvt_f32_f16_e32 v155, v80
	v_add_f32_e32 v154, v154, v155
	v_fmac_f32_e32 v58, v36, v154
	v_cvt_f32_f16_sdwa v156, v72 dst_sel:DWORD dst_unused:UNUSED_PAD src0_sel:WORD_1
	v_cvt_f32_f16_sdwa v157, v80 dst_sel:DWORD dst_unused:UNUSED_PAD src0_sel:WORD_1
	v_add_f32_e32 v156, v156, v157
	v_fmac_f32_e32 v59, v37, v156
	v_cvt_f32_f16_e32 v154, v73
	v_cvt_f32_f16_e32 v155, v81
	v_add_f32_e32 v154, v154, v155
	v_fmac_f32_e32 v60, v38, v154
	v_cvt_f32_f16_sdwa v156, v73 dst_sel:DWORD dst_unused:UNUSED_PAD src0_sel:WORD_1
	v_cvt_f32_f16_sdwa v157, v81 dst_sel:DWORD dst_unused:UNUSED_PAD src0_sel:WORD_1
	v_add_f32_e32 v156, v156, v157
	v_fmac_f32_e32 v61, v39, v156
	v_cvt_f32_f16_e32 v154, v74
	v_cvt_f32_f16_e32 v155, v82
	v_add_f32_e32 v154, v154, v155
	v_fmac_f32_e32 v62, v40, v154
	v_cvt_f32_f16_sdwa v156, v74 dst_sel:DWORD dst_unused:UNUSED_PAD src0_sel:WORD_1
	v_cvt_f32_f16_sdwa v157, v82 dst_sel:DWORD dst_unused:UNUSED_PAD src0_sel:WORD_1
	v_add_f32_e32 v156, v156, v157
	v_fmac_f32_e32 v63, v41, v156
	v_cvt_f32_f16_e32 v154, v75
	v_cvt_f32_f16_e32 v155, v83
	v_add_f32_e32 v154, v154, v155
	v_fmac_f32_e32 v64, v42, v154
	v_cvt_f32_f16_sdwa v156, v75 dst_sel:DWORD dst_unused:UNUSED_PAD src0_sel:WORD_1
	v_cvt_f32_f16_sdwa v157, v83 dst_sel:DWORD dst_unused:UNUSED_PAD src0_sel:WORD_1
	v_add_f32_e32 v156, v156, v157
	v_fmac_f32_e32 v65, v43, v156
	v_cvt_f32_f16_e32 v154, v76
	v_cvt_f32_f16_e32 v155, v84
	v_add_f32_e32 v154, v154, v155
	v_fmac_f32_e32 v66, v44, v154
	v_cvt_f32_f16_sdwa v156, v76 dst_sel:DWORD dst_unused:UNUSED_PAD src0_sel:WORD_1
	v_cvt_f32_f16_sdwa v157, v84 dst_sel:DWORD dst_unused:UNUSED_PAD src0_sel:WORD_1
	v_add_f32_e32 v156, v156, v157
	v_fmac_f32_e32 v67, v45, v156
	v_cvt_f32_f16_e32 v154, v77
	v_cvt_f32_f16_e32 v155, v85
	v_add_f32_e32 v154, v154, v155
	v_fmac_f32_e32 v68, v46, v154
	v_cvt_f32_f16_sdwa v156, v77 dst_sel:DWORD dst_unused:UNUSED_PAD src0_sel:WORD_1
	v_cvt_f32_f16_sdwa v157, v85 dst_sel:DWORD dst_unused:UNUSED_PAD src0_sel:WORD_1
	v_add_f32_e32 v156, v156, v157
	v_fmac_f32_e32 v69, v47, v156
	global_store_dwordx4 v150, v[54:57], s[34:35] offset:0
	global_store_dwordx4 v150, v[58:61], s[34:35] offset:1024
	global_store_dwordx4 v150, v[62:65], s[34:35] offset:2048
	global_store_dwordx4 v150, v[66:69], s[34:35] offset:3072
	s_add_u32 s5, s5, 1
	s_sub_u32 s9, s5, 0x800
	s_lshr_b32 s9, s9, 13
	s_cmp_eq_u32 s9, s8
	s_cbranch_scc1 .Lr1c_nr4
	s_mov_b32 s8, s9
	s_waitcnt vmcnt(0)
	s_add_u32 s10, s9, 9
	s_mul_i32 s10, s10, 0x6000
	s_add_u32 s10, s10, 0x5000
	s_add_u32 s38, s56, s10
	s_addc_u32 s39, s57, 0
	global_load_dwordx4 v[32:35], v150, s[38:39] offset:0
	global_load_dwordx4 v[36:39], v150, s[38:39] offset:1024
	global_load_dwordx4 v[40:43], v150, s[38:39] offset:2048
	global_load_dwordx4 v[44:47], v150, s[38:39] offset:3072
	s_waitcnt vmcnt(0)
; DI void row1_phase(const Params& P, int combine_l, int norm_l, int r_begin) {
;     ...
;       const float* xm = r < TC ? P.xcbuf + (size_t)r * D : P.out + (size_t)(r - TC) * D;
;       const half_t* y0 = P.yA + (size_t)(2 * r) * D; const half_t* y1 = y0 + D;
; #pragma unroll
;       for (int i = 0; i < 4; i++) { int c = i * 256 + lane * 4; xv[i] = *(const float4*)(xm + c); ya[i] = *(const h4*)(y0 + c); yb[i] = *(const h4*)(y1 + c); }
;     ...
;       float* xm = r < TC ? P.xcbuf + (size_t)r * D : P.out + (size_t)(r - TC) * D;
;       const float* g2 = P.mod + (size_t)(combine_l * 9 + n) * 6144 + 5 * 1024;
; #pragma unroll
;       for (int i = 0; i < 4; i++) {
;         int c = i * 256 + lane * 4;
;         float4 g = *(const float4*)(g2 + c); float4 t = xv[i];
;         t.x += g.x * ((float)ya[i][0] + (float)yb[i][0]); t.y += g.y * ((float)ya[i][1] + (float)yb[i][1]);
;         t.z += g.z * ((float)ya[i][2] + (float)yb[i][2]); t.w += g.w * ((float)ya[i][3] + (float)yb[i][3]);
;         *(float4*)(xm + c) = t; xv[i] = t;
;       }
;     ...
;   for (int r = r_lo; r < r_hi; r += 4) {
.Lr1c_nr4:
	s_waitcnt vmcnt(40)
	v_accvgpr_read_b32 v54, a96
	v_accvgpr_read_b32 v55, a97
	v_accvgpr_read_b32 v56, a98
	v_accvgpr_read_b32 v57, a99
	v_accvgpr_read_b32 v58, a100
	v_accvgpr_read_b32 v59, a101
	v_accvgpr_read_b32 v60, a102
	v_accvgpr_read_b32 v61, a103
	v_accvgpr_read_b32 v62, a104
	v_accvgpr_read_b32 v63, a105
	v_accvgpr_read_b32 v64, a106
	v_accvgpr_read_b32 v65, a107
	v_accvgpr_read_b32 v66, a108
	v_accvgpr_read_b32 v67, a109
	v_accvgpr_read_b32 v68, a110
	v_accvgpr_read_b32 v69, a111
	v_accvgpr_read_b32 v70, a112
	v_accvgpr_read_b32 v71, a113
	v_accvgpr_read_b32 v72, a114
	v_accvgpr_read_b32 v73, a115
	v_accvgpr_read_b32 v74, a116
	v_accvgpr_read_b32 v75, a117
	v_accvgpr_read_b32 v76, a118
	v_accvgpr_read_b32 v77, a119
	v_accvgpr_read_b32 v78, a120
	v_accvgpr_read_b32 v79, a121
	v_accvgpr_read_b32 v80, a122
	v_accvgpr_read_b32 v81, a123
	v_accvgpr_read_b32 v82, a124
	v_accvgpr_read_b32 v83, a125
	v_accvgpr_read_b32 v84, a126
	v_accvgpr_read_b32 v85, a127
	s_lshl_b32 s10, s5, 12
	s_cmp_lt_u32 s5, 0x800
	s_cselect_b64 s[34:35], s[48:49], s[50:51]
	s_add_u32 s34, s34, s10
	s_addc_u32 s35, s35, 0
	s_cmp_lt_u32 s7, 0x800
	s_cselect_b64 s[60:61], s[48:49], s[50:51]
	s_lshl_b32 s10, s7, 12
	s_add_u32 s60, s60, s10
	s_addc_u32 s61, s61, 0
	global_load_dwordx4 a[96:99], v150, s[60:61] offset:0
	global_load_dwordx4 a[100:103], v150, s[60:61] offset:1024
	global_load_dwordx4 a[104:107], v150, s[60:61] offset:2048
	global_load_dwordx4 a[108:111], v150, s[60:61] offset:3072
	s_add_u32 s62, s52, s10
	s_addc_u32 s63, s53, 0
	global_load_dwordx2 a[112:113], v151, s[62:63] offset:0
	global_load_dwordx2 a[114:115], v151, s[62:63] offset:512
	global_load_dwordx2 a[116:117], v151, s[62:63] offset:1024
	global_load_dwordx2 a[118:119], v151, s[62:63] offset:1536
	global_load_dwordx2 a[120:121], v151, s[62:63] offset:2048
	global_load_dwordx2 a[122:123], v151, s[62:63] offset:2560
	global_load_dwordx2 a[124:125], v151, s[62:63] offset:3072
	global_load_dwordx2 a[126:127], v151, s[62:63] offset:3584
	s_add_u32 s7, s7, 1
	v_cvt_f32_f16_e32 v154, v70
	v_cvt_f32_f16_e32 v155, v78
	v_add_f32_e32 v154, v154, v155
	v_fmac_f32_e32 v54, v32, v154
	v_cvt_f32_f16_sdwa v156, v70 dst_sel:DWORD dst_unused:UNUSED_PAD src0_sel:WORD_1
	v_cvt_f32_f16_sdwa v157, v78 dst_sel:DWORD dst_unused:UNUSED_PAD src0_sel:WORD_1
	v_add_f32_e32 v156, v156, v157
	v_fmac_f32_e32 v55, v33, v156
	v_cvt_f32_f16_e32 v154, v71
	v_cvt_f32_f16_e32 v155, v79
	v_add_f32_e32 v154, v154, v155
	v_fmac_f32_e32 v56, v34, v154
	v_cvt_f32_f16_sdwa v156, v71 dst_sel:DWORD dst_unused:UNUSED_PAD src0_sel:WORD_1
	v_cvt_f32_f16_sdwa v157, v79 dst_sel:DWORD dst_unused:UNUSED_PAD src0_sel:WORD_1
	v_add_f32_e32 v156, v156, v157
	v_fmac_f32_e32 v57, v35, v156
	v_cvt_f32_f16_e32 v154, v72
	v_cvt_f32_f16_e32 v155, v80
	v_add_f32_e32 v154, v154, v155
	v_fmac_f32_e32 v58, v36, v154
	v_cvt_f32_f16_sdwa v156, v72 dst_sel:DWORD dst_unused:UNUSED_PAD src0_sel:WORD_1
	v_cvt_f32_f16_sdwa v157, v80 dst_sel:DWORD dst_unused:UNUSED_PAD src0_sel:WORD_1
	v_add_f32_e32 v156, v156, v157
	v_fmac_f32_e32 v59, v37, v156
	v_cvt_f32_f16_e32 v154, v73
	v_cvt_f32_f16_e32 v155, v81
	v_add_f32_e32 v154, v154, v155
	v_fmac_f32_e32 v60, v38, v154
	v_cvt_f32_f16_sdwa v156, v73 dst_sel:DWORD dst_unused:UNUSED_PAD src0_sel:WORD_1
	v_cvt_f32_f16_sdwa v157, v81 dst_sel:DWORD dst_unused:UNUSED_PAD src0_sel:WORD_1
	v_add_f32_e32 v156, v156, v157
	v_fmac_f32_e32 v61, v39, v156
	v_cvt_f32_f16_e32 v154, v74
	v_cvt_f32_f16_e32 v155, v82
	v_add_f32_e32 v154, v154, v155
	v_fmac_f32_e32 v62, v40, v154
	v_cvt_f32_f16_sdwa v156, v74 dst_sel:DWORD dst_unused:UNUSED_PAD src0_sel:WORD_1
	v_cvt_f32_f16_sdwa v157, v82 dst_sel:DWORD dst_unused:UNUSED_PAD src0_sel:WORD_1
	v_add_f32_e32 v156, v156, v157
	v_fmac_f32_e32 v63, v41, v156
	v_cvt_f32_f16_e32 v154, v75
	v_cvt_f32_f16_e32 v155, v83
	v_add_f32_e32 v154, v154, v155
	v_fmac_f32_e32 v64, v42, v154
	v_cvt_f32_f16_sdwa v156, v75 dst_sel:DWORD dst_unused:UNUSED_PAD src0_sel:WORD_1
	v_cvt_f32_f16_sdwa v157, v83 dst_sel:DWORD dst_unused:UNUSED_PAD src0_sel:WORD_1
	v_add_f32_e32 v156, v156, v157
	v_fmac_f32_e32 v65, v43, v156
	v_cvt_f32_f16_e32 v154, v76
	v_cvt_f32_f16_e32 v155, v84
	v_add_f32_e32 v154, v154, v155
	v_fmac_f32_e32 v66, v44, v154
	v_cvt_f32_f16_sdwa v156, v76 dst_sel:DWORD dst_unused:UNUSED_PAD src0_sel:WORD_1
	v_cvt_f32_f16_sdwa v157, v84 dst_sel:DWORD dst_unused:UNUSED_PAD src0_sel:WORD_1
	v_add_f32_e32 v156, v156, v157
	v_fmac_f32_e32 v67, v45, v156
	v_cvt_f32_f16_e32 v154, v77
	v_cvt_f32_f16_e32 v155, v85
	v_add_f32_e32 v154, v154, v155
	v_fmac_f32_e32 v68, v46, v154
	v_cvt_f32_f16_sdwa v156, v77 dst_sel:DWORD dst_unused:UNUSED_PAD src0_sel:WORD_1
	v_cvt_f32_f16_sdwa v157, v85 dst_sel:DWORD dst_unused:UNUSED_PAD src0_sel:WORD_1
	v_add_f32_e32 v156, v156, v157
	v_fmac_f32_e32 v69, v47, v156
	global_store_dwordx4 v150, v[54:57], s[34:35] offset:0
	global_store_dwordx4 v150, v[58:61], s[34:35] offset:1024
	global_store_dwordx4 v150, v[62:65], s[34:35] offset:2048
	global_store_dwordx4 v150, v[66:69], s[34:35] offset:3072
	s_add_u32 s5, s5, 1
	s_sub_u32 s98, s98, 1
	s_cmp_lg_u32 s98, 0
	s_cbranch_scc1 .Lr1c_loop
	s_sub_u32 s9, s5, 0x800
	s_lshr_b32 s9, s9, 13
	s_cmp_eq_u32 s9, s8
	s_cbranch_scc1 .Lr1c_nr5
	s_mov_b32 s8, s9
	s_waitcnt vmcnt(0)
	s_add_u32 s10, s9, 9
	s_mul_i32 s10, s10, 0x6000
	s_add_u32 s10, s10, 0x5000
	s_add_u32 s38, s56, s10
	s_addc_u32 s39, s57, 0
	global_load_dwordx4 v[32:35], v150, s[38:39] offset:0
	global_load_dwordx4 v[36:39], v150, s[38:39] offset:1024
	global_load_dwordx4 v[40:43], v150, s[38:39] offset:2048
	global_load_dwordx4 v[44:47], v150, s[38:39] offset:3072
	s_waitcnt vmcnt(0)
; DI void row1_phase(const Params& P, int combine_l, int norm_l, int r_begin) {
;     ...
;       const float* xm = r < TC ? P.xcbuf + (size_t)r * D : P.out + (size_t)(r - TC) * D;
;       const half_t* y0 = P.yA + (size_t)(2 * r) * D; const half_t* y1 = y0 + D;
; #pragma unroll
;       for (int i = 0; i < 4; i++) { int c = i * 256 + lane * 4; xv[i] = *(const float4*)(xm + c); ya[i] = *(const h4*)(y0 + c); yb[i] = *(const h4*)(y1 + c); }
;     ...
;       float* xm = r < TC ? P.xcbuf + (size_t)r * D : P.out + (size_t)(r - TC) * D;
;       const float* g2 = P.mod + (size_t)(combine_l * 9 + n) * 6144 + 5 * 1024;
; #pragma unroll
;       for (int i = 0; i < 4; i++) {
;         int c = i * 256 + lane * 4;
;         float4 g = *(const float4*)(g2 + c); float4 t = xv[i];
;         t.x += g.x * ((float)ya[i][0] + (float)yb[i][0]); t.y += g.y * ((float)ya[i][1] + (float)yb[i][1]);
;         t.z += g.z * ((float)ya[i][2] + (float)yb[i][2]); t.w += g.w * ((float)ya[i][3] + (float)yb[i][3]);
;         *(float4*)(xm + c) = t; xv[i] = t;
;       }
.Lr1c_nr5:
	s_waitcnt vmcnt(40)
	v_accvgpr_read_b32 v54, a0
	v_accvgpr_read_b32 v55, a1
	v_accvgpr_read_b32 v56, a2
	v_accvgpr_read_b32 v57, a3
	v_accvgpr_read_b32 v58, a4
	v_accvgpr_read_b32 v59, a5
	v_accvgpr_read_b32 v60, a6
	v_accvgpr_read_b32 v61, a7
	v_accvgpr_read_b32 v62, a8
	v_accvgpr_read_b32 v63, a9
	v_accvgpr_read_b32 v64, a10
	v_accvgpr_read_b32 v65, a11
	v_accvgpr_read_b32 v66, a12
	v_accvgpr_read_b32 v67, a13
	v_accvgpr_read_b32 v68, a14
	v_accvgpr_read_b32 v69, a15
	v_accvgpr_read_b32 v70, a16
	v_accvgpr_read_b32 v71, a17
	v_accvgpr_read_b32 v72, a18
	v_accvgpr_read_b32 v73, a19
	v_accvgpr_read_b32 v74, a20
	v_accvgpr_read_b32 v75, a21
	v_accvgpr_read_b32 v76, a22
	v_accvgpr_read_b32 v77, a23
	v_accvgpr_read_b32 v78, a24
	v_accvgpr_read_b32 v79, a25
	v_accvgpr_read_b32 v80, a26
	v_accvgpr_read_b32 v81, a27
	v_accvgpr_read_b32 v82, a28
	v_accvgpr_read_b32 v83, a29
	v_accvgpr_read_b32 v84, a30
	v_accvgpr_read_b32 v85, a31
	s_lshl_b32 s10, s5, 12
	s_cmp_lt_u32 s5, 0x800
	s_cselect_b64 s[34:35], s[48:49], s[50:51]
	s_add_u32 s34, s34, s10
	s_addc_u32 s35, s35, 0
	v_cvt_f32_f16_e32 v154, v70
	v_cvt_f32_f16_e32 v155, v78
	v_add_f32_e32 v154, v154, v155
	v_fmac_f32_e32 v54, v32, v154
	v_cvt_f32_f16_sdwa v156, v70 dst_sel:DWORD dst_unused:UNUSED_PAD src0_sel:WORD_1
	v_cvt_f32_f16_sdwa v157, v78 dst_sel:DWORD dst_unused:UNUSED_PAD src0_sel:WORD_1
	v_add_f32_e32 v156, v156, v157
	v_fmac_f32_e32 v55, v33, v156
	v_cvt_f32_f16_e32 v154, v71
	v_cvt_f32_f16_e32 v155, v79
	v_add_f32_e32 v154, v154, v155
	v_fmac_f32_e32 v56, v34, v154
	v_cvt_f32_f16_sdwa v156, v71 dst_sel:DWORD dst_unused:UNUSED_PAD src0_sel:WORD_1
	v_cvt_f32_f16_sdwa v157, v79 dst_sel:DWORD dst_unused:UNUSED_PAD src0_sel:WORD_1
	v_add_f32_e32 v156, v156, v157
	v_fmac_f32_e32 v57, v35, v156
	v_cvt_f32_f16_e32 v154, v72
	v_cvt_f32_f16_e32 v155, v80
	v_add_f32_e32 v154, v154, v155
	v_fmac_f32_e32 v58, v36, v154
	v_cvt_f32_f16_sdwa v156, v72 dst_sel:DWORD dst_unused:UNUSED_PAD src0_sel:WORD_1
	v_cvt_f32_f16_sdwa v157, v80 dst_sel:DWORD dst_unused:UNUSED_PAD src0_sel:WORD_1
	v_add_f32_e32 v156, v156, v157
	v_fmac_f32_e32 v59, v37, v156
	v_cvt_f32_f16_e32 v154, v73
	v_cvt_f32_f16_e32 v155, v81
	v_add_f32_e32 v154, v154, v155
	v_fmac_f32_e32 v60, v38, v154
	v_cvt_f32_f16_sdwa v156, v73 dst_sel:DWORD dst_unused:UNUSED_PAD src0_sel:WORD_1
	v_cvt_f32_f16_sdwa v157, v81 dst_sel:DWORD dst_unused:UNUSED_PAD src0_sel:WORD_1
	v_add_f32_e32 v156, v156, v157
	v_fmac_f32_e32 v61, v39, v156
	v_cvt_f32_f16_e32 v154, v74
	v_cvt_f32_f16_e32 v155, v82
	v_add_f32_e32 v154, v154, v155
	v_fmac_f32_e32 v62, v40, v154
	v_cvt_f32_f16_sdwa v156, v74 dst_sel:DWORD dst_unused:UNUSED_PAD src0_sel:WORD_1
	v_cvt_f32_f16_sdwa v157, v82 dst_sel:DWORD dst_unused:UNUSED_PAD src0_sel:WORD_1
	v_add_f32_e32 v156, v156, v157
	v_fmac_f32_e32 v63, v41, v156
	v_cvt_f32_f16_e32 v154, v75
	v_cvt_f32_f16_e32 v155, v83
	v_add_f32_e32 v154, v154, v155
	v_fmac_f32_e32 v64, v42, v154
	v_cvt_f32_f16_sdwa v156, v75 dst_sel:DWORD dst_unused:UNUSED_PAD src0_sel:WORD_1
	v_cvt_f32_f16_sdwa v157, v83 dst_sel:DWORD dst_unused:UNUSED_PAD src0_sel:WORD_1
	v_add_f32_e32 v156, v156, v157
	v_fmac_f32_e32 v65, v43, v156
	v_cvt_f32_f16_e32 v154, v76
	v_cvt_f32_f16_e32 v155, v84
	v_add_f32_e32 v154, v154, v155
	v_fmac_f32_e32 v66, v44, v154
	v_cvt_f32_f16_sdwa v156, v76 dst_sel:DWORD dst_unused:UNUSED_PAD src0_sel:WORD_1
	v_cvt_f32_f16_sdwa v157, v84 dst_sel:DWORD dst_unused:UNUSED_PAD src0_sel:WORD_1
	v_add_f32_e32 v156, v156, v157
	v_fmac_f32_e32 v67, v45, v156
	v_cvt_f32_f16_e32 v154, v77
	v_cvt_f32_f16_e32 v155, v85
	v_add_f32_e32 v154, v154, v155
	v_fmac_f32_e32 v68, v46, v154
	v_cvt_f32_f16_sdwa v156, v77 dst_sel:DWORD dst_unused:UNUSED_PAD src0_sel:WORD_1
	v_cvt_f32_f16_sdwa v157, v85 dst_sel:DWORD dst_unused:UNUSED_PAD src0_sel:WORD_1
	v_add_f32_e32 v156, v156, v157
	v_fmac_f32_e32 v69, v47, v156
	global_store_dwordx4 v150, v[54:57], s[34:35] offset:0
	global_store_dwordx4 v150, v[58:61], s[34:35] offset:1024
	global_store_dwordx4 v150, v[62:65], s[34:35] offset:2048
	global_store_dwordx4 v150, v[66:69], s[34:35] offset:3072
	s_add_u32 s5, s5, 1
	s_sub_u32 s9, s5, 0x800
	s_lshr_b32 s9, s9, 13
	s_cmp_eq_u32 s9, s8
	s_cbranch_scc1 .Lr1c_nr6
	s_mov_b32 s8, s9
	s_waitcnt vmcnt(0)
	s_add_u32 s10, s9, 9
	s_mul_i32 s10, s10, 0x6000
	s_add_u32 s10, s10, 0x5000
	s_add_u32 s38, s56, s10
	s_addc_u32 s39, s57, 0
	global_load_dwordx4 v[32:35], v150, s[38:39] offset:0
	global_load_dwordx4 v[36:39], v150, s[38:39] offset:1024
	global_load_dwordx4 v[40:43], v150, s[38:39] offset:2048
	global_load_dwordx4 v[44:47], v150, s[38:39] offset:3072
	s_waitcnt vmcnt(0)
; DI void row1_phase(const Params& P, int combine_l, int norm_l, int r_begin) {
;     ...
;       const float* xm = r < TC ? P.xcbuf + (size_t)r * D : P.out + (size_t)(r - TC) * D;
;       const half_t* y0 = P.yA + (size_t)(2 * r) * D; const half_t* y1 = y0 + D;
; #pragma unroll
;       for (int i = 0; i < 4; i++) { int c = i * 256 + lane * 4; xv[i] = *(const float4*)(xm + c); ya[i] = *(const h4*)(y0 + c); yb[i] = *(const h4*)(y1 + c); }
;     ...
;       float* xm = r < TC ? P.xcbuf + (size_t)r * D : P.out + (size_t)(r - TC) * D;
;       const float* g2 = P.mod + (size_t)(combine_l * 9 + n) * 6144 + 5 * 1024;
; #pragma unroll
;       for (int i = 0; i < 4; i++) {
;         int c = i * 256 + lane * 4;
;         float4 g = *(const float4*)(g2 + c); float4 t = xv[i];
;         t.x += g.x * ((float)ya[i][0] + (float)yb[i][0]); t.y += g.y * ((float)ya[i][1] + (float)yb[i][1]);
;         t.z += g.z * ((float)ya[i][2] + (float)yb[i][2]); t.w += g.w * ((float)ya[i][3] + (float)yb[i][3]);
;         *(float4*)(xm + c) = t; xv[i] = t;
;       }
.Lr1c_nr6:
	s_waitcnt vmcnt(28)
	v_accvgpr_read_b32 v54, a32
	v_accvgpr_read_b32 v55, a33
	v_accvgpr_read_b32 v56, a34
	v_accvgpr_read_b32 v57, a35
	v_accvgpr_read_b32 v58, a36
	v_accvgpr_read_b32 v59, a37
	v_accvgpr_read_b32 v60, a38
	v_accvgpr_read_b32 v61, a39
	v_accvgpr_read_b32 v62, a40
	v_accvgpr_read_b32 v63, a41
	v_accvgpr_read_b32 v64, a42
	v_accvgpr_read_b32 v65, a43
	v_accvgpr_read_b32 v66, a44
	v_accvgpr_read_b32 v67, a45
	v_accvgpr_read_b32 v68, a46
	v_accvgpr_read_b32 v69, a47
	v_accvgpr_read_b32 v70, a48
	v_accvgpr_read_b32 v71, a49
	v_accvgpr_read_b32 v72, a50
	v_accvgpr_read_b32 v73, a51
	v_accvgpr_read_b32 v74, a52
	v_accvgpr_read_b32 v75, a53
	v_accvgpr_read_b32 v76, a54
	v_accvgpr_read_b32 v77, a55
	v_accvgpr_read_b32 v78, a56
	v_accvgpr_read_b32 v79, a57
	v_accvgpr_read_b32 v80, a58
	v_accvgpr_read_b32 v81, a59
	v_accvgpr_read_b32 v82, a60
	v_accvgpr_read_b32 v83, a61
	v_accvgpr_read_b32 v84, a62
	v_accvgpr_read_b32 v85, a63
	s_lshl_b32 s10, s5, 12
	s_cmp_lt_u32 s5, 0x800
	s_cselect_b64 s[34:35], s[48:49], s[50:51]
	s_add_u32 s34, s34, s10
	s_addc_u32 s35, s35, 0
	v_cvt_f32_f16_e32 v154, v70
	v_cvt_f32_f16_e32 v155, v78
	v_add_f32_e32 v154, v154, v155
	v_fmac_f32_e32 v54, v32, v154
	v_cvt_f32_f16_sdwa v156, v70 dst_sel:DWORD dst_unused:UNUSED_PAD src0_sel:WORD_1
	v_cvt_f32_f16_sdwa v157, v78 dst_sel:DWORD dst_unused:UNUSED_PAD src0_sel:WORD_1
	v_add_f32_e32 v156, v156, v157
	v_fmac_f32_e32 v55, v33, v156
	v_cvt_f32_f16_e32 v154, v71
	v_cvt_f32_f16_e32 v155, v79
	v_add_f32_e32 v154, v154, v155
	v_fmac_f32_e32 v56, v34, v154
	v_cvt_f32_f16_sdwa v156, v71 dst_sel:DWORD dst_unused:UNUSED_PAD src0_sel:WORD_1
	v_cvt_f32_f16_sdwa v157, v79 dst_sel:DWORD dst_unused:UNUSED_PAD src0_sel:WORD_1
	v_add_f32_e32 v156, v156, v157
	v_fmac_f32_e32 v57, v35, v156
	v_cvt_f32_f16_e32 v154, v72
	v_cvt_f32_f16_e32 v155, v80
	v_add_f32_e32 v154, v154, v155
	v_fmac_f32_e32 v58, v36, v154
	v_cvt_f32_f16_sdwa v156, v72 dst_sel:DWORD dst_unused:UNUSED_PAD src0_sel:WORD_1
	v_cvt_f32_f16_sdwa v157, v80 dst_sel:DWORD dst_unused:UNUSED_PAD src0_sel:WORD_1
	v_add_f32_e32 v156, v156, v157
	v_fmac_f32_e32 v59, v37, v156
	v_cvt_f32_f16_e32 v154, v73
	v_cvt_f32_f16_e32 v155, v81
	v_add_f32_e32 v154, v154, v155
	v_fmac_f32_e32 v60, v38, v154
	v_cvt_f32_f16_sdwa v156, v73 dst_sel:DWORD dst_unused:UNUSED_PAD src0_sel:WORD_1
	v_cvt_f32_f16_sdwa v157, v81 dst_sel:DWORD dst_unused:UNUSED_PAD src0_sel:WORD_1
	v_add_f32_e32 v156, v156, v157
	v_fmac_f32_e32 v61, v39, v156
	v_cvt_f32_f16_e32 v154, v74
	v_cvt_f32_f16_e32 v155, v82
	v_add_f32_e32 v154, v154, v155
	v_fmac_f32_e32 v62, v40, v154
	v_cvt_f32_f16_sdwa v156, v74 dst_sel:DWORD dst_unused:UNUSED_PAD src0_sel:WORD_1
	v_cvt_f32_f16_sdwa v157, v82 dst_sel:DWORD dst_unused:UNUSED_PAD src0_sel:WORD_1
	v_add_f32_e32 v156, v156, v157
	v_fmac_f32_e32 v63, v41, v156
	v_cvt_f32_f16_e32 v154, v75
	v_cvt_f32_f16_e32 v155, v83
	v_add_f32_e32 v154, v154, v155
	v_fmac_f32_e32 v64, v42, v154
	v_cvt_f32_f16_sdwa v156, v75 dst_sel:DWORD dst_unused:UNUSED_PAD src0_sel:WORD_1
	v_cvt_f32_f16_sdwa v157, v83 dst_sel:DWORD dst_unused:UNUSED_PAD src0_sel:WORD_1
	v_add_f32_e32 v156, v156, v157
	v_fmac_f32_e32 v65, v43, v156
	v_cvt_f32_f16_e32 v154, v76
	v_cvt_f32_f16_e32 v155, v84
	v_add_f32_e32 v154, v154, v155
	v_fmac_f32_e32 v66, v44, v154
	v_cvt_f32_f16_sdwa v156, v76 dst_sel:DWORD dst_unused:UNUSED_PAD src0_sel:WORD_1
	v_cvt_f32_f16_sdwa v157, v84 dst_sel:DWORD dst_unused:UNUSED_PAD src0_sel:WORD_1
	v_add_f32_e32 v156, v156, v157
	v_fmac_f32_e32 v67, v45, v156
	v_cvt_f32_f16_e32 v154, v77
	v_cvt_f32_f16_e32 v155, v85
	v_add_f32_e32 v154, v154, v155
	v_fmac_f32_e32 v68, v46, v154
	v_cvt_f32_f16_sdwa v156, v77 dst_sel:DWORD dst_unused:UNUSED_PAD src0_sel:WORD_1
	v_cvt_f32_f16_sdwa v157, v85 dst_sel:DWORD dst_unused:UNUSED_PAD src0_sel:WORD_1
	v_add_f32_e32 v156, v156, v157
	v_fmac_f32_e32 v69, v47, v156
	global_store_dwordx4 v150, v[54:57], s[34:35] offset:0
	global_store_dwordx4 v150, v[58:61], s[34:35] offset:1024
	global_store_dwordx4 v150, v[62:65], s[34:35] offset:2048
	global_store_dwordx4 v150, v[66:69], s[34:35] offset:3072
	s_add_u32 s5, s5, 1
	s_sub_u32 s9, s5, 0x800
	s_lshr_b32 s9, s9, 13
	s_cmp_eq_u32 s9, s8
	s_cbranch_scc1 .Lr1c_nr7
	s_mov_b32 s8, s9
	s_waitcnt vmcnt(0)
	s_add_u32 s10, s9, 9
	s_mul_i32 s10, s10, 0x6000
	s_add_u32 s10, s10, 0x5000
	s_add_u32 s38, s56, s10
	s_addc_u32 s39, s57, 0
	global_load_dwordx4 v[32:35], v150, s[38:39] offset:0
	global_load_dwordx4 v[36:39], v150, s[38:39] offset:1024
	global_load_dwordx4 v[40:43], v150, s[38:39] offset:2048
	global_load_dwordx4 v[44:47], v150, s[38:39] offset:3072
	s_waitcnt vmcnt(0)
; DI void row1_phase(const Params& P, int combine_l, int norm_l, int r_begin) {
;     ...
;       const float* xm = r < TC ? P.xcbuf + (size_t)r * D : P.out + (size_t)(r - TC) * D;
;       const half_t* y0 = P.yA + (size_t)(2 * r) * D; const half_t* y1 = y0 + D;
; #pragma unroll
;       for (int i = 0; i < 4; i++) { int c = i * 256 + lane * 4; xv[i] = *(const float4*)(xm + c); ya[i] = *(const h4*)(y0 + c); yb[i] = *(const h4*)(y1 + c); }
;     ...
;       float* xm = r < TC ? P.xcbuf + (size_t)r * D : P.out + (size_t)(r - TC) * D;
;       const float* g2 = P.mod + (size_t)(combine_l * 9 + n) * 6144 + 5 * 1024;
; #pragma unroll
;       for (int i = 0; i < 4; i++) {
;         int c = i * 256 + lane * 4;
;         float4 g = *(const float4*)(g2 + c); float4 t = xv[i];
;         t.x += g.x * ((float)ya[i][0] + (float)yb[i][0]); t.y += g.y * ((float)ya[i][1] + (float)yb[i][1]);
;         t.z += g.z * ((float)ya[i][2] + (float)yb[i][2]); t.w += g.w * ((float)ya[i][3] + (float)yb[i][3]);
;         *(float4*)(xm + c) = t; xv[i] = t;
;       }
.Lr1c_nr7:
	s_waitcnt vmcnt(16)
	v_accvgpr_read_b32 v54, a64
	v_accvgpr_read_b32 v55, a65
	v_accvgpr_read_b32 v56, a66
	v_accvgpr_read_b32 v57, a67
	v_accvgpr_read_b32 v58, a68
	v_accvgpr_read_b32 v59, a69
	v_accvgpr_read_b32 v60, a70
	v_accvgpr_read_b32 v61, a71
	v_accvgpr_read_b32 v62, a72
	v_accvgpr_read_b32 v63, a73
	v_accvgpr_read_b32 v64, a74
	v_accvgpr_read_b32 v65, a75
	v_accvgpr_read_b32 v66, a76
	v_accvgpr_read_b32 v67, a77
	v_accvgpr_read_b32 v68, a78
	v_accvgpr_read_b32 v69, a79
	v_accvgpr_read_b32 v70, a80
	v_accvgpr_read_b32 v71, a81
	v_accvgpr_read_b32 v72, a82
	v_accvgpr_read_b32 v73, a83
	v_accvgpr_read_b32 v74, a84
	v_accvgpr_read_b32 v75, a85
	v_accvgpr_read_b32 v76, a86
	v_accvgpr_read_b32 v77, a87
	v_accvgpr_read_b32 v78, a88
	v_accvgpr_read_b32 v79, a89
	v_accvgpr_read_b32 v80, a90
	v_accvgpr_read_b32 v81, a91
	v_accvgpr_read_b32 v82, a92
	v_accvgpr_read_b32 v83, a93
	v_accvgpr_read_b32 v84, a94
	v_accvgpr_read_b32 v85, a95
	s_lshl_b32 s10, s5, 12
	s_cmp_lt_u32 s5, 0x800
	s_cselect_b64 s[34:35], s[48:49], s[50:51]
	s_add_u32 s34, s34, s10
	s_addc_u32 s35, s35, 0
	v_cvt_f32_f16_e32 v154, v70
	v_cvt_f32_f16_e32 v155, v78
	v_add_f32_e32 v154, v154, v155
	v_fmac_f32_e32 v54, v32, v154
	v_cvt_f32_f16_sdwa v156, v70 dst_sel:DWORD dst_unused:UNUSED_PAD src0_sel:WORD_1
	v_cvt_f32_f16_sdwa v157, v78 dst_sel:DWORD dst_unused:UNUSED_PAD src0_sel:WORD_1
	v_add_f32_e32 v156, v156, v157
	v_fmac_f32_e32 v55, v33, v156
	v_cvt_f32_f16_e32 v154, v71
	v_cvt_f32_f16_e32 v155, v79
	v_add_f32_e32 v154, v154, v155
	v_fmac_f32_e32 v56, v34, v154
	v_cvt_f32_f16_sdwa v156, v71 dst_sel:DWORD dst_unused:UNUSED_PAD src0_sel:WORD_1
	v_cvt_f32_f16_sdwa v157, v79 dst_sel:DWORD dst_unused:UNUSED_PAD src0_sel:WORD_1
	v_add_f32_e32 v156, v156, v157
	v_fmac_f32_e32 v57, v35, v156
	v_cvt_f32_f16_e32 v154, v72
	v_cvt_f32_f16_e32 v155, v80
	v_add_f32_e32 v154, v154, v155
	v_fmac_f32_e32 v58, v36, v154
	v_cvt_f32_f16_sdwa v156, v72 dst_sel:DWORD dst_unused:UNUSED_PAD src0_sel:WORD_1
	v_cvt_f32_f16_sdwa v157, v80 dst_sel:DWORD dst_unused:UNUSED_PAD src0_sel:WORD_1
	v_add_f32_e32 v156, v156, v157
	v_fmac_f32_e32 v59, v37, v156
	v_cvt_f32_f16_e32 v154, v73
	v_cvt_f32_f16_e32 v155, v81
	v_add_f32_e32 v154, v154, v155
	v_fmac_f32_e32 v60, v38, v154
	v_cvt_f32_f16_sdwa v156, v73 dst_sel:DWORD dst_unused:UNUSED_PAD src0_sel:WORD_1
	v_cvt_f32_f16_sdwa v157, v81 dst_sel:DWORD dst_unused:UNUSED_PAD src0_sel:WORD_1
	v_add_f32_e32 v156, v156, v157
	v_fmac_f32_e32 v61, v39, v156
	v_cvt_f32_f16_e32 v154, v74
	v_cvt_f32_f16_e32 v155, v82
	v_add_f32_e32 v154, v154, v155
	v_fmac_f32_e32 v62, v40, v154
	v_cvt_f32_f16_sdwa v156, v74 dst_sel:DWORD dst_unused:UNUSED_PAD src0_sel:WORD_1
	v_cvt_f32_f16_sdwa v157, v82 dst_sel:DWORD dst_unused:UNUSED_PAD src0_sel:WORD_1
	v_add_f32_e32 v156, v156, v157
	v_fmac_f32_e32 v63, v41, v156
	v_cvt_f32_f16_e32 v154, v75
	v_cvt_f32_f16_e32 v155, v83
	v_add_f32_e32 v154, v154, v155
	v_fmac_f32_e32 v64, v42, v154
	v_cvt_f32_f16_sdwa v156, v75 dst_sel:DWORD dst_unused:UNUSED_PAD src0_sel:WORD_1
	v_cvt_f32_f16_sdwa v157, v83 dst_sel:DWORD dst_unused:UNUSED_PAD src0_sel:WORD_1
	v_add_f32_e32 v156, v156, v157
	v_fmac_f32_e32 v65, v43, v156
	v_cvt_f32_f16_e32 v154, v76
	v_cvt_f32_f16_e32 v155, v84
	v_add_f32_e32 v154, v154, v155
	v_fmac_f32_e32 v66, v44, v154
	v_cvt_f32_f16_sdwa v156, v76 dst_sel:DWORD dst_unused:UNUSED_PAD src0_sel:WORD_1
	v_cvt_f32_f16_sdwa v157, v84 dst_sel:DWORD dst_unused:UNUSED_PAD src0_sel:WORD_1
	v_add_f32_e32 v156, v156, v157
	v_fmac_f32_e32 v67, v45, v156
	v_cvt_f32_f16_e32 v154, v77
	v_cvt_f32_f16_e32 v155, v85
	v_add_f32_e32 v154, v154, v155
	v_fmac_f32_e32 v68, v46, v154
	v_cvt_f32_f16_sdwa v156, v77 dst_sel:DWORD dst_unused:UNUSED_PAD src0_sel:WORD_1
	v_cvt_f32_f16_sdwa v157, v85 dst_sel:DWORD dst_unused:UNUSED_PAD src0_sel:WORD_1
	v_add_f32_e32 v156, v156, v157
	v_fmac_f32_e32 v69, v47, v156
	global_store_dwordx4 v150, v[54:57], s[34:35] offset:0
	global_store_dwordx4 v150, v[58:61], s[34:35] offset:1024
	global_store_dwordx4 v150, v[62:65], s[34:35] offset:2048
	global_store_dwordx4 v150, v[66:69], s[34:35] offset:3072
	s_add_u32 s5, s5, 1
	s_sub_u32 s9, s5, 0x800
	s_lshr_b32 s9, s9, 13
	s_cmp_eq_u32 s9, s8
	s_cbranch_scc1 .Lr1c_nr8
	s_mov_b32 s8, s9
	s_waitcnt vmcnt(0)
	s_add_u32 s10, s9, 9
	s_mul_i32 s10, s10, 0x6000
	s_add_u32 s10, s10, 0x5000
	s_add_u32 s38, s56, s10
	s_addc_u32 s39, s57, 0
	global_load_dwordx4 v[32:35], v150, s[38:39] offset:0
	global_load_dwordx4 v[36:39], v150, s[38:39] offset:1024
	global_load_dwordx4 v[40:43], v150, s[38:39] offset:2048
	global_load_dwordx4 v[44:47], v150, s[38:39] offset:3072
	s_waitcnt vmcnt(0)
; DI void row1_phase(const Params& P, int combine_l, int norm_l, int r_begin) {
;     ...
;     const int n = row_mod(r);
;     if (combine_l >= 0) {
;       float* xm = r < TC ? P.xcbuf + (size_t)r * D : P.out + (size_t)(r - TC) * D;
;       const float* g2 = P.mod + (size_t)(combine_l * 9 + n) * 6144 + 5 * 1024;
; #pragma unroll
;       for (int i = 0; i < 4; i++) {
;         int c = i * 256 + lane * 4;
;         float4 g = *(const float4*)(g2 + c); float4 t = xv[i];
;         t.x += g.x * ((float)ya[i][0] + (float)yb[i][0]); t.y += g.y * ((float)ya[i][1] + (float)yb[i][1]);
;         t.z += g.z * ((float)ya[i][2] + (float)yb[i][2]); t.w += g.w * ((float)ya[i][3] + (float)yb[i][3]);
;         *(float4*)(xm + c) = t; xv[i] = t;
;       }
.Lr1c_nr8:
	s_waitcnt vmcnt(4)
	v_accvgpr_read_b32 v54, a96
	v_accvgpr_read_b32 v55, a97
	v_accvgpr_read_b32 v56, a98
	v_accvgpr_read_b32 v57, a99
	v_accvgpr_read_b32 v58, a100
	v_accvgpr_read_b32 v59, a101
	v_accvgpr_read_b32 v60, a102
	v_accvgpr_read_b32 v61, a103
	v_accvgpr_read_b32 v62, a104
	v_accvgpr_read_b32 v63, a105
	v_accvgpr_read_b32 v64, a106
	v_accvgpr_read_b32 v65, a107
	v_accvgpr_read_b32 v66, a108
	v_accvgpr_read_b32 v67, a109
	v_accvgpr_read_b32 v68, a110
	v_accvgpr_read_b32 v69, a111
	v_accvgpr_read_b32 v70, a112
	v_accvgpr_read_b32 v71, a113
	v_accvgpr_read_b32 v72, a114
	v_accvgpr_read_b32 v73, a115
	v_accvgpr_read_b32 v74, a116
	v_accvgpr_read_b32 v75, a117
	v_accvgpr_read_b32 v76, a118
	v_accvgpr_read_b32 v77, a119
	v_accvgpr_read_b32 v78, a120
	v_accvgpr_read_b32 v79, a121
	v_accvgpr_read_b32 v80, a122
	v_accvgpr_read_b32 v81, a123
	v_accvgpr_read_b32 v82, a124
	v_accvgpr_read_b32 v83, a125
	v_accvgpr_read_b32 v84, a126
	v_accvgpr_read_b32 v85, a127
	s_lshl_b32 s10, s5, 12
	s_cmp_lt_u32 s5, 0x800
	s_cselect_b64 s[34:35], s[48:49], s[50:51]
	s_add_u32 s34, s34, s10
	s_addc_u32 s35, s35, 0
	v_cvt_f32_f16_e32 v154, v70
	v_cvt_f32_f16_e32 v155, v78
	v_add_f32_e32 v154, v154, v155
	v_fmac_f32_e32 v54, v32, v154
	v_cvt_f32_f16_sdwa v156, v70 dst_sel:DWORD dst_unused:UNUSED_PAD src0_sel:WORD_1
	v_cvt_f32_f16_sdwa v157, v78 dst_sel:DWORD dst_unused:UNUSED_PAD src0_sel:WORD_1
	v_add_f32_e32 v156, v156, v157
	v_fmac_f32_e32 v55, v33, v156
	v_cvt_f32_f16_e32 v154, v71
	v_cvt_f32_f16_e32 v155, v79
	v_add_f32_e32 v154, v154, v155
	v_fmac_f32_e32 v56, v34, v154
	v_cvt_f32_f16_sdwa v156, v71 dst_sel:DWORD dst_unused:UNUSED_PAD src0_sel:WORD_1
	v_cvt_f32_f16_sdwa v157, v79 dst_sel:DWORD dst_unused:UNUSED_PAD src0_sel:WORD_1
	v_add_f32_e32 v156, v156, v157
	v_fmac_f32_e32 v57, v35, v156
	v_cvt_f32_f16_e32 v154, v72
	v_cvt_f32_f16_e32 v155, v80
	v_add_f32_e32 v154, v154, v155
	v_fmac_f32_e32 v58, v36, v154
	v_cvt_f32_f16_sdwa v156, v72 dst_sel:DWORD dst_unused:UNUSED_PAD src0_sel:WORD_1
	v_cvt_f32_f16_sdwa v157, v80 dst_sel:DWORD dst_unused:UNUSED_PAD src0_sel:WORD_1
	v_add_f32_e32 v156, v156, v157
	v_fmac_f32_e32 v59, v37, v156
	v_cvt_f32_f16_e32 v154, v73
	v_cvt_f32_f16_e32 v155, v81
	v_add_f32_e32 v154, v154, v155
	v_fmac_f32_e32 v60, v38, v154
	v_cvt_f32_f16_sdwa v156, v73 dst_sel:DWORD dst_unused:UNUSED_PAD src0_sel:WORD_1
	v_cvt_f32_f16_sdwa v157, v81 dst_sel:DWORD dst_unused:UNUSED_PAD src0_sel:WORD_1
	v_add_f32_e32 v156, v156, v157
	v_fmac_f32_e32 v61, v39, v156
	v_cvt_f32_f16_e32 v154, v74
	v_cvt_f32_f16_e32 v155, v82
	v_add_f32_e32 v154, v154, v155
	v_fmac_f32_e32 v62, v40, v154
	v_cvt_f32_f16_sdwa v156, v74 dst_sel:DWORD dst_unused:UNUSED_PAD src0_sel:WORD_1
	v_cvt_f32_f16_sdwa v157, v82 dst_sel:DWORD dst_unused:UNUSED_PAD src0_sel:WORD_1
	v_add_f32_e32 v156, v156, v157
	v_fmac_f32_e32 v63, v41, v156
	v_cvt_f32_f16_e32 v154, v75
	v_cvt_f32_f16_e32 v155, v83
	v_add_f32_e32 v154, v154, v155
	v_fmac_f32_e32 v64, v42, v154
	v_cvt_f32_f16_sdwa v156, v75 dst_sel:DWORD dst_unused:UNUSED_PAD src0_sel:WORD_1
	v_cvt_f32_f16_sdwa v157, v83 dst_sel:DWORD dst_unused:UNUSED_PAD src0_sel:WORD_1
	v_add_f32_e32 v156, v156, v157
	v_fmac_f32_e32 v65, v43, v156
	v_cvt_f32_f16_e32 v154, v76
	v_cvt_f32_f16_e32 v155, v84
	v_add_f32_e32 v154, v154, v155
	v_fmac_f32_e32 v66, v44, v154
	v_cvt_f32_f16_sdwa v156, v76 dst_sel:DWORD dst_unused:UNUSED_PAD src0_sel:WORD_1
	v_cvt_f32_f16_sdwa v157, v84 dst_sel:DWORD dst_unused:UNUSED_PAD src0_sel:WORD_1
	v_add_f32_e32 v156, v156, v157
	v_fmac_f32_e32 v67, v45, v156
	v_cvt_f32_f16_e32 v154, v77
	v_cvt_f32_f16_e32 v155, v85
	v_add_f32_e32 v154, v154, v155
	v_fmac_f32_e32 v68, v46, v154
	v_cvt_f32_f16_sdwa v156, v77 dst_sel:DWORD dst_unused:UNUSED_PAD src0_sel:WORD_1
	v_cvt_f32_f16_sdwa v157, v85 dst_sel:DWORD dst_unused:UNUSED_PAD src0_sel:WORD_1
	v_add_f32_e32 v156, v156, v157
	v_fmac_f32_e32 v69, v47, v156
	global_store_dwordx4 v150, v[54:57], s[34:35] offset:0
	global_store_dwordx4 v150, v[58:61], s[34:35] offset:1024
	global_store_dwordx4 v150, v[62:65], s[34:35] offset:2048
	global_store_dwordx4 v150, v[66:69], s[34:35] offset:3072
	s_add_u32 s5, s5, 1
	s_waitcnt vmcnt(0)
